# adds full-line lane-contiguous epilogue stores for the FFN1 (both layers) and R/K/V GEMMs: B-tile row remap so a wave owns adjacent column groups, DPP half exchange + bpermute lane transpose, 8 rows x
# speedup vs baseline: 1.0053x; 1.0053x over previous
; #define PG8_WAIT_V(n) asm volatile("s_waitcnt vmcnt(" #n ")" ::: "memory")
; #define PG8_BAR __builtin_amdgcn_s_barrier()
; template <class Epi, class Sched, bool ALIGN_EPI = false, bool SP2 = false>
; __device__ __forceinline__ void gemm_phase(PG8_LAS unsigned char* lds, const Gemm g, const Sched& S, const Epi& E) {
;     int tid_l_ = threadIdx.x; asm volatile("" : "+v"(tid_l_)); const int tid = tid_l_, wid = __builtin_amdgcn_readfirstlane(tid >> 6), lane = tid & 63, wr = wid >> 2, wc = wid & 3, fr = lane & 15, fq = lane >> 4;
;     const int K = g.K, nt = K / BK;
;     unsigned voffA[2], voffB[2];
; #pragma unroll
;     for (int i = 0; i < 2; ++i) { int R, C; stage_rc(tid * 16 + i * 8192, R, C); const int Rb = Epi::PERM ? ((R & ~31) + perm32(R & 31)) : R;
;         voffA[i] = (unsigned)(R * K + C) * 2u; voffB[i] = (unsigned)(Rb * K + C) * 2u; }
;     const size_t kstep = (size_t)(BK * 2);
;     const size_t hstep = (size_t)HALF * K * 2;
;     const size_t tstep = 2 * hstep;
;     const unsigned ldsw = (unsigned)wid * 1024u;
;     const int aoff = lds_byte(wr * 64 + fr, fq * 8), boff = lds_byte(wc * 32 + fr, fq * 8);
;     ...
;     Unit cur, nxt; int ui = 0;
;     if (!S.next(0, cur)) return;
;     f32x4 acc[2][2][4][2];
; #pragma unroll
;     for (int a = 0; a < 2; ++a)
; #pragma unroll
;         for (int b = 0; b < 2; ++b)
; #pragma unroll
;             for (int m = 0; m < 4; ++m)
; #pragma unroll
;                 for (int n = 0; n < 2; ++n) acc[a][b][m][n] = (f32x4){0.f, 0.f, 0.f, 0.f};
;     bf16x8 At[4][2], B0[2][2], B1[2][2];
;     const char* cA = (const char*)g.A + (size_t)cur.pm * tstep; const char* cB = (const char*)g.Bt + (size_t)cur.pn * tstep;
;     S.a_ready(cur);
;     if constexpr (SP2) {
;         PG8_STAGE(PG8_SB(0, 0), cB, voffB); PG8_STAGE(PG8_SB(0, 1), cB + hstep, voffB); PG8_STAGE(PG8_SA(0, 0), cA, voffA); PG8_STAGE(PG8_SA(0, 1), cA + hstep, voffA);
;         if (wr == 1) PG8_BAR;
;         PG8_WAIT_V(2); PG8_BAR;
;         PG8_STAGE(PG8_SB(1, 0), cB + kstep, voffB); PG8_STAGE(PG8_SA(1, 0), cA + kstep, voffA); PG8_STAGE(PG8_SB(1, 1), cB + hstep + kstep, voffB);
;         PG8_WAIT_V(6); PG8_BAR;
;     } else {
;         PG8_STAGE(PG8_SB(0, 0), cB, voffB); PG8_STAGE(PG8_SA(0, 0), cA, voffA); PG8_STAGE(PG8_SB(0, 1), cB + hstep, voffB); PG8_STAGE(PG8_SA(0, 1), cA + hstep, voffA);
;         if (wr == 1) PG8_BAR;
;         PG8_WAIT_V(4); PG8_BAR;
.LBB0_45:
	s_andn2_b64 vcc, exec, s[30:31]
	s_cbranch_vccnz .LBB0_66
	s_waitcnt vmcnt(0)
	v_mov_b32_e32 v6, v208
	s_cmpk_gt_i32 s23, 0x7ff
	s_nop 0
	v_readfirstlane_b32 s33, v6
	s_cbranch_scc1 .LBB0_66
	v_lshlrev_b32_e32 v3, 4, v6
	v_add_u32_e32 v1, 0x2000, v3
	v_ashrrev_i32_e32 v0, 31, v1
	v_lshrrev_b32_e32 v0, 22, v0
	v_add_u32_e32 v0, v1, v0
	v_ashrrev_i32_e32 v0, 10, v0
	v_mul_i32_i24_e32 v2, 0x400, v0
	v_sub_u32_e32 v1, v1, v2
	v_lshrrev_b32_e32 v2, 4, v1
	v_bitop3_b32 v2, v2, v1, 32 bitop3:0x6c
	v_ashrrev_i32_e32 v1, 31, v2
	v_lshrrev_b32_e32 v1, 26, v1
	v_add_u32_e32 v4, v2, v1
	v_lshlrev_b32_e32 v5, 3, v0
	v_ashrrev_i32_e32 v1, 6, v4
	v_and_b32_e32 v5, -16, v5
	v_add_u32_e32 v5, v1, v5
	v_and_b32_e32 v7, 3, v1
	s_mov_b32 s7, 0xfffe0
	v_lshrrev_b32_e32 v8, 2, v5
	v_lshlrev_b32_e32 v9, 1, v5
	v_and_b32_e32 v4, 0xc0, v4
	v_and_b32_e32 v252, s7, v5
	v_lshl_or_b32 v7, v252, 1, v7
	v_and_b32_e32 v8, 4, v8
	v_and_b32_e32 v9, 24, v9
	v_sub_u32_e32 v2, v2, v4
	v_mov_b32_e32 v12, 1
	v_or3_b32 v7, v7, v8, v9
	v_lshlrev_b32_e32 v8, 5, v0
	v_ashrrev_i16_sdwa v2, v12, sext(v2) dst_sel:DWORD dst_unused:UNUSED_PAD src0_sel:DWORD src1_sel:BYTE_0
	v_and_b32_e32 v8, 32, v8
	v_bfe_i32 v2, v2, 0, 16
	v_add_lshl_u32 v4, v8, v2, 1
	v_lshl_add_u32 v130, v7, 12, v4
	v_lshl_add_u32 v132, v5, 12, v4
	v_bfe_i32 v4, v6, 27, 1
	v_lshrrev_b32_e32 v4, 22, v4
	v_add_u32_e32 v4, v3, v4
	v_and_b32_e32 v4, 0xfffffc00, v4
	v_sub_u32_e32 v3, v3, v4
	v_lshrrev_b32_e32 v4, 4, v3
	v_bitop3_b32 v5, v4, v3, 32 bitop3:0x6c
	v_ashrrev_i32_e32 v4, 31, v6
	v_lshrrev_b32_e32 v4, 26, v4
	v_ashrrev_i32_e32 v3, 31, v5
	v_add_u32_e32 v4, v6, v4
	v_lshrrev_b32_e32 v3, 26, v3
	v_ashrrev_i32_e32 v4, 6, v4
	s_ashr_i32 s28, s33, 6
	v_add_u32_e32 v7, v5, v3
	v_lshlrev_b32_e32 v8, 3, v4
	v_readlane_b32 s26, v255, 5
	s_ashr_i32 s29, s33, 8
	s_lshl_b32 s2, s28, 10
	v_ashrrev_i32_e32 v3, 6, v7
	v_and_b32_e32 v8, -16, v8
	v_readlane_b32 s27, v255, 6
	v_add_u32_e32 v8, v3, v8
	v_and_b32_e32 v9, 3, v3
	s_and_b64 s[26:27], s[26:27], exec
	v_and_b32_e32 v252, s7, v8
	v_lshl_or_b32 v9, v252, 1, v9
	s_cselect_b32 s7, s67, s66
	v_readlane_b32 s10, v255, 4
	s_add_i32 s7, s7, s10
	s_ashr_i32 s10, s7, 31
	s_lshr_b32 s10, s10, 25
	s_add_i32 s10, s7, s10
	s_mov_b32 s6, s17
	s_ashr_i32 s17, s10, 7
	s_lshl_b32 s17, s17, 2
	s_sub_i32 s26, 64, s17
	s_min_i32 s26, s26, 4
	v_and_b32_e32 v7, 0xc0, v7
	s_abs_i32 s27, s26
	v_sub_u32_e32 v5, v5, v7
	v_cvt_f32_u32_e32 v7, s27
	s_sub_i32 s31, 0, s27
	s_and_b32 s10, s10, 0xffffff80
	s_sub_i32 s7, s7, s10
	v_rcp_iflag_f32_e32 v7, v7
	s_abs_i32 s30, s7
	s_xor_b32 s10, s7, s26
	s_ashr_i32 s10, s10, 31
	v_mul_f32_e32 v7, 0x4f7ffffe, v7
	v_cvt_u32_f32_e32 v7, v7
	v_lshrrev_b32_e32 v10, 2, v8
	v_lshlrev_b32_e32 v11, 1, v8
	v_and_b32_e32 v10, 4, v10
	v_readfirstlane_b32 s34, v7
	s_mul_i32 s31, s31, s34
	s_mul_hi_u32 s31, s34, s31
	s_add_i32 s34, s34, s31
	s_mul_hi_u32 s31, s30, s34
	s_mul_i32 s34, s31, s27
	s_sub_i32 s30, s30, s34
	s_add_i32 s34, s31, 1
	s_sub_i32 s35, s30, s27
	s_cmp_ge_u32 s30, s27
	s_cselect_b32 s31, s34, s31
	s_cselect_b32 s30, s35, s30
	s_add_i32 s34, s31, 1
	s_cmp_ge_u32 s30, s27
	s_cselect_b32 s27, s34, s31
	s_xor_b32 s27, s27, s10
	s_sub_i32 s10, s27, s10
	s_mul_i32 s26, s10, s26
	s_sub_i32 s7, s7, s26
	v_readlane_b32 s26, v255, 7
	s_add_i32 s7, s7, s26
	s_add_i32 s52, s7, s17
	v_readlane_b32 s7, v255, 8
	s_add_i32 s54, s10, s7
	v_and_b32_e32 v11, 24, v11
	s_ashr_i32 s53, s52, 31
	s_ashr_i32 s55, s54, 31
	v_or3_b32 v9, v9, v10, v11
	v_lshlrev_b32_e32 v10, 5, v4
	v_ashrrev_i16_sdwa v5, v12, sext(v5) dst_sel:DWORD dst_unused:UNUSED_PAD src0_sel:DWORD src1_sel:BYTE_0
	s_lshl_b64 s[26:27], s[52:53], 20
	s_lshl_b64 s[30:31], s[54:55], 20
	v_and_b32_e32 v10, 32, v10
	v_bfe_i32 v5, v5, 0, 16
	s_add_u32 s58, s84, s30
	v_add_lshl_u32 v10, v10, v5, 1
	s_addc_u32 s59, s85, s31
	s_add_i32 s10, s2, 0
	v_lshl_add_u32 v128, v9, 12, v10
	s_add_i32 m0, s10, 0x10000
	v_lshl_add_u32 v134, v8, 12, v10
	global_load_lds_dwordx4 v128, s[58:59]
	s_add_i32 m0, s10, 0x12000
	s_add_u32 s30, s58, 0x20000
	global_load_lds_dwordx4 v130, s[58:59]
	s_addc_u32 s31, s59, 0
	s_add_i32 m0, s10, 0x14000
	s_nop 0
	global_load_lds_dwordx4 v128, s[30:31]
	s_add_i32 m0, s10, 0x16000
	s_add_u32 s56, s83, s26
	s_addc_u32 s57, s93, s27
	s_add_i32 s17, s10, 0x2000
	global_load_lds_dwordx4 v130, s[30:31]
	s_mov_b32 m0, s10
	s_add_u32 s30, s56, 0x80000
	global_load_lds_dwordx4 v134, s[56:57]
	s_mov_b32 m0, s17
	s_addc_u32 s31, s57, 0
	s_add_i32 s26, s10, 0x4000
	global_load_lds_dwordx4 v132, s[56:57]
	s_mov_b32 m0, s26
	s_add_i32 s27, s10, 0x6000
	global_load_lds_dwordx4 v134, s[30:31]
	s_mov_b32 m0, s27
	s_cmp_eq_u32 s29, 1
	global_load_lds_dwordx4 v132, s[30:31]
	s_cselect_b64 s[30:31], -1, 0
	s_cmp_lg_u32 s29, 1
	s_cbranch_scc1 .LBB0_49
	s_barrier
.LBB0_49:
	v_lshrrev_b32_e32 v16, 1, v6
	v_and_b32_e32 v16, 24, v16
	v_and_b32_e32 v7, 15, v6
	v_lshlrev_b32_e32 v17, 1, v16
	v_lshlrev_b32_e32 v6, 2, v6
	v_bfe_u32 v252, v208, 3, 3
	v_lshl_or_b32 v142, s29, 6, v252
	v_lshl_or_b32 v7, v7, 6, v17
	s_lshl_b32 s7, s29, 13
	v_and_b32_e32 v6, 32, v6
	v_bitop3_b32 v17, v7, s7, v6 bitop3:0xde
	s_lshl_b32 s7, s28, 5
	s_and_b32 s7, s7, 0x60
	v_lshl_add_u64 v[8:9], s[58:59], 0, v[128:129]
	v_mov_b32_e32 v131, v129
	s_lshl_b32 s28, s7, 7
	v_lshl_add_u64 v[10:11], s[58:59], 0, v[130:131]
	v_mov_b32_e32 v135, v129
	v_bitop3_b32 v143, v7, s28, v6 bitop3:0xde
	s_add_i32 m0, s10, 0x18000
	v_lshl_add_u64 v[6:7], v[8:9], 0, s[20:21]
	v_lshl_add_u64 v[12:13], s[56:57], 0, v[134:135]
	v_mov_b32_e32 v133, v129
	s_waitcnt vmcnt(2)
	s_barrier
	global_load_lds_dwordx4 v[6:7], off
	v_lshl_add_u64 v[6:7], v[10:11], 0, s[20:21]
	s_add_i32 m0, s10, 0x1a000
	s_add_i32 s28, s10, 0x8000
	s_add_i32 s29, s10, 0xa000
	v_lshl_add_u64 v[14:15], s[56:57], 0, v[132:133]
	global_load_lds_dwordx4 v[6:7], off
	v_lshl_add_u64 v[6:7], v[12:13], 0, s[20:21]
	s_mov_b32 m0, s28
	s_add_u32 s34, s58, 0x20080
	global_load_lds_dwordx4 v[6:7], off
	v_lshl_add_u64 v[6:7], v[14:15], 0, s[20:21]
	s_mov_b32 m0, s29
	s_addc_u32 s35, s59, 0
	global_load_lds_dwordx4 v[6:7], off
	s_add_i32 m0, s10, 0x1c000
	v_lshl_add_u64 v[6:7], s[34:35], 0, v[128:129]
	global_load_lds_dwordx4 v[6:7], off
	v_lshl_add_u64 v[6:7], s[34:35], 0, v[130:131]
	s_add_i32 m0, s10, 0x1e000
	s_cmpk_lt_u32 s33, 0x100
	global_load_lds_dwordx4 v[6:7], off
	v_lshlrev_b32_e32 v6, 15, v4
	v_and_b32_e32 v6, 0xffff0000, v6
	v_lshl_add_u32 v3, v3, 12, v6
	v_and_b32_e32 v4, 1, v4
	v_lshl_or_b32 v3, v4, 6, v3
	v_lshl_add_u32 v136, v5, 1, v3
	v_lshlrev_b32_e32 v3, 15, v0
	v_and_b32_e32 v3, 0xffff0000, v3
	s_waitcnt vmcnt(6)
	v_lshl_add_u32 v1, v1, 12, v3
	v_and_b32_e32 v0, 1, v0
	v_lshl_or_b32 v0, v0, 6, v1
	s_cselect_b64 s[42:43], -1, 0
	v_and_b32_e32 v252, 7, v208
	v_lshlrev_b32_e32 v252, 3, v252
	v_lshl_or_b32 v144, s7, 1, v252
	v_mov_b32_e32 v137, v129
	v_lshl_add_u32 v138, v2, 1, v0
	v_mov_b32_e32 v139, v129
	s_mov_b32 s33, 0
	v_add_u32_e32 v145, 0, v17
	s_barrier
	s_branch .LBB0_52

; #define PG8_STAGE(bufoff, gbase, voff) do { _Pragma("unroll") for (int _i = 0; _i < 2; ++_i) \
;         __builtin_amdgcn_global_load_lds((const unsigned*)((const char*)(gbase) + (voff)[_i]), (PG8_LAS unsigned*)(lds + (bufoff) + ldsw + _i * 8192), 16, 0, 0); } while (0)
; #define PG8_LDA(dst, b, h) do { _Pragma("unroll") for (int m = 0; m < 4; ++m) _Pragma("unroll") for (int k = 0; k < 2; ++k) dst[m][k] = *(const PG8_LAS bf16x8*)(lds + PG8_SA(b, h) + aoff + m * 2048 + k * 1024); } while (0)
; #define PG8_LDB(dst, b, h) do { _Pragma("unroll") for (int n = 0; n < 2; ++n) _Pragma("unroll") for (int k = 0; k < 2; ++k) dst[n][k] = *(const PG8_LAS bf16x8*)(lds + PG8_SB(b, h) + boff + n * 2048 + k * 1024); } while (0)
; #define PG8_MMA(ai, bj, At, Bt) do { __builtin_amdgcn_s_setprio(1); _Pragma("unroll") for (int m = 0; m < 4; ++m) _Pragma("unroll") for (int n = 0; n < 2; ++n) _Pragma("unroll") for (int k = 0; k < 2; ++k) \
;         acc[ai][bj][m][n] = __builtin_amdgcn_mfma_f32_16x16x32_bf16(Bt[n][k], At[m][k], acc[ai][bj][m][n], 0, 0, 0); __builtin_amdgcn_s_setprio(0); } while (0)
; #define PG8_WAIT_V(n) asm volatile("s_waitcnt vmcnt(" #n ")" ::: "memory")
; #define PG8_WAIT_L(n) asm volatile("s_waitcnt lgkmcnt(" #n ")" ::: "memory")
; #define PG8_BAR __builtin_amdgcn_s_barrier()
; #define PG8_SCHED __builtin_amdgcn_sched_barrier(0)
; template <class Epi, class Sched, bool ALIGN_EPI = false, bool SP2 = false>
; __device__ __forceinline__ void gemm_phase(PG8_LAS unsigned char* lds, const Gemm g, const Sched& S, const Epi& E) {
;     ...
;             PG8_LDB(B0, 0, 0); PG8_LDB(B1, 0, 1); PG8_SCHED; PG8_LDA(At, 0, 0); PG8_STAGE(PG8_SA(1, 1), a1 + hstep, voffA);
;             PG8_WAIT_V(8); PG8_WAIT_L(0); PG8_BAR; PG8_MMA(0, 0, At, B0); PG8_MMA(0, 1, At, B1); PG8_BAR; PG8_SCHED;
;             PG8_LDA(At, 0, 1); PG8_STAGE(PG8_SB(0, 0), b2, voffB); PG8_STAGE(PG8_SB(0, 1), b2 + hstep, voffB); PG8_STAGE(PG8_SA(0, 0), a2, voffA);
;             PG8_WAIT_V(8); PG8_WAIT_L(0); PG8_BAR; PG8_MMA(1, 0, At, B0); PG8_MMA(1, 1, At, B1); PG8_BAR; PG8_SCHED;
.LBB0_59:
	s_add_u32 s7, s56, 0xfff80080
	s_addc_u32 s58, s57, -1
	s_add_i32 s62, 0, 0x10000
	s_cmp_eq_u32 s55, 28
	s_cselect_b32 s61, s34, s58
	s_cselect_b32 s60, s35, s7
	v_add_u32_e32 v140, s62, v143
	s_cselect_b32 s59, s37, s53
	s_cselect_b32 s58, s45, s47
	s_add_i32 s7, 0, 0x14000
	ds_read_b128 v[146:149], v140
	ds_read_b128 v[150:153], v140 offset:1024
	ds_read_b128 v[154:157], v140 offset:2048
	ds_read_b128 v[158:161], v140 offset:3072
	v_add_u32_e32 v140, s7, v143
	ds_read_b128 v[162:165], v140
	ds_read_b128 v[166:169], v140 offset:1024
	ds_read_b128 v[170:173], v140 offset:2048
	ds_read_b128 v[174:177], v140 offset:3072
	v_lshl_add_u64 v[140:141], s[56:57], 0, v[136:137]
	s_add_i32 m0, s10, 0xc000
	ds_read_b128 v[178:181], v145
	ds_read_b128 v[182:185], v145 offset:1024
	ds_read_b128 v[186:189], v145 offset:2048
	ds_read_b128 v[190:193], v145 offset:3072
	ds_read_b128 v[214:217], v145 offset:4096
	ds_read_b128 v[220:223], v145 offset:5120
	ds_read_b128 v[224:227], v145 offset:6144
	ds_read_b128 v[228:231], v145 offset:7168
	global_load_lds_dwordx4 v[140:141], off
	v_lshl_add_u64 v[140:141], s[56:57], 0, v[138:139]
	s_add_i32 m0, s10, 0xe000
	s_nop 0
	global_load_lds_dwordx4 v[140:141], off
	s_waitcnt vmcnt(8)
	s_waitcnt lgkmcnt(0)
	s_barrier
	s_setprio 1
	s_waitcnt lgkmcnt(0)
	v_mfma_f32_16x16x32_bf16 v[124:127], v[146:149], v[178:181], v[124:127]
	v_mfma_f32_16x16x32_bf16 v[120:123], v[154:157], v[178:181], v[120:123]
	v_mfma_f32_16x16x32_bf16 v[108:111], v[146:149], v[186:189], v[108:111]
	v_mfma_f32_16x16x32_bf16 v[104:107], v[154:157], v[186:189], v[104:107]
	v_mfma_f32_16x16x32_bf16 v[92:95], v[146:149], v[214:217], v[92:95]
	v_mfma_f32_16x16x32_bf16 v[88:91], v[154:157], v[214:217], v[88:91]
	v_mfma_f32_16x16x32_bf16 v[76:79], v[146:149], v[224:227], v[76:79]
	v_mfma_f32_16x16x32_bf16 v[72:75], v[154:157], v[224:227], v[72:75]
	v_mfma_f32_16x16x32_bf16 v[124:127], v[150:153], v[182:185], v[124:127]
	v_mfma_f32_16x16x32_bf16 v[120:123], v[158:161], v[182:185], v[120:123]
	v_mfma_f32_16x16x32_bf16 v[108:111], v[150:153], v[190:193], v[108:111]
	v_mfma_f32_16x16x32_bf16 v[104:107], v[158:161], v[190:193], v[104:107]
	v_mfma_f32_16x16x32_bf16 v[92:95], v[150:153], v[220:223], v[92:95]
	v_mfma_f32_16x16x32_bf16 v[88:91], v[158:161], v[220:223], v[88:91]
	v_mfma_f32_16x16x32_bf16 v[76:79], v[150:153], v[228:231], v[76:79]
	v_mfma_f32_16x16x32_bf16 v[72:75], v[158:161], v[228:231], v[72:75]
	s_setprio 0
	s_setprio 1
	v_mfma_f32_16x16x32_bf16 v[116:119], v[162:165], v[178:181], v[116:119]
	v_mfma_f32_16x16x32_bf16 v[112:115], v[170:173], v[178:181], v[112:115]
	v_mfma_f32_16x16x32_bf16 v[100:103], v[162:165], v[186:189], v[100:103]
	v_mfma_f32_16x16x32_bf16 v[96:99], v[170:173], v[186:189], v[96:99]
	v_mfma_f32_16x16x32_bf16 v[84:87], v[162:165], v[214:217], v[84:87]
	v_mfma_f32_16x16x32_bf16 v[80:83], v[170:173], v[214:217], v[80:83]
	v_mfma_f32_16x16x32_bf16 v[68:71], v[162:165], v[224:227], v[68:71]
	v_mfma_f32_16x16x32_bf16 v[64:67], v[170:173], v[224:227], v[64:67]
	v_mfma_f32_16x16x32_bf16 v[116:119], v[166:169], v[182:185], v[116:119]
	v_mfma_f32_16x16x32_bf16 v[112:115], v[174:177], v[182:185], v[112:115]
	v_mfma_f32_16x16x32_bf16 v[100:103], v[166:169], v[190:193], v[100:103]
	v_mfma_f32_16x16x32_bf16 v[96:99], v[174:177], v[190:193], v[96:99]
	v_mfma_f32_16x16x32_bf16 v[84:87], v[166:169], v[220:223], v[84:87]
	v_mfma_f32_16x16x32_bf16 v[80:83], v[174:177], v[220:223], v[80:83]
	v_mfma_f32_16x16x32_bf16 v[68:71], v[166:169], v[228:231], v[68:71]
	v_mfma_f32_16x16x32_bf16 v[64:67], v[174:177], v[228:231], v[64:67]
	s_setprio 0
	s_barrier
	s_add_i32 s62, s62, s2
	v_lshl_add_u64 v[140:141], s[58:59], 0, v[128:129]
	s_mov_b32 m0, s62
	ds_read_b128 v[178:181], v145 offset:16384
	ds_read_b128 v[182:185], v145 offset:17408
	ds_read_b128 v[186:189], v145 offset:18432
	ds_read_b128 v[190:193], v145 offset:19456
	ds_read_b128 v[214:217], v145 offset:20480
	ds_read_b128 v[220:223], v145 offset:21504
	ds_read_b128 v[224:227], v145 offset:22528
	ds_read_b128 v[228:231], v145 offset:23552
	global_load_lds_dwordx4 v[140:141], off
	s_add_i32 m0, s62, 0x2000
	s_add_u32 s62, s58, 0x20000
	v_lshl_add_u64 v[206:207], s[58:59], 0, v[130:131]
	s_addc_u32 s63, s59, 0
	s_add_i32 s7, s7, s2
	global_load_lds_dwordx4 v[206:207], off
	v_lshl_add_u64 v[232:233], s[62:63], 0, v[128:129]
	s_mov_b32 m0, s7
	v_lshl_add_u64 v[234:235], s[60:61], 0, v[132:133]
	global_load_lds_dwordx4 v[232:233], off
	v_lshl_add_u64 v[232:233], s[62:63], 0, v[130:131]
	s_add_i32 m0, s7, 0x2000
	s_nop 0
	global_load_lds_dwordx4 v[232:233], off
	v_lshl_add_u64 v[232:233], s[60:61], 0, v[134:135]
	s_mov_b32 m0, s10
	s_nop 0
	global_load_lds_dwordx4 v[232:233], off
	s_mov_b32 m0, s17
	s_nop 0
	global_load_lds_dwordx4 v[234:235], off
	s_waitcnt vmcnt(8)
	s_waitcnt lgkmcnt(0)
	s_barrier
; #define PG8_STAGE(bufoff, gbase, voff) do { _Pragma("unroll") for (int _i = 0; _i < 2; ++_i) \
;         __builtin_amdgcn_global_load_lds((const unsigned*)((const char*)(gbase) + (voff)[_i]), (PG8_LAS unsigned*)(lds + (bufoff) + ldsw + _i * 8192), 16, 0, 0); } while (0)
; #define PG8_LDA(dst, b, h) do { _Pragma("unroll") for (int m = 0; m < 4; ++m) _Pragma("unroll") for (int k = 0; k < 2; ++k) dst[m][k] = *(const PG8_LAS bf16x8*)(lds + PG8_SA(b, h) + aoff + m * 2048 + k * 1024); } while (0)
; #define PG8_LDB(dst, b, h) do { _Pragma("unroll") for (int n = 0; n < 2; ++n) _Pragma("unroll") for (int k = 0; k < 2; ++k) dst[n][k] = *(const PG8_LAS bf16x8*)(lds + PG8_SB(b, h) + boff + n * 2048 + k * 1024); } while (0)
; #define PG8_MMA(ai, bj, At, Bt) do { __builtin_amdgcn_s_setprio(1); _Pragma("unroll") for (int m = 0; m < 4; ++m) _Pragma("unroll") for (int n = 0; n < 2; ++n) _Pragma("unroll") for (int k = 0; k < 2; ++k) \
;         acc[ai][bj][m][n] = __builtin_amdgcn_mfma_f32_16x16x32_bf16(Bt[n][k], At[m][k], acc[ai][bj][m][n], 0, 0, 0); __builtin_amdgcn_s_setprio(0); } while (0)
; #define PG8_WAIT_V(n) asm volatile("s_waitcnt vmcnt(" #n ")" ::: "memory")
; #define PG8_WAIT_L(n) asm volatile("s_waitcnt lgkmcnt(" #n ")" ::: "memory")
; #define PG8_BAR __builtin_amdgcn_s_barrier()
; #define PG8_SCHED __builtin_amdgcn_sched_barrier(0)
; template <class Epi, class Sched, bool ALIGN_EPI = false, bool SP2 = false>
; __device__ __forceinline__ void gemm_phase(PG8_LAS unsigned char* lds, const Gemm g, const Sched& S, const Epi& E) {
;     ...
;             PG8_WAIT_V(8); PG8_WAIT_L(0); PG8_BAR; PG8_MMA(1, 0, At, B0); PG8_MMA(1, 1, At, B1); PG8_BAR; PG8_SCHED;
;             PG8_LDB(B0, 1, 0); PG8_LDB(B1, 1, 1); PG8_SCHED; PG8_LDA(At, 1, 0); PG8_STAGE(PG8_SA(0, 1), a2 + hstep, voffA);
;             PG8_WAIT_V(8); PG8_WAIT_L(0); PG8_BAR; PG8_MMA(0, 0, At, B0); PG8_MMA(0, 1, At, B1); PG8_BAR; PG8_SCHED;
	s_setprio 1
	s_waitcnt lgkmcnt(0)
	v_mfma_f32_16x16x32_bf16 v[60:63], v[146:149], v[178:181], v[60:63]
	v_mfma_f32_16x16x32_bf16 v[56:59], v[154:157], v[178:181], v[56:59]
	v_mfma_f32_16x16x32_bf16 v[44:47], v[146:149], v[186:189], v[44:47]
	v_mfma_f32_16x16x32_bf16 v[40:43], v[154:157], v[186:189], v[40:43]
	v_mfma_f32_16x16x32_bf16 v[28:31], v[146:149], v[214:217], v[28:31]
	v_mfma_f32_16x16x32_bf16 v[24:27], v[154:157], v[214:217], v[24:27]
	v_mfma_f32_16x16x32_bf16 v[12:15], v[146:149], v[224:227], v[12:15]
	v_mfma_f32_16x16x32_bf16 v[8:11], v[154:157], v[224:227], v[8:11]
	v_mfma_f32_16x16x32_bf16 v[60:63], v[150:153], v[182:185], v[60:63]
	v_mfma_f32_16x16x32_bf16 v[56:59], v[158:161], v[182:185], v[56:59]
	v_mfma_f32_16x16x32_bf16 v[44:47], v[150:153], v[190:193], v[44:47]
	v_mfma_f32_16x16x32_bf16 v[40:43], v[158:161], v[190:193], v[40:43]
	v_mfma_f32_16x16x32_bf16 v[28:31], v[150:153], v[220:223], v[28:31]
	v_mfma_f32_16x16x32_bf16 v[24:27], v[158:161], v[220:223], v[24:27]
	v_mfma_f32_16x16x32_bf16 v[12:15], v[150:153], v[228:231], v[12:15]
	v_mfma_f32_16x16x32_bf16 v[8:11], v[158:161], v[228:231], v[8:11]
	s_setprio 0
	s_setprio 1
	v_mfma_f32_16x16x32_bf16 v[52:55], v[162:165], v[178:181], v[52:55]
	v_mfma_f32_16x16x32_bf16 v[48:51], v[170:173], v[178:181], v[48:51]
	v_mfma_f32_16x16x32_bf16 v[36:39], v[162:165], v[186:189], v[36:39]
	v_mfma_f32_16x16x32_bf16 v[32:35], v[170:173], v[186:189], v[32:35]
	v_mfma_f32_16x16x32_bf16 v[20:23], v[162:165], v[214:217], v[20:23]
	v_mfma_f32_16x16x32_bf16 v[16:19], v[170:173], v[214:217], v[16:19]
	v_mfma_f32_16x16x32_bf16 v[4:7], v[162:165], v[224:227], v[4:7]
	v_mfma_f32_16x16x32_bf16 v[0:3], v[170:173], v[224:227], v[0:3]
	v_mfma_f32_16x16x32_bf16 v[52:55], v[166:169], v[182:185], v[52:55]
	v_mfma_f32_16x16x32_bf16 v[48:51], v[174:177], v[182:185], v[48:51]
	v_mfma_f32_16x16x32_bf16 v[36:39], v[166:169], v[190:193], v[36:39]
	v_mfma_f32_16x16x32_bf16 v[32:35], v[174:177], v[190:193], v[32:35]
	v_mfma_f32_16x16x32_bf16 v[20:23], v[166:169], v[220:223], v[20:23]
	v_mfma_f32_16x16x32_bf16 v[16:19], v[174:177], v[220:223], v[16:19]
	v_mfma_f32_16x16x32_bf16 v[4:7], v[166:169], v[228:231], v[4:7]
	v_mfma_f32_16x16x32_bf16 v[0:3], v[174:177], v[228:231], v[0:3]
	s_setprio 0
	s_barrier
	s_add_i32 s7, 0, 0x18000
	s_add_i32 s62, 0, 0x1c000
	v_add_u32_e32 v158, s7, v143
	v_add_u32_e32 v174, s62, v143
	ds_read_b128 v[146:149], v158
	ds_read_b128 v[150:153], v158 offset:1024
	ds_read_b128 v[154:157], v158 offset:2048
	ds_read_b128 v[158:161], v158 offset:3072
	ds_read_b128 v[162:165], v174
	ds_read_b128 v[166:169], v174 offset:1024
	ds_read_b128 v[170:173], v174 offset:2048
	ds_read_b128 v[174:177], v174 offset:3072
	s_add_u32 s60, s60, 0x80000
	s_addc_u32 s61, s61, 0
	s_mov_b32 m0, s26
	v_lshl_add_u64 v[236:237], s[60:61], 0, v[134:135]
	ds_read_b128 v[178:181], v145 offset:32768
	ds_read_b128 v[182:185], v145 offset:33792
	ds_read_b128 v[186:189], v145 offset:34816
	ds_read_b128 v[190:193], v145 offset:35840
	ds_read_b128 v[214:217], v145 offset:36864
	ds_read_b128 v[220:223], v145 offset:37888
	ds_read_b128 v[224:227], v145 offset:38912
	ds_read_b128 v[228:231], v145 offset:39936
	global_load_lds_dwordx4 v[236:237], off
	v_lshl_add_u64 v[236:237], s[60:61], 0, v[132:133]
	s_mov_b32 m0, s27
	s_nop 0
	global_load_lds_dwordx4 v[236:237], off
	s_waitcnt vmcnt(8)
	s_waitcnt lgkmcnt(0)
	s_barrier
	s_setprio 1
	s_waitcnt lgkmcnt(0)
	v_mfma_f32_16x16x32_bf16 v[124:127], v[146:149], v[178:181], v[124:127]
	v_mfma_f32_16x16x32_bf16 v[120:123], v[154:157], v[178:181], v[120:123]
	v_mfma_f32_16x16x32_bf16 v[108:111], v[146:149], v[186:189], v[108:111]
	v_mfma_f32_16x16x32_bf16 v[104:107], v[154:157], v[186:189], v[104:107]
	v_mfma_f32_16x16x32_bf16 v[92:95], v[146:149], v[214:217], v[92:95]
	v_mfma_f32_16x16x32_bf16 v[88:91], v[154:157], v[214:217], v[88:91]
	v_mfma_f32_16x16x32_bf16 v[76:79], v[146:149], v[224:227], v[76:79]
	v_mfma_f32_16x16x32_bf16 v[72:75], v[154:157], v[224:227], v[72:75]
	v_mfma_f32_16x16x32_bf16 v[124:127], v[150:153], v[182:185], v[124:127]
	v_mfma_f32_16x16x32_bf16 v[120:123], v[158:161], v[182:185], v[120:123]
	v_mfma_f32_16x16x32_bf16 v[108:111], v[150:153], v[190:193], v[108:111]
	v_mfma_f32_16x16x32_bf16 v[104:107], v[158:161], v[190:193], v[104:107]
	v_mfma_f32_16x16x32_bf16 v[92:95], v[150:153], v[220:223], v[92:95]
	v_mfma_f32_16x16x32_bf16 v[88:91], v[158:161], v[220:223], v[88:91]
	v_mfma_f32_16x16x32_bf16 v[76:79], v[150:153], v[228:231], v[76:79]
	v_mfma_f32_16x16x32_bf16 v[72:75], v[158:161], v[228:231], v[72:75]
	s_setprio 0
	s_setprio 1
	v_mfma_f32_16x16x32_bf16 v[116:119], v[162:165], v[178:181], v[116:119]
	v_mfma_f32_16x16x32_bf16 v[112:115], v[170:173], v[178:181], v[112:115]
	v_mfma_f32_16x16x32_bf16 v[100:103], v[162:165], v[186:189], v[100:103]
	v_mfma_f32_16x16x32_bf16 v[96:99], v[170:173], v[186:189], v[96:99]
	v_mfma_f32_16x16x32_bf16 v[84:87], v[162:165], v[214:217], v[84:87]
	v_mfma_f32_16x16x32_bf16 v[80:83], v[170:173], v[214:217], v[80:83]
	v_mfma_f32_16x16x32_bf16 v[68:71], v[162:165], v[224:227], v[68:71]
	v_mfma_f32_16x16x32_bf16 v[64:67], v[170:173], v[224:227], v[64:67]
	v_mfma_f32_16x16x32_bf16 v[116:119], v[166:169], v[182:185], v[116:119]
	v_mfma_f32_16x16x32_bf16 v[112:115], v[174:177], v[182:185], v[112:115]
	v_mfma_f32_16x16x32_bf16 v[100:103], v[166:169], v[190:193], v[100:103]
	v_mfma_f32_16x16x32_bf16 v[96:99], v[174:177], v[190:193], v[96:99]
	v_mfma_f32_16x16x32_bf16 v[84:87], v[166:169], v[220:223], v[84:87]
	v_mfma_f32_16x16x32_bf16 v[80:83], v[174:177], v[220:223], v[80:83]
	v_mfma_f32_16x16x32_bf16 v[68:71], v[166:169], v[228:231], v[68:71]
	v_mfma_f32_16x16x32_bf16 v[64:67], v[174:177], v[228:231], v[64:67]
	s_setprio 0
	s_barrier
; __device__ __forceinline__ u32x4 pack8_bf16(f32x4 a, f32x4 b) { u32x4 w; w.x = cvt_pk_bf16(a[0], a[1]); w.y = cvt_pk_bf16(a[2], a[3]); w.z = cvt_pk_bf16(b[0], b[1]); w.w = cvt_pk_bf16(b[2], b[3]); return w; }
; #define PG8_STAGE(bufoff, gbase, voff) do { _Pragma("unroll") for (int _i = 0; _i < 2; ++_i) \
;         __builtin_amdgcn_global_load_lds((const unsigned*)((const char*)(gbase) + (voff)[_i]), (PG8_LAS unsigned*)(lds + (bufoff) + ldsw + _i * 8192), 16, 0, 0); } while (0)
; #define PG8_LDA(dst, b, h) do { _Pragma("unroll") for (int m = 0; m < 4; ++m) _Pragma("unroll") for (int k = 0; k < 2; ++k) dst[m][k] = *(const PG8_LAS bf16x8*)(lds + PG8_SA(b, h) + aoff + m * 2048 + k * 1024); } while (0)
; #define PG8_WAIT_V(n) asm volatile("s_waitcnt vmcnt(" #n ")" ::: "memory")
; #define PG8_WAIT_L(n) asm volatile("s_waitcnt lgkmcnt(" #n ")" ::: "memory")
; #define PG8_BAR __builtin_amdgcn_s_barrier()
;     __device__ __forceinline__ void operator()(const f32x4 (&acc)[2][2][4][2], const Unit& u, int wr, int wc, int fr, int fq) const {
;         const int g = u.pn / nNper, pnl = u.pn - g * nNper, pml = u.pm & 63;
;         bf16_t* base = O + (size_t)g * gstride;
;         const int row0 = pml * BM + wr * 64 + fr, col0 = pnl * BM + wc * 32 + 8 * fq;
; #pragma unroll
;         for (int ai = 0; ai < 2; ++ai)
; #pragma unroll
;             for (int m = 0; m < 4; ++m) { bf16_t* rowp = base + (size_t)(row0 + ai * HALF + m * 16) * ldc + col0;
; #pragma unroll
;                 for (int bj = 0; bj < 2; ++bj) { f32x4 v0 = acc[ai][bj][m][0], v1 = acc[ai][bj][m][1];
;                     if (ACT == 1) {
; #pragma unroll
;                         for (int j = 0; j < 4; ++j) { float a = fmaxf(v0[j], 0.f), b = fmaxf(v1[j], 0.f); v0[j] = a * a; v1[j] = b * b; } }
;                     *(u32x4*)(rowp + bj * HALF) = pack8_bf16(v0, v1); } }
; template <class Epi, class Sched, bool ALIGN_EPI = false, bool SP2 = false>
; __device__ __forceinline__ void gemm_phase(PG8_LAS unsigned char* lds, const Gemm g, const Sched& S, const Epi& E) {
;     ...
;             PG8_LDA(At, 1, 1); PG8_STAGE(PG8_SB(1, 0), b3, voffB); PG8_STAGE(PG8_SB(1, 1), b3 + hstep, voffB); PG8_STAGE(PG8_SA(1, 0), a3, voffA);
;             PG8_WAIT_V(8); PG8_WAIT_L(0); PG8_BAR; PG8_MMA(1, 0, At, B0); PG8_MMA(1, 1, At, B1); PG8_BAR; PG8_SCHED;
;     ...
;         if constexpr (ALIGN_EPI) { if (wr == 0) PG8_BAR; }
	s_add_i32 s7, s7, s2
	v_lshl_add_u64 v[140:141], v[140:141], 0, s[20:21]
	s_mov_b32 m0, s7
	ds_read_b128 v[178:181], v145 offset:49152
	ds_read_b128 v[182:185], v145 offset:50176
	ds_read_b128 v[186:189], v145 offset:51200
	ds_read_b128 v[190:193], v145 offset:52224
	ds_read_b128 v[214:217], v145 offset:53248
	ds_read_b128 v[220:223], v145 offset:54272
	ds_read_b128 v[224:227], v145 offset:55296
	ds_read_b128 v[228:231], v145 offset:56320
	global_load_lds_dwordx4 v[140:141], off
	s_add_i32 m0, s7, 0x2000
	s_add_u32 s58, s58, 0x20080
	v_lshl_add_u64 v[140:141], v[206:207], 0, s[20:21]
	s_addc_u32 s59, s59, 0
	s_add_i32 s7, s62, s2
	global_load_lds_dwordx4 v[140:141], off
	v_lshl_add_u64 v[140:141], s[58:59], 0, v[128:129]
	s_mov_b32 m0, s7
	s_nop 0
	global_load_lds_dwordx4 v[140:141], off
	v_lshl_add_u64 v[140:141], s[58:59], 0, v[130:131]
	s_add_i32 m0, s7, 0x2000
	s_nop 0
	global_load_lds_dwordx4 v[140:141], off
	v_lshl_add_u64 v[140:141], v[232:233], 0, s[20:21]
	s_mov_b32 m0, s28
	s_nop 0
	global_load_lds_dwordx4 v[140:141], off
	v_lshl_add_u64 v[140:141], v[234:235], 0, s[20:21]
	s_mov_b32 m0, s29
	s_nop 0
	global_load_lds_dwordx4 v[140:141], off
	s_waitcnt vmcnt(8)
	s_waitcnt lgkmcnt(0)
	s_barrier
	s_setprio 1
	s_waitcnt lgkmcnt(0)
	v_mfma_f32_16x16x32_bf16 v[60:63], v[146:149], v[178:181], v[60:63]
	v_mfma_f32_16x16x32_bf16 v[56:59], v[154:157], v[178:181], v[56:59]
	v_mfma_f32_16x16x32_bf16 v[44:47], v[146:149], v[186:189], v[44:47]
	v_mfma_f32_16x16x32_bf16 v[40:43], v[154:157], v[186:189], v[40:43]
	v_mfma_f32_16x16x32_bf16 v[28:31], v[146:149], v[214:217], v[28:31]
	v_mfma_f32_16x16x32_bf16 v[24:27], v[154:157], v[214:217], v[24:27]
	v_mfma_f32_16x16x32_bf16 v[12:15], v[146:149], v[224:227], v[12:15]
	v_mfma_f32_16x16x32_bf16 v[8:11], v[154:157], v[224:227], v[8:11]
	v_mfma_f32_16x16x32_bf16 v[60:63], v[150:153], v[182:185], v[60:63]
	v_mfma_f32_16x16x32_bf16 v[56:59], v[158:161], v[182:185], v[56:59]
	v_mfma_f32_16x16x32_bf16 v[44:47], v[150:153], v[190:193], v[44:47]
	v_mfma_f32_16x16x32_bf16 v[40:43], v[158:161], v[190:193], v[40:43]
	v_mfma_f32_16x16x32_bf16 v[28:31], v[150:153], v[220:223], v[28:31]
	v_mfma_f32_16x16x32_bf16 v[24:27], v[158:161], v[220:223], v[24:27]
	v_mfma_f32_16x16x32_bf16 v[12:15], v[150:153], v[228:231], v[12:15]
	v_mfma_f32_16x16x32_bf16 v[8:11], v[158:161], v[228:231], v[8:11]
	s_setprio 0
	s_setprio 1
	v_mfma_f32_16x16x32_bf16 v[52:55], v[162:165], v[178:181], v[52:55]
	v_mfma_f32_16x16x32_bf16 v[48:51], v[170:173], v[178:181], v[48:51]
	v_mfma_f32_16x16x32_bf16 v[36:39], v[162:165], v[186:189], v[36:39]
	v_mfma_f32_16x16x32_bf16 v[32:35], v[170:173], v[186:189], v[32:35]
	v_mfma_f32_16x16x32_bf16 v[20:23], v[162:165], v[214:217], v[20:23]
	v_mfma_f32_16x16x32_bf16 v[16:19], v[170:173], v[214:217], v[16:19]
	v_mfma_f32_16x16x32_bf16 v[4:7], v[162:165], v[224:227], v[4:7]
	v_mfma_f32_16x16x32_bf16 v[0:3], v[170:173], v[224:227], v[0:3]
	v_mfma_f32_16x16x32_bf16 v[52:55], v[166:169], v[182:185], v[52:55]
	v_mfma_f32_16x16x32_bf16 v[48:51], v[174:177], v[182:185], v[48:51]
	v_mfma_f32_16x16x32_bf16 v[36:39], v[166:169], v[190:193], v[36:39]
	v_mfma_f32_16x16x32_bf16 v[32:35], v[174:177], v[190:193], v[32:35]
	v_mfma_f32_16x16x32_bf16 v[20:23], v[166:169], v[220:223], v[20:23]
	v_mfma_f32_16x16x32_bf16 v[16:19], v[174:177], v[220:223], v[16:19]
	v_mfma_f32_16x16x32_bf16 v[4:7], v[166:169], v[228:231], v[4:7]
	v_mfma_f32_16x16x32_bf16 v[0:3], v[174:177], v[228:231], v[0:3]
	s_setprio 0
	s_barrier
	s_add_i32 s55, s55, 2
	s_add_u32 s56, s56, 0x100
	s_addc_u32 s57, s57, 0
	s_add_u32 s47, s47, 0x100
	s_addc_u32 s53, s53, 0
	s_cmp_gt_u32 s55, 29
	s_cbranch_scc0 .LBB0_59
	s_and_b64 vcc, exec, s[42:43]
	s_cbranch_vccz .LBB0_62
	s_barrier
.LBB0_62:
	s_ashr_i32 s7, s54, 31
	s_lshr_b32 s7, s7, 27
	s_add_i32 s7, s54, s7
	s_and_b32 s7, s7, 0xffffe0
	s_lshl_b32 s34, s52, 8
	s_sub_i32 s7, s54, s7
	s_and_b32 s34, s34, 0x3f00
	v_add_u32_e32 v146, s34, v142
	v_lshl_or_b32 v140, s7, 8, v144
	v_ashrrev_i32_e32 v141, 31, v140
	v_ashrrev_i32_e32 v147, 31, v146
	v_lshl_add_u64 v[148:149], v[140:141], 1, s[8:9]
	v_lshlrev_b64 v[140:141], 14, v[146:147]
	v_lshl_add_u64 v[140:141], v[148:149], 0, v[140:141]
	s_mov_b64 s[34:35], 0x40000
	v_mov_b32_e32 v242, 0x20000
	v_mov_b32_e32 v243, 0
	v_and_b32_e32 v238, 8, v208
	v_cmp_ne_u32_e32 vcc, 0, v238
	v_and_b32_e32 v240, 63, v208
	v_lshrrev_b32_e32 v241, 3, v240
	v_and_b32_e32 v244, 3, v240
	v_lshl_add_u32 v241, v244, 4, v241
	v_and_b32_e32 v244, 4, v240
	v_lshl_add_u32 v241, v244, 1, v241
	v_lshlrev_b32_e32 v240, 2, v241
	v_max_f32_e32 v124, 0, v124
	v_max_f32_e32 v125, 0, v125
	v_max_f32_e32 v126, 0, v126
	v_max_f32_e32 v127, 0, v127
	v_max_f32_e32 v120, 0, v120
	v_max_f32_e32 v121, 0, v121
	v_max_f32_e32 v122, 0, v122
	v_max_f32_e32 v123, 0, v123
	v_max_f32_e32 v116, 0, v116
	v_max_f32_e32 v117, 0, v117
	v_max_f32_e32 v118, 0, v118
	v_max_f32_e32 v119, 0, v119
	v_max_f32_e32 v112, 0, v112
	v_max_f32_e32 v113, 0, v113
	v_max_f32_e32 v114, 0, v114
	v_max_f32_e32 v115, 0, v115
	v_mul_f32_e32 v124, v124, v124
	v_mul_f32_e32 v125, v125, v125
	v_mul_f32_e32 v126, v126, v126
	v_mul_f32_e32 v127, v127, v127
	v_mul_f32_e32 v120, v120, v120
	v_mul_f32_e32 v121, v121, v121
	v_mul_f32_e32 v122, v122, v122
	v_mul_f32_e32 v123, v123, v123
	v_mul_f32_e32 v116, v116, v116
	v_mul_f32_e32 v117, v117, v117
	v_mul_f32_e32 v118, v118, v118
	v_mul_f32_e32 v119, v119, v119
	v_mul_f32_e32 v112, v112, v112
	v_mul_f32_e32 v113, v113, v113
	v_mul_f32_e32 v114, v114, v114
	v_mul_f32_e32 v115, v115, v115
	v_cvt_pk_bf16_f32 v124, v124, v125
	v_cvt_pk_bf16_f32 v125, v126, v127
	v_cvt_pk_bf16_f32 v126, v120, v121
	v_cvt_pk_bf16_f32 v127, v122, v123
	v_cvt_pk_bf16_f32 v116, v116, v117
	v_cvt_pk_bf16_f32 v117, v118, v119
	v_cvt_pk_bf16_f32 v118, v112, v113
	v_cvt_pk_bf16_f32 v119, v114, v115
	v_mov_b32_dpp v246, v116 row_ror:8 row_mask:0xf bank_mask:0xf
	v_mov_b32_dpp v247, v117 row_ror:8 row_mask:0xf bank_mask:0xf
	v_mov_b32_dpp v248, v118 row_ror:8 row_mask:0xf bank_mask:0xf
	v_mov_b32_dpp v249, v119 row_ror:8 row_mask:0xf bank_mask:0xf
	v_mov_b32_dpp v250, v124 row_ror:8 row_mask:0xf bank_mask:0xf
	v_mov_b32_dpp v251, v125 row_ror:8 row_mask:0xf bank_mask:0xf
	v_mov_b32_dpp v252, v126 row_ror:8 row_mask:0xf bank_mask:0xf
	v_mov_b32_dpp v253, v127 row_ror:8 row_mask:0xf bank_mask:0xf
	v_cndmask_b32_e32 v246, v124, v246, vcc
	v_cndmask_b32_e32 v247, v125, v247, vcc
	v_cndmask_b32_e32 v248, v126, v248, vcc
	v_cndmask_b32_e32 v249, v127, v249, vcc
	v_cndmask_b32_e32 v250, v250, v116, vcc
	v_cndmask_b32_e32 v251, v251, v117, vcc
	v_cndmask_b32_e32 v252, v252, v118, vcc
	v_cndmask_b32_e32 v253, v253, v119, vcc
	ds_bpermute_b32 v246, v240, v246
	ds_bpermute_b32 v247, v240, v247
	ds_bpermute_b32 v248, v240, v248
	ds_bpermute_b32 v249, v240, v249
	ds_bpermute_b32 v250, v240, v250
	ds_bpermute_b32 v251, v240, v251
	ds_bpermute_b32 v252, v240, v252
	ds_bpermute_b32 v253, v240, v253
	v_lshl_add_u64 v[238:239], v[140:141], 0, v[242:243]
	s_waitcnt lgkmcnt(4)
; __device__ __forceinline__ u32x4 pack8_bf16(f32x4 a, f32x4 b) { u32x4 w; w.x = cvt_pk_bf16(a[0], a[1]); w.y = cvt_pk_bf16(a[2], a[3]); w.z = cvt_pk_bf16(b[0], b[1]); w.w = cvt_pk_bf16(b[2], b[3]); return w; }
; #define ACT(t) (KBASE(t) <= qlo + QBLK - 1 && KBASE(t) + KVBLK - 1 >= qlo - W + 1)
;     __device__ __forceinline__ void operator()(const f32x4 (&acc)[2][2][4][2], const Unit& u, int wr, int wc, int fr, int fq) const {
;         const int g = u.pn / nNper, pnl = u.pn - g * nNper, pml = u.pm & 63;
;         bf16_t* base = O + (size_t)g * gstride;
;         const int row0 = pml * BM + wr * 64 + fr, col0 = pnl * BM + wc * 32 + 8 * fq;
; #pragma unroll
;         for (int ai = 0; ai < 2; ++ai)
; #pragma unroll
;             for (int m = 0; m < 4; ++m) { bf16_t* rowp = base + (size_t)(row0 + ai * HALF + m * 16) * ldc + col0;
; #pragma unroll
;                 for (int bj = 0; bj < 2; ++bj) { f32x4 v0 = acc[ai][bj][m][0], v1 = acc[ai][bj][m][1];
;                     if (ACT == 1) {
; #pragma unroll
;                         for (int j = 0; j < 4; ++j) { float a = fmaxf(v0[j], 0.f), b = fmaxf(v1[j], 0.f); v0[j] = a * a; v1[j] = b * b; } }
;                     *(u32x4*)(rowp + bj * HALF) = pack8_bf16(v0, v1); } }
	global_store_dwordx4 v[140:141], v[246:249], off
	s_waitcnt lgkmcnt(0)
	global_store_dwordx4 v[238:239], v[250:253], off
	v_lshl_add_u64 v[140:141], v[140:141], 0, s[34:35]
	v_max_f32_e32 v108, 0, v108
	v_max_f32_e32 v109, 0, v109
	v_max_f32_e32 v110, 0, v110
	v_max_f32_e32 v111, 0, v111
	v_max_f32_e32 v104, 0, v104
	v_max_f32_e32 v105, 0, v105
	v_max_f32_e32 v106, 0, v106
	v_max_f32_e32 v107, 0, v107
	v_max_f32_e32 v100, 0, v100
	v_max_f32_e32 v101, 0, v101
	v_max_f32_e32 v102, 0, v102
	v_max_f32_e32 v103, 0, v103
	v_max_f32_e32 v96, 0, v96
	v_max_f32_e32 v97, 0, v97
	v_max_f32_e32 v98, 0, v98
	v_max_f32_e32 v99, 0, v99
	v_mul_f32_e32 v108, v108, v108
	v_mul_f32_e32 v109, v109, v109
	v_mul_f32_e32 v110, v110, v110
	v_mul_f32_e32 v111, v111, v111
	v_mul_f32_e32 v104, v104, v104
	v_mul_f32_e32 v105, v105, v105
	v_mul_f32_e32 v106, v106, v106
	v_mul_f32_e32 v107, v107, v107
	v_mul_f32_e32 v100, v100, v100
	v_mul_f32_e32 v101, v101, v101
	v_mul_f32_e32 v102, v102, v102
	v_mul_f32_e32 v103, v103, v103
	v_mul_f32_e32 v96, v96, v96
	v_mul_f32_e32 v97, v97, v97
	v_mul_f32_e32 v98, v98, v98
	v_mul_f32_e32 v99, v99, v99
	v_cvt_pk_bf16_f32 v108, v108, v109
	v_cvt_pk_bf16_f32 v109, v110, v111
	v_cvt_pk_bf16_f32 v110, v104, v105
	v_cvt_pk_bf16_f32 v111, v106, v107
	v_cvt_pk_bf16_f32 v100, v100, v101
	v_cvt_pk_bf16_f32 v101, v102, v103
	v_cvt_pk_bf16_f32 v102, v96, v97
	v_cvt_pk_bf16_f32 v103, v98, v99
	v_mov_b32_dpp v246, v100 row_ror:8 row_mask:0xf bank_mask:0xf
	v_mov_b32_dpp v247, v101 row_ror:8 row_mask:0xf bank_mask:0xf
	v_mov_b32_dpp v248, v102 row_ror:8 row_mask:0xf bank_mask:0xf
	v_mov_b32_dpp v249, v103 row_ror:8 row_mask:0xf bank_mask:0xf
	v_mov_b32_dpp v250, v108 row_ror:8 row_mask:0xf bank_mask:0xf
	v_mov_b32_dpp v251, v109 row_ror:8 row_mask:0xf bank_mask:0xf
	v_mov_b32_dpp v252, v110 row_ror:8 row_mask:0xf bank_mask:0xf
	v_mov_b32_dpp v253, v111 row_ror:8 row_mask:0xf bank_mask:0xf
	v_cndmask_b32_e32 v246, v108, v246, vcc
	v_cndmask_b32_e32 v247, v109, v247, vcc
	v_cndmask_b32_e32 v248, v110, v248, vcc
	v_cndmask_b32_e32 v249, v111, v249, vcc
	v_cndmask_b32_e32 v250, v250, v100, vcc
	v_cndmask_b32_e32 v251, v251, v101, vcc
	v_cndmask_b32_e32 v252, v252, v102, vcc
	v_cndmask_b32_e32 v253, v253, v103, vcc
	ds_bpermute_b32 v246, v240, v246
	ds_bpermute_b32 v247, v240, v247
	ds_bpermute_b32 v248, v240, v248
	ds_bpermute_b32 v249, v240, v249
	ds_bpermute_b32 v250, v240, v250
	ds_bpermute_b32 v251, v240, v251
	ds_bpermute_b32 v252, v240, v252
	ds_bpermute_b32 v253, v240, v253
	v_lshl_add_u64 v[238:239], v[140:141], 0, v[242:243]
	s_waitcnt lgkmcnt(4)
	global_store_dwordx4 v[140:141], v[246:249], off
	s_waitcnt lgkmcnt(0)
	global_store_dwordx4 v[238:239], v[250:253], off
	v_lshl_add_u64 v[140:141], v[140:141], 0, s[34:35]
	v_max_f32_e32 v92, 0, v92
	v_max_f32_e32 v93, 0, v93
	v_max_f32_e32 v94, 0, v94
	v_max_f32_e32 v95, 0, v95
	v_max_f32_e32 v88, 0, v88
	v_max_f32_e32 v89, 0, v89
	v_max_f32_e32 v90, 0, v90
	v_max_f32_e32 v91, 0, v91
	v_max_f32_e32 v84, 0, v84
	v_max_f32_e32 v85, 0, v85
	v_max_f32_e32 v86, 0, v86
	v_max_f32_e32 v87, 0, v87
	v_max_f32_e32 v80, 0, v80
	v_max_f32_e32 v81, 0, v81
	v_max_f32_e32 v82, 0, v82
	v_max_f32_e32 v83, 0, v83
	v_mul_f32_e32 v92, v92, v92
	v_mul_f32_e32 v93, v93, v93
	v_mul_f32_e32 v94, v94, v94
	v_mul_f32_e32 v95, v95, v95
	v_mul_f32_e32 v88, v88, v88
	v_mul_f32_e32 v89, v89, v89
	v_mul_f32_e32 v90, v90, v90
	v_mul_f32_e32 v91, v91, v91
	v_mul_f32_e32 v84, v84, v84
	v_mul_f32_e32 v85, v85, v85
	v_mul_f32_e32 v86, v86, v86
	v_mul_f32_e32 v87, v87, v87
	v_mul_f32_e32 v80, v80, v80
	v_mul_f32_e32 v81, v81, v81
	v_mul_f32_e32 v82, v82, v82
	v_mul_f32_e32 v83, v83, v83
	v_cvt_pk_bf16_f32 v92, v92, v93
	v_cvt_pk_bf16_f32 v93, v94, v95
	v_cvt_pk_bf16_f32 v94, v88, v89
	v_cvt_pk_bf16_f32 v95, v90, v91
	v_cvt_pk_bf16_f32 v84, v84, v85
	v_cvt_pk_bf16_f32 v85, v86, v87
	v_cvt_pk_bf16_f32 v86, v80, v81
	v_cvt_pk_bf16_f32 v87, v82, v83
	v_mov_b32_dpp v246, v84 row_ror:8 row_mask:0xf bank_mask:0xf
	v_mov_b32_dpp v247, v85 row_ror:8 row_mask:0xf bank_mask:0xf
	v_mov_b32_dpp v248, v86 row_ror:8 row_mask:0xf bank_mask:0xf
	v_mov_b32_dpp v249, v87 row_ror:8 row_mask:0xf bank_mask:0xf
	v_mov_b32_dpp v250, v92 row_ror:8 row_mask:0xf bank_mask:0xf
	v_mov_b32_dpp v251, v93 row_ror:8 row_mask:0xf bank_mask:0xf
	v_mov_b32_dpp v252, v94 row_ror:8 row_mask:0xf bank_mask:0xf
	v_mov_b32_dpp v253, v95 row_ror:8 row_mask:0xf bank_mask:0xf
	v_cndmask_b32_e32 v246, v92, v246, vcc
	v_cndmask_b32_e32 v247, v93, v247, vcc
	v_cndmask_b32_e32 v248, v94, v248, vcc
	v_cndmask_b32_e32 v249, v95, v249, vcc
	v_cndmask_b32_e32 v250, v250, v84, vcc
	v_cndmask_b32_e32 v251, v251, v85, vcc
	v_cndmask_b32_e32 v252, v252, v86, vcc
	v_cndmask_b32_e32 v253, v253, v87, vcc
	ds_bpermute_b32 v246, v240, v246
	ds_bpermute_b32 v247, v240, v247
	ds_bpermute_b32 v248, v240, v248
	ds_bpermute_b32 v249, v240, v249
	ds_bpermute_b32 v250, v240, v250
	ds_bpermute_b32 v251, v240, v251
	ds_bpermute_b32 v252, v240, v252
	ds_bpermute_b32 v253, v240, v253
	v_lshl_add_u64 v[238:239], v[140:141], 0, v[242:243]
	s_waitcnt lgkmcnt(4)
	global_store_dwordx4 v[140:141], v[246:249], off
	s_waitcnt lgkmcnt(0)
; __device__ __forceinline__ u32x4 pack8_bf16(f32x4 a, f32x4 b) { u32x4 w; w.x = cvt_pk_bf16(a[0], a[1]); w.y = cvt_pk_bf16(a[2], a[3]); w.z = cvt_pk_bf16(b[0], b[1]); w.w = cvt_pk_bf16(b[2], b[3]); return w; }
; #define ACT(t) (KBASE(t) <= qlo + QBLK - 1 && KBASE(t) + KVBLK - 1 >= qlo - W + 1)
;     __device__ __forceinline__ void operator()(const f32x4 (&acc)[2][2][4][2], const Unit& u, int wr, int wc, int fr, int fq) const {
;         const int g = u.pn / nNper, pnl = u.pn - g * nNper, pml = u.pm & 63;
;         bf16_t* base = O + (size_t)g * gstride;
;         const int row0 = pml * BM + wr * 64 + fr, col0 = pnl * BM + wc * 32 + 8 * fq;
; #pragma unroll
;         for (int ai = 0; ai < 2; ++ai)
; #pragma unroll
;             for (int m = 0; m < 4; ++m) { bf16_t* rowp = base + (size_t)(row0 + ai * HALF + m * 16) * ldc + col0;
; #pragma unroll
;                 for (int bj = 0; bj < 2; ++bj) { f32x4 v0 = acc[ai][bj][m][0], v1 = acc[ai][bj][m][1];
;                     if (ACT == 1) {
; #pragma unroll
;                         for (int j = 0; j < 4; ++j) { float a = fmaxf(v0[j], 0.f), b = fmaxf(v1[j], 0.f); v0[j] = a * a; v1[j] = b * b; } }
;                     *(u32x4*)(rowp + bj * HALF) = pack8_bf16(v0, v1); } }
	global_store_dwordx4 v[238:239], v[250:253], off
	v_lshl_add_u64 v[140:141], v[140:141], 0, s[34:35]
	v_max_f32_e32 v76, 0, v76
	v_max_f32_e32 v77, 0, v77
	v_max_f32_e32 v78, 0, v78
	v_max_f32_e32 v79, 0, v79
	v_max_f32_e32 v72, 0, v72
	v_max_f32_e32 v73, 0, v73
	v_max_f32_e32 v74, 0, v74
	v_max_f32_e32 v75, 0, v75
	v_max_f32_e32 v68, 0, v68
	v_max_f32_e32 v69, 0, v69
	v_max_f32_e32 v70, 0, v70
	v_max_f32_e32 v71, 0, v71
	v_max_f32_e32 v64, 0, v64
	v_max_f32_e32 v65, 0, v65
	v_max_f32_e32 v66, 0, v66
	v_max_f32_e32 v67, 0, v67
	v_mul_f32_e32 v76, v76, v76
	v_mul_f32_e32 v77, v77, v77
	v_mul_f32_e32 v78, v78, v78
	v_mul_f32_e32 v79, v79, v79
	v_mul_f32_e32 v72, v72, v72
	v_mul_f32_e32 v73, v73, v73
	v_mul_f32_e32 v74, v74, v74
	v_mul_f32_e32 v75, v75, v75
	v_mul_f32_e32 v68, v68, v68
	v_mul_f32_e32 v69, v69, v69
	v_mul_f32_e32 v70, v70, v70
	v_mul_f32_e32 v71, v71, v71
	v_mul_f32_e32 v64, v64, v64
	v_mul_f32_e32 v65, v65, v65
	v_mul_f32_e32 v66, v66, v66
	v_mul_f32_e32 v67, v67, v67
	v_cvt_pk_bf16_f32 v76, v76, v77
	v_cvt_pk_bf16_f32 v77, v78, v79
	v_cvt_pk_bf16_f32 v78, v72, v73
	v_cvt_pk_bf16_f32 v79, v74, v75
	v_cvt_pk_bf16_f32 v68, v68, v69
	v_cvt_pk_bf16_f32 v69, v70, v71
	v_cvt_pk_bf16_f32 v70, v64, v65
	v_cvt_pk_bf16_f32 v71, v66, v67
	v_mov_b32_dpp v246, v68 row_ror:8 row_mask:0xf bank_mask:0xf
	v_mov_b32_dpp v247, v69 row_ror:8 row_mask:0xf bank_mask:0xf
	v_mov_b32_dpp v248, v70 row_ror:8 row_mask:0xf bank_mask:0xf
	v_mov_b32_dpp v249, v71 row_ror:8 row_mask:0xf bank_mask:0xf
	v_mov_b32_dpp v250, v76 row_ror:8 row_mask:0xf bank_mask:0xf
	v_mov_b32_dpp v251, v77 row_ror:8 row_mask:0xf bank_mask:0xf
	v_mov_b32_dpp v252, v78 row_ror:8 row_mask:0xf bank_mask:0xf
	v_mov_b32_dpp v253, v79 row_ror:8 row_mask:0xf bank_mask:0xf
	v_cndmask_b32_e32 v246, v76, v246, vcc
	v_cndmask_b32_e32 v247, v77, v247, vcc
	v_cndmask_b32_e32 v248, v78, v248, vcc
	v_cndmask_b32_e32 v249, v79, v249, vcc
	v_cndmask_b32_e32 v250, v250, v68, vcc
	v_cndmask_b32_e32 v251, v251, v69, vcc
	v_cndmask_b32_e32 v252, v252, v70, vcc
	v_cndmask_b32_e32 v253, v253, v71, vcc
	ds_bpermute_b32 v246, v240, v246
	ds_bpermute_b32 v247, v240, v247
	ds_bpermute_b32 v248, v240, v248
	ds_bpermute_b32 v249, v240, v249
	ds_bpermute_b32 v250, v240, v250
	ds_bpermute_b32 v251, v240, v251
	ds_bpermute_b32 v252, v240, v252
	ds_bpermute_b32 v253, v240, v253
	v_lshl_add_u64 v[238:239], v[140:141], 0, v[242:243]
	s_waitcnt lgkmcnt(4)
	global_store_dwordx4 v[140:141], v[246:249], off
	s_waitcnt lgkmcnt(0)
	global_store_dwordx4 v[238:239], v[250:253], off
	s_mov_b64 s[34:35], 0x140000
	v_lshl_add_u64 v[140:141], v[140:141], 0, s[34:35]
	s_mov_b64 s[34:35], 0x40000
	v_max_f32_e32 v60, 0, v60
	v_max_f32_e32 v61, 0, v61
	v_max_f32_e32 v62, 0, v62
	v_max_f32_e32 v63, 0, v63
	v_max_f32_e32 v56, 0, v56
	v_max_f32_e32 v57, 0, v57
	v_max_f32_e32 v58, 0, v58
	v_max_f32_e32 v59, 0, v59
	v_max_f32_e32 v52, 0, v52
	v_max_f32_e32 v53, 0, v53
	v_max_f32_e32 v54, 0, v54
	v_max_f32_e32 v55, 0, v55
	v_max_f32_e32 v48, 0, v48
	v_max_f32_e32 v49, 0, v49
	v_max_f32_e32 v50, 0, v50
	v_max_f32_e32 v51, 0, v51
	v_mul_f32_e32 v60, v60, v60
	v_mul_f32_e32 v61, v61, v61
	v_mul_f32_e32 v62, v62, v62
	v_mul_f32_e32 v63, v63, v63
	v_mul_f32_e32 v56, v56, v56
	v_mul_f32_e32 v57, v57, v57
	v_mul_f32_e32 v58, v58, v58
	v_mul_f32_e32 v59, v59, v59
	v_mul_f32_e32 v52, v52, v52
	v_mul_f32_e32 v53, v53, v53
	v_mul_f32_e32 v54, v54, v54
	v_mul_f32_e32 v55, v55, v55
	v_mul_f32_e32 v48, v48, v48
	v_mul_f32_e32 v49, v49, v49
	v_mul_f32_e32 v50, v50, v50
	v_mul_f32_e32 v51, v51, v51
	v_cvt_pk_bf16_f32 v60, v60, v61
	v_cvt_pk_bf16_f32 v61, v62, v63
	v_cvt_pk_bf16_f32 v62, v56, v57
	v_cvt_pk_bf16_f32 v63, v58, v59
	v_cvt_pk_bf16_f32 v52, v52, v53
	v_cvt_pk_bf16_f32 v53, v54, v55
	v_cvt_pk_bf16_f32 v54, v48, v49
	v_cvt_pk_bf16_f32 v55, v50, v51
	v_mov_b32_dpp v246, v52 row_ror:8 row_mask:0xf bank_mask:0xf
	v_mov_b32_dpp v247, v53 row_ror:8 row_mask:0xf bank_mask:0xf
	v_mov_b32_dpp v248, v54 row_ror:8 row_mask:0xf bank_mask:0xf
	v_mov_b32_dpp v249, v55 row_ror:8 row_mask:0xf bank_mask:0xf
	v_mov_b32_dpp v250, v60 row_ror:8 row_mask:0xf bank_mask:0xf
	v_mov_b32_dpp v251, v61 row_ror:8 row_mask:0xf bank_mask:0xf
	v_mov_b32_dpp v252, v62 row_ror:8 row_mask:0xf bank_mask:0xf
	v_mov_b32_dpp v253, v63 row_ror:8 row_mask:0xf bank_mask:0xf
	v_cndmask_b32_e32 v246, v60, v246, vcc
	v_cndmask_b32_e32 v247, v61, v247, vcc
	v_cndmask_b32_e32 v248, v62, v248, vcc
	v_cndmask_b32_e32 v249, v63, v249, vcc
	v_cndmask_b32_e32 v250, v250, v52, vcc
	v_cndmask_b32_e32 v251, v251, v53, vcc
	v_cndmask_b32_e32 v252, v252, v54, vcc
	v_cndmask_b32_e32 v253, v253, v55, vcc
	ds_bpermute_b32 v246, v240, v246
	ds_bpermute_b32 v247, v240, v247
	ds_bpermute_b32 v248, v240, v248
	ds_bpermute_b32 v249, v240, v249
	ds_bpermute_b32 v250, v240, v250
	ds_bpermute_b32 v251, v240, v251
	ds_bpermute_b32 v252, v240, v252
	ds_bpermute_b32 v253, v240, v253
	v_lshl_add_u64 v[238:239], v[140:141], 0, v[242:243]
	s_waitcnt lgkmcnt(4)
	global_store_dwordx4 v[140:141], v[246:249], off
	s_waitcnt lgkmcnt(0)
; __device__ __forceinline__ u32x4 pack8_bf16(f32x4 a, f32x4 b) { u32x4 w; w.x = cvt_pk_bf16(a[0], a[1]); w.y = cvt_pk_bf16(a[2], a[3]); w.z = cvt_pk_bf16(b[0], b[1]); w.w = cvt_pk_bf16(b[2], b[3]); return w; }
; #define ACT(t) (KBASE(t) <= qlo + QBLK - 1 && KBASE(t) + KVBLK - 1 >= qlo - W + 1)
;     __device__ __forceinline__ void operator()(const f32x4 (&acc)[2][2][4][2], const Unit& u, int wr, int wc, int fr, int fq) const {
;         const int g = u.pn / nNper, pnl = u.pn - g * nNper, pml = u.pm & 63;
;         bf16_t* base = O + (size_t)g * gstride;
;         const int row0 = pml * BM + wr * 64 + fr, col0 = pnl * BM + wc * 32 + 8 * fq;
; #pragma unroll
;         for (int ai = 0; ai < 2; ++ai)
; #pragma unroll
;             for (int m = 0; m < 4; ++m) { bf16_t* rowp = base + (size_t)(row0 + ai * HALF + m * 16) * ldc + col0;
; #pragma unroll
;                 for (int bj = 0; bj < 2; ++bj) { f32x4 v0 = acc[ai][bj][m][0], v1 = acc[ai][bj][m][1];
;                     if (ACT == 1) {
; #pragma unroll
;                         for (int j = 0; j < 4; ++j) { float a = fmaxf(v0[j], 0.f), b = fmaxf(v1[j], 0.f); v0[j] = a * a; v1[j] = b * b; } }
;                     *(u32x4*)(rowp + bj * HALF) = pack8_bf16(v0, v1); } }
	global_store_dwordx4 v[238:239], v[250:253], off
	v_lshl_add_u64 v[140:141], v[140:141], 0, s[34:35]
	v_max_f32_e32 v44, 0, v44
	v_max_f32_e32 v45, 0, v45
	v_max_f32_e32 v46, 0, v46
	v_max_f32_e32 v47, 0, v47
	v_max_f32_e32 v40, 0, v40
	v_max_f32_e32 v41, 0, v41
	v_max_f32_e32 v42, 0, v42
	v_max_f32_e32 v43, 0, v43
	v_max_f32_e32 v36, 0, v36
	v_max_f32_e32 v37, 0, v37
	v_max_f32_e32 v38, 0, v38
	v_max_f32_e32 v39, 0, v39
	v_max_f32_e32 v32, 0, v32
	v_max_f32_e32 v33, 0, v33
	v_max_f32_e32 v34, 0, v34
	v_max_f32_e32 v35, 0, v35
	v_mul_f32_e32 v44, v44, v44
	v_mul_f32_e32 v45, v45, v45
	v_mul_f32_e32 v46, v46, v46
	v_mul_f32_e32 v47, v47, v47
	v_mul_f32_e32 v40, v40, v40
	v_mul_f32_e32 v41, v41, v41
	v_mul_f32_e32 v42, v42, v42
	v_mul_f32_e32 v43, v43, v43
	v_mul_f32_e32 v36, v36, v36
	v_mul_f32_e32 v37, v37, v37
	v_mul_f32_e32 v38, v38, v38
	v_mul_f32_e32 v39, v39, v39
	v_mul_f32_e32 v32, v32, v32
	v_mul_f32_e32 v33, v33, v33
	v_mul_f32_e32 v34, v34, v34
	v_mul_f32_e32 v35, v35, v35
	v_cvt_pk_bf16_f32 v44, v44, v45
	v_cvt_pk_bf16_f32 v45, v46, v47
	v_cvt_pk_bf16_f32 v46, v40, v41
	v_cvt_pk_bf16_f32 v47, v42, v43
	v_cvt_pk_bf16_f32 v36, v36, v37
	v_cvt_pk_bf16_f32 v37, v38, v39
	v_cvt_pk_bf16_f32 v38, v32, v33
	v_cvt_pk_bf16_f32 v39, v34, v35
	v_mov_b32_dpp v246, v36 row_ror:8 row_mask:0xf bank_mask:0xf
	v_mov_b32_dpp v247, v37 row_ror:8 row_mask:0xf bank_mask:0xf
	v_mov_b32_dpp v248, v38 row_ror:8 row_mask:0xf bank_mask:0xf
	v_mov_b32_dpp v249, v39 row_ror:8 row_mask:0xf bank_mask:0xf
	v_mov_b32_dpp v250, v44 row_ror:8 row_mask:0xf bank_mask:0xf
	v_mov_b32_dpp v251, v45 row_ror:8 row_mask:0xf bank_mask:0xf
	v_mov_b32_dpp v252, v46 row_ror:8 row_mask:0xf bank_mask:0xf
	v_mov_b32_dpp v253, v47 row_ror:8 row_mask:0xf bank_mask:0xf
	v_cndmask_b32_e32 v246, v44, v246, vcc
	v_cndmask_b32_e32 v247, v45, v247, vcc
	v_cndmask_b32_e32 v248, v46, v248, vcc
	v_cndmask_b32_e32 v249, v47, v249, vcc
	v_cndmask_b32_e32 v250, v250, v36, vcc
	v_cndmask_b32_e32 v251, v251, v37, vcc
	v_cndmask_b32_e32 v252, v252, v38, vcc
	v_cndmask_b32_e32 v253, v253, v39, vcc
	ds_bpermute_b32 v246, v240, v246
	ds_bpermute_b32 v247, v240, v247
	ds_bpermute_b32 v248, v240, v248
	ds_bpermute_b32 v249, v240, v249
	ds_bpermute_b32 v250, v240, v250
	ds_bpermute_b32 v251, v240, v251
	ds_bpermute_b32 v252, v240, v252
	ds_bpermute_b32 v253, v240, v253
	v_lshl_add_u64 v[238:239], v[140:141], 0, v[242:243]
	s_waitcnt lgkmcnt(4)
	global_store_dwordx4 v[140:141], v[246:249], off
	s_waitcnt lgkmcnt(0)
	global_store_dwordx4 v[238:239], v[250:253], off
	v_lshl_add_u64 v[140:141], v[140:141], 0, s[34:35]
	v_max_f32_e32 v28, 0, v28
	v_max_f32_e32 v29, 0, v29
	v_max_f32_e32 v30, 0, v30
	v_max_f32_e32 v31, 0, v31
	v_max_f32_e32 v24, 0, v24
	v_max_f32_e32 v25, 0, v25
	v_max_f32_e32 v26, 0, v26
	v_max_f32_e32 v27, 0, v27
	v_max_f32_e32 v20, 0, v20
	v_max_f32_e32 v21, 0, v21
	v_max_f32_e32 v22, 0, v22
	v_max_f32_e32 v23, 0, v23
	v_max_f32_e32 v16, 0, v16
	v_max_f32_e32 v17, 0, v17
	v_max_f32_e32 v18, 0, v18
	v_max_f32_e32 v19, 0, v19
	v_mul_f32_e32 v28, v28, v28
	v_mul_f32_e32 v29, v29, v29
	v_mul_f32_e32 v30, v30, v30
	v_mul_f32_e32 v31, v31, v31
	v_mul_f32_e32 v24, v24, v24
	v_mul_f32_e32 v25, v25, v25
	v_mul_f32_e32 v26, v26, v26
	v_mul_f32_e32 v27, v27, v27
	v_mul_f32_e32 v20, v20, v20
	v_mul_f32_e32 v21, v21, v21
	v_mul_f32_e32 v22, v22, v22
	v_mul_f32_e32 v23, v23, v23
	v_mul_f32_e32 v16, v16, v16
	v_mul_f32_e32 v17, v17, v17
	v_mul_f32_e32 v18, v18, v18
	v_mul_f32_e32 v19, v19, v19
	v_cvt_pk_bf16_f32 v28, v28, v29
	v_cvt_pk_bf16_f32 v29, v30, v31
	v_cvt_pk_bf16_f32 v30, v24, v25
	v_cvt_pk_bf16_f32 v31, v26, v27
	v_cvt_pk_bf16_f32 v20, v20, v21
	v_cvt_pk_bf16_f32 v21, v22, v23
	v_cvt_pk_bf16_f32 v22, v16, v17
	v_cvt_pk_bf16_f32 v23, v18, v19
	v_mov_b32_dpp v246, v20 row_ror:8 row_mask:0xf bank_mask:0xf
	v_mov_b32_dpp v247, v21 row_ror:8 row_mask:0xf bank_mask:0xf
	v_mov_b32_dpp v248, v22 row_ror:8 row_mask:0xf bank_mask:0xf
	v_mov_b32_dpp v249, v23 row_ror:8 row_mask:0xf bank_mask:0xf
	v_mov_b32_dpp v250, v28 row_ror:8 row_mask:0xf bank_mask:0xf
	v_mov_b32_dpp v251, v29 row_ror:8 row_mask:0xf bank_mask:0xf
	v_mov_b32_dpp v252, v30 row_ror:8 row_mask:0xf bank_mask:0xf
	v_mov_b32_dpp v253, v31 row_ror:8 row_mask:0xf bank_mask:0xf
	v_cndmask_b32_e32 v246, v28, v246, vcc
	v_cndmask_b32_e32 v247, v29, v247, vcc
	v_cndmask_b32_e32 v248, v30, v248, vcc
	v_cndmask_b32_e32 v249, v31, v249, vcc
	v_cndmask_b32_e32 v250, v250, v20, vcc
	v_cndmask_b32_e32 v251, v251, v21, vcc
	v_cndmask_b32_e32 v252, v252, v22, vcc
	v_cndmask_b32_e32 v253, v253, v23, vcc
	ds_bpermute_b32 v246, v240, v246
	ds_bpermute_b32 v247, v240, v247
	ds_bpermute_b32 v248, v240, v248
	ds_bpermute_b32 v249, v240, v249
	ds_bpermute_b32 v250, v240, v250
	ds_bpermute_b32 v251, v240, v251
	ds_bpermute_b32 v252, v240, v252
	ds_bpermute_b32 v253, v240, v253
	v_lshl_add_u64 v[238:239], v[140:141], 0, v[242:243]
	s_waitcnt lgkmcnt(4)
; __device__ __forceinline__ u32x4 pack8_bf16(f32x4 a, f32x4 b) { u32x4 w; w.x = cvt_pk_bf16(a[0], a[1]); w.y = cvt_pk_bf16(a[2], a[3]); w.z = cvt_pk_bf16(b[0], b[1]); w.w = cvt_pk_bf16(b[2], b[3]); return w; }
; #define PG8_BAR __builtin_amdgcn_s_barrier()
; #define ACT(t) (KBASE(t) <= qlo + QBLK - 1 && KBASE(t) + KVBLK - 1 >= qlo - W + 1)
;     __device__ __forceinline__ void operator()(const f32x4 (&acc)[2][2][4][2], const Unit& u, int wr, int wc, int fr, int fq) const {
;         const int g = u.pn / nNper, pnl = u.pn - g * nNper, pml = u.pm & 63;
;         bf16_t* base = O + (size_t)g * gstride;
;         const int row0 = pml * BM + wr * 64 + fr, col0 = pnl * BM + wc * 32 + 8 * fq;
; #pragma unroll
;         for (int ai = 0; ai < 2; ++ai)
; #pragma unroll
;             for (int m = 0; m < 4; ++m) { bf16_t* rowp = base + (size_t)(row0 + ai * HALF + m * 16) * ldc + col0;
; #pragma unroll
;                 for (int bj = 0; bj < 2; ++bj) { f32x4 v0 = acc[ai][bj][m][0], v1 = acc[ai][bj][m][1];
;                     if (ACT == 1) {
; #pragma unroll
;                         for (int j = 0; j < 4; ++j) { float a = fmaxf(v0[j], 0.f), b = fmaxf(v1[j], 0.f); v0[j] = a * a; v1[j] = b * b; } }
;                     *(u32x4*)(rowp + bj * HALF) = pack8_bf16(v0, v1); } }
; template <class Epi, class Sched, bool ALIGN_EPI = false, bool SP2 = false>
; __device__ __forceinline__ void gemm_phase(PG8_LAS unsigned char* lds, const Gemm g, const Sched& S, const Epi& E) {
;     ...
;         if (!has_next) break;
; #pragma unroll
;         for (int a = 0; a < 2; ++a)
; #pragma unroll
;             for (int b = 0; b < 2; ++b)
; #pragma unroll
;                 for (int m = 0; m < 4; ++m)
; #pragma unroll
;                     for (int n = 0; n < 2; ++n) acc[a][b][m][n] = (f32x4){0.f, 0.f, 0.f, 0.f};
;         cur = nxt; cA = nA; cB = nB; ++ui;
;         if constexpr (ALIGN_EPI) { if (wr == 1) PG8_BAR; }
	global_store_dwordx4 v[140:141], v[246:249], off
	s_waitcnt lgkmcnt(0)
	global_store_dwordx4 v[238:239], v[250:253], off
	v_lshl_add_u64 v[140:141], v[140:141], 0, s[34:35]
	v_max_f32_e32 v12, 0, v12
	v_max_f32_e32 v13, 0, v13
	v_max_f32_e32 v14, 0, v14
	v_max_f32_e32 v15, 0, v15
	v_max_f32_e32 v8, 0, v8
	v_max_f32_e32 v9, 0, v9
	v_max_f32_e32 v10, 0, v10
	v_max_f32_e32 v11, 0, v11
	v_max_f32_e32 v4, 0, v4
	v_max_f32_e32 v5, 0, v5
	v_max_f32_e32 v6, 0, v6
	v_max_f32_e32 v7, 0, v7
	v_max_f32_e32 v0, 0, v0
	v_max_f32_e32 v1, 0, v1
	v_max_f32_e32 v2, 0, v2
	v_max_f32_e32 v3, 0, v3
	v_mul_f32_e32 v12, v12, v12
	v_mul_f32_e32 v13, v13, v13
	v_mul_f32_e32 v14, v14, v14
	v_mul_f32_e32 v15, v15, v15
	v_mul_f32_e32 v8, v8, v8
	v_mul_f32_e32 v9, v9, v9
	v_mul_f32_e32 v10, v10, v10
	v_mul_f32_e32 v11, v11, v11
	v_mul_f32_e32 v4, v4, v4
	v_mul_f32_e32 v5, v5, v5
	v_mul_f32_e32 v6, v6, v6
	v_mul_f32_e32 v7, v7, v7
	v_mul_f32_e32 v0, v0, v0
	v_mul_f32_e32 v1, v1, v1
	v_mul_f32_e32 v2, v2, v2
	v_mul_f32_e32 v3, v3, v3
	v_cvt_pk_bf16_f32 v12, v12, v13
	v_cvt_pk_bf16_f32 v13, v14, v15
	v_cvt_pk_bf16_f32 v14, v8, v9
	v_cvt_pk_bf16_f32 v15, v10, v11
	v_cvt_pk_bf16_f32 v4, v4, v5
	v_cvt_pk_bf16_f32 v5, v6, v7
	v_cvt_pk_bf16_f32 v6, v0, v1
	v_cvt_pk_bf16_f32 v7, v2, v3
	v_mov_b32_dpp v246, v4 row_ror:8 row_mask:0xf bank_mask:0xf
	v_mov_b32_dpp v247, v5 row_ror:8 row_mask:0xf bank_mask:0xf
	v_mov_b32_dpp v248, v6 row_ror:8 row_mask:0xf bank_mask:0xf
	v_mov_b32_dpp v249, v7 row_ror:8 row_mask:0xf bank_mask:0xf
	v_mov_b32_dpp v250, v12 row_ror:8 row_mask:0xf bank_mask:0xf
	v_mov_b32_dpp v251, v13 row_ror:8 row_mask:0xf bank_mask:0xf
	v_mov_b32_dpp v252, v14 row_ror:8 row_mask:0xf bank_mask:0xf
	v_mov_b32_dpp v253, v15 row_ror:8 row_mask:0xf bank_mask:0xf
	v_cndmask_b32_e32 v246, v12, v246, vcc
	v_cndmask_b32_e32 v247, v13, v247, vcc
	v_cndmask_b32_e32 v248, v14, v248, vcc
	v_cndmask_b32_e32 v249, v15, v249, vcc
	v_cndmask_b32_e32 v250, v250, v4, vcc
	v_cndmask_b32_e32 v251, v251, v5, vcc
	v_cndmask_b32_e32 v252, v252, v6, vcc
	v_cndmask_b32_e32 v253, v253, v7, vcc
	ds_bpermute_b32 v246, v240, v246
	ds_bpermute_b32 v247, v240, v247
	ds_bpermute_b32 v248, v240, v248
	ds_bpermute_b32 v249, v240, v249
	ds_bpermute_b32 v250, v240, v250
	ds_bpermute_b32 v251, v240, v251
	ds_bpermute_b32 v252, v240, v252
	ds_bpermute_b32 v253, v240, v253
	v_lshl_add_u64 v[238:239], v[140:141], 0, v[242:243]
	s_waitcnt lgkmcnt(4)
	global_store_dwordx4 v[140:141], v[246:249], off
	s_waitcnt lgkmcnt(0)
	global_store_dwordx4 v[238:239], v[250:253], off
	s_andn2_b64 vcc, exec, s[40:41]
	s_mov_b64 s[34:35], -1
	s_cbranch_vccnz .LBB0_51
	s_andn2_b64 vcc, exec, s[30:31]
	s_cbranch_vccnz .LBB0_50
	s_barrier
	s_branch .LBB0_50

; #define PG8_WAIT_V(n) asm volatile("s_waitcnt vmcnt(" #n ")" ::: "memory")
; #define PG8_BAR __builtin_amdgcn_s_barrier()
; template <class Epi, class Sched, bool ALIGN_EPI = false, bool SP2 = false>
; __device__ __forceinline__ void gemm_phase(PG8_LAS unsigned char* lds, const Gemm g, const Sched& S, const Epi& E) {
;     int tid_l_ = threadIdx.x; asm volatile("" : "+v"(tid_l_)); const int tid = tid_l_, wid = __builtin_amdgcn_readfirstlane(tid >> 6), lane = tid & 63, wr = wid >> 2, wc = wid & 3, fr = lane & 15, fq = lane >> 4;
;     const int K = g.K, nt = K / BK;
;     unsigned voffA[2], voffB[2];
; #pragma unroll
;     for (int i = 0; i < 2; ++i) { int R, C; stage_rc(tid * 16 + i * 8192, R, C); const int Rb = Epi::PERM ? ((R & ~31) + perm32(R & 31)) : R;
;         voffA[i] = (unsigned)(R * K + C) * 2u; voffB[i] = (unsigned)(Rb * K + C) * 2u; }
;     const size_t kstep = (size_t)(BK * 2);
;     const size_t hstep = (size_t)HALF * K * 2;
;     const size_t tstep = 2 * hstep;
;     const unsigned ldsw = (unsigned)wid * 1024u;
;     const int aoff = lds_byte(wr * 64 + fr, fq * 8), boff = lds_byte(wc * 32 + fr, fq * 8);
;     ...
;     Unit cur, nxt; int ui = 0;
;     if (!S.next(0, cur)) return;
;     f32x4 acc[2][2][4][2];
; #pragma unroll
;     for (int a = 0; a < 2; ++a)
; #pragma unroll
;         for (int b = 0; b < 2; ++b)
; #pragma unroll
;             for (int m = 0; m < 4; ++m)
; #pragma unroll
;                 for (int n = 0; n < 2; ++n) acc[a][b][m][n] = (f32x4){0.f, 0.f, 0.f, 0.f};
;     bf16x8 At[4][2], B0[2][2], B1[2][2];
;     const char* cA = (const char*)g.A + (size_t)cur.pm * tstep; const char* cB = (const char*)g.Bt + (size_t)cur.pn * tstep;
;     S.a_ready(cur);
;     if constexpr (SP2) {
;         PG8_STAGE(PG8_SB(0, 0), cB, voffB); PG8_STAGE(PG8_SB(0, 1), cB + hstep, voffB); PG8_STAGE(PG8_SA(0, 0), cA, voffA); PG8_STAGE(PG8_SA(0, 1), cA + hstep, voffA);
;         if (wr == 1) PG8_BAR;
;         PG8_WAIT_V(2); PG8_BAR;
;         PG8_STAGE(PG8_SB(1, 0), cB + kstep, voffB); PG8_STAGE(PG8_SA(1, 0), cA + kstep, voffA); PG8_STAGE(PG8_SB(1, 1), cB + hstep + kstep, voffB);
;         PG8_WAIT_V(6); PG8_BAR;
;     } else {
;         PG8_STAGE(PG8_SB(0, 0), cB, voffB); PG8_STAGE(PG8_SA(0, 0), cA, voffA); PG8_STAGE(PG8_SB(0, 1), cB + hstep, voffB); PG8_STAGE(PG8_SA(0, 1), cA + hstep, voffA);
;         if (wr == 1) PG8_BAR;
;         PG8_WAIT_V(4); PG8_BAR;
.LBB0_313:
	s_andn2_b64 vcc, exec, s[8:9]
	s_cbranch_vccnz .LBB0_334
	v_readlane_b32 s8, v255, 9
	s_waitcnt vmcnt(0)
	v_mov_b32_e32 v6, v208
	v_readlane_b32 s9, v255, 10
	s_andn2_b64 vcc, exec, s[8:9]
	v_readfirstlane_b32 s12, v6
	s_cbranch_vccnz .LBB0_334
	v_lshlrev_b32_e32 v3, 4, v6
	v_add_u32_e32 v1, 0x2000, v3
	v_ashrrev_i32_e32 v0, 31, v1
	v_lshrrev_b32_e32 v0, 22, v0
	v_add_u32_e32 v0, v1, v0
	v_ashrrev_i32_e32 v0, 10, v0
	v_mul_i32_i24_e32 v2, 0x400, v0
	v_sub_u32_e32 v1, v1, v2
	v_lshrrev_b32_e32 v2, 4, v1
	v_bitop3_b32 v2, v2, v1, 32 bitop3:0x6c
	v_ashrrev_i32_e32 v1, 31, v2
	v_lshrrev_b32_e32 v1, 26, v1
	v_add_u32_e32 v4, v2, v1
	v_lshlrev_b32_e32 v5, 3, v0
	v_ashrrev_i32_e32 v1, 6, v4
	v_and_b32_e32 v5, -16, v5
	v_add_u32_e32 v5, v1, v5
	v_and_b32_e32 v7, 3, v1
	s_mov_b32 s7, 0xfffe0
	v_lshrrev_b32_e32 v8, 2, v5
	v_lshlrev_b32_e32 v9, 1, v5
	v_and_b32_e32 v4, 0xc0, v4
	v_and_b32_e32 v252, s7, v5
	v_lshl_or_b32 v7, v252, 1, v7
	v_and_b32_e32 v8, 4, v8
	v_and_b32_e32 v9, 24, v9
	v_sub_u32_e32 v2, v2, v4
	v_mov_b32_e32 v12, 1
	v_or3_b32 v7, v7, v8, v9
	v_lshlrev_b32_e32 v8, 5, v0
	v_ashrrev_i16_sdwa v2, v12, sext(v2) dst_sel:DWORD dst_unused:UNUSED_PAD src0_sel:DWORD src1_sel:BYTE_0
	v_and_b32_e32 v8, 32, v8
	v_bfe_i32 v2, v2, 0, 16
	v_add_lshl_u32 v4, v8, v2, 1
	v_lshl_add_u32 v130, v7, 12, v4
	v_lshl_add_u32 v132, v5, 12, v4
	v_bfe_i32 v4, v6, 27, 1
	v_lshrrev_b32_e32 v4, 22, v4
	v_add_u32_e32 v4, v3, v4
	v_and_b32_e32 v4, 0xfffffc00, v4
	v_sub_u32_e32 v3, v3, v4
	v_lshrrev_b32_e32 v4, 4, v3
	v_bitop3_b32 v5, v4, v3, 32 bitop3:0x6c
	v_ashrrev_i32_e32 v4, 31, v6
	v_lshrrev_b32_e32 v4, 26, v4
	v_ashrrev_i32_e32 v3, 31, v5
	v_add_u32_e32 v4, v6, v4
	v_lshrrev_b32_e32 v3, 26, v3
	v_ashrrev_i32_e32 v4, 6, v4
	v_add_u32_e32 v7, v5, v3
	v_lshlrev_b32_e32 v8, 3, v4
	v_ashrrev_i32_e32 v3, 6, v7
	v_and_b32_e32 v8, -16, v8
	v_add_u32_e32 v8, v3, v8
	v_and_b32_e32 v9, 3, v3
	s_ashr_i32 s13, s12, 6
	v_and_b32_e32 v252, s7, v8
	v_lshl_or_b32 v9, v252, 1, v9
	v_readlane_b32 s6, v255, 2
	s_ashr_i32 s18, s12, 8
	s_lshl_b32 s2, s13, 10
	v_readlane_b32 s7, v255, 3
	s_and_b64 s[8:9], s[6:7], exec
	s_cselect_b32 s8, s91, s17
	s_add_i32 s8, s8, s74
	s_ashr_i32 s9, s8, 31
	s_lshr_b32 s9, s9, 27
	s_add_i32 s9, s8, s9
	s_ashr_i32 s10, s9, 5
	s_lshl_b32 s10, s10, 2
	s_mov_b32 s6, s17
	s_sub_i32 s17, 64, s10
	s_min_i32 s17, s17, 4
	v_and_b32_e32 v7, 0xc0, v7
	s_abs_i32 s19, s17
	v_sub_u32_e32 v5, v5, v7
	v_cvt_f32_u32_e32 v7, s19
	s_sub_i32 s27, 0, s19
	s_andn2_b32 s9, s9, 31
	s_sub_i32 s8, s8, s9
	v_rcp_iflag_f32_e32 v7, v7
	s_abs_i32 s26, s8
	s_xor_b32 s9, s8, s17
	s_ashr_i32 s9, s9, 31
	v_mul_f32_e32 v7, 0x4f7ffffe, v7
	v_cvt_u32_f32_e32 v7, v7
	v_lshrrev_b32_e32 v10, 2, v8
	v_lshlrev_b32_e32 v11, 1, v8
	v_and_b32_e32 v10, 4, v10
	v_readfirstlane_b32 s28, v7
	s_mul_i32 s27, s27, s28
	s_mul_hi_u32 s27, s28, s27
	s_add_i32 s28, s28, s27
	s_mul_hi_u32 s27, s26, s28
	s_mul_i32 s28, s27, s19
	s_sub_i32 s26, s26, s28
	s_add_i32 s28, s27, 1
	s_sub_i32 s29, s26, s19
	s_cmp_ge_u32 s26, s19
	s_cselect_b32 s27, s28, s27
	s_cselect_b32 s26, s29, s26
	s_add_i32 s28, s27, 1
	s_cmp_ge_u32 s26, s19
	s_cselect_b32 s19, s28, s27
	s_xor_b32 s19, s19, s9
	s_sub_i32 s9, s19, s9
	s_mul_i32 s17, s9, s17
	s_sub_i32 s8, s8, s17
	s_add_i32 s8, s8, s90
	s_add_i32 s44, s8, s10
	s_add_i32 s42, s9, s94
	v_and_b32_e32 v11, 24, v11
	s_ashr_i32 s45, s44, 31
	s_ashr_i32 s43, s42, 31
	v_or3_b32 v9, v9, v10, v11
	v_lshlrev_b32_e32 v10, 5, v4
	v_ashrrev_i16_sdwa v5, v12, sext(v5) dst_sel:DWORD dst_unused:UNUSED_PAD src0_sel:DWORD src1_sel:BYTE_0
	s_lshl_b64 s[8:9], s[44:45], 20
	s_lshl_b64 s[26:27], s[42:43], 20
	v_and_b32_e32 v10, 32, v10
	v_bfe_i32 v5, v5, 0, 16
	s_add_u32 s52, s0, s26
	v_add_lshl_u32 v10, v10, v5, 1
	s_addc_u32 s53, s1, s27
	s_add_i32 s10, s2, 0
	v_lshl_add_u32 v128, v9, 12, v10
	s_add_i32 m0, s10, 0x10000
	v_lshl_add_u32 v134, v8, 12, v10
	global_load_lds_dwordx4 v128, s[52:53]
	s_add_i32 m0, s10, 0x12000
	s_add_u32 s26, s52, 0x20000
	global_load_lds_dwordx4 v130, s[52:53]
	s_addc_u32 s27, s53, 0
	s_add_i32 m0, s10, 0x14000
	s_nop 0
	global_load_lds_dwordx4 v128, s[26:27]
	s_add_i32 m0, s10, 0x16000
	s_add_u32 s50, s84, s8
	s_addc_u32 s51, s85, s9
	s_add_i32 s17, s10, 0x2000
	global_load_lds_dwordx4 v130, s[26:27]
	s_mov_b32 m0, s10
	s_add_u32 s8, s50, 0x80000
	global_load_lds_dwordx4 v134, s[50:51]
	s_mov_b32 m0, s17
	s_addc_u32 s9, s51, 0
	s_add_i32 s26, s10, 0x4000
	global_load_lds_dwordx4 v132, s[50:51]
	s_mov_b32 m0, s26
	s_add_i32 s27, s10, 0x6000
	global_load_lds_dwordx4 v134, s[8:9]
	s_mov_b32 m0, s27
	s_cmp_eq_u32 s18, 1
	global_load_lds_dwordx4 v132, s[8:9]
	s_cselect_b64 s[8:9], -1, 0
	s_cmp_lg_u32 s18, 1
	s_cbranch_scc1 .LBB0_317
	s_barrier
.LBB0_317:
	v_lshrrev_b32_e32 v16, 1, v6
	v_and_b32_e32 v16, 24, v16
	s_lshl_b32 s13, s13, 5
	v_and_b32_e32 v7, 15, v6
	v_lshlrev_b32_e32 v17, 1, v16
	v_lshlrev_b32_e32 v6, 2, v6
	s_and_b32 s30, s13, 0x60
	v_lshl_add_u64 v[8:9], s[52:53], 0, v[128:129]
	v_mov_b32_e32 v131, v129
	v_bfe_u32 v252, v208, 3, 3
	v_lshl_or_b32 v142, s18, 6, v252
	v_lshl_or_b32 v7, v7, 6, v17
	s_lshl_b32 s18, s18, 13
	v_and_b32_e32 v6, 32, v6
	s_lshl_b32 s13, s30, 7
	v_lshl_add_u64 v[10:11], s[52:53], 0, v[130:131]
	v_mov_b32_e32 v135, v129
	v_bitop3_b32 v17, v7, s18, v6 bitop3:0xde
	v_bitop3_b32 v143, v7, s13, v6 bitop3:0xde
	s_add_i32 m0, s10, 0x18000
	v_lshl_add_u64 v[6:7], v[8:9], 0, s[20:21]
	v_lshl_add_u64 v[12:13], s[50:51], 0, v[134:135]
	v_mov_b32_e32 v133, v129
	s_waitcnt vmcnt(2)
	s_barrier
	global_load_lds_dwordx4 v[6:7], off
	v_lshl_add_u64 v[6:7], v[10:11], 0, s[20:21]
	s_add_i32 m0, s10, 0x1a000
	s_add_i32 s28, s10, 0x8000
	s_add_i32 s29, s10, 0xa000
	v_lshl_add_u64 v[14:15], s[50:51], 0, v[132:133]
	global_load_lds_dwordx4 v[6:7], off
	v_lshl_add_u64 v[6:7], v[12:13], 0, s[20:21]
	s_mov_b32 m0, s28
	s_add_u32 s18, s52, 0x20080
	global_load_lds_dwordx4 v[6:7], off
	v_lshl_add_u64 v[6:7], v[14:15], 0, s[20:21]
	s_mov_b32 m0, s29
	s_addc_u32 s19, s53, 0
	global_load_lds_dwordx4 v[6:7], off
	s_add_i32 m0, s10, 0x1c000
	v_lshl_add_u64 v[6:7], s[18:19], 0, v[128:129]
	global_load_lds_dwordx4 v[6:7], off
	v_lshl_add_u64 v[6:7], s[18:19], 0, v[130:131]
	s_add_i32 m0, s10, 0x1e000
	s_cmpk_lt_u32 s12, 0x100
	global_load_lds_dwordx4 v[6:7], off
	v_lshlrev_b32_e32 v6, 15, v4
	v_and_b32_e32 v6, 0xffff0000, v6
	v_lshl_add_u32 v3, v3, 12, v6
	v_and_b32_e32 v4, 1, v4
	v_lshl_or_b32 v3, v4, 6, v3
	v_lshl_add_u32 v136, v5, 1, v3
	v_lshlrev_b32_e32 v3, 15, v0
	v_and_b32_e32 v3, 0xffff0000, v3
	s_waitcnt vmcnt(6)
	v_lshl_add_u32 v1, v1, 12, v3
	v_and_b32_e32 v0, 1, v0
	v_lshl_or_b32 v0, v0, 6, v1
	s_cselect_b64 s[12:13], -1, 0
	v_and_b32_e32 v252, 7, v208
	v_lshlrev_b32_e32 v252, 3, v252
	v_lshl_or_b32 v144, s30, 1, v252
	v_mov_b32_e32 v137, v129
	v_lshl_add_u32 v138, v2, 1, v0
	v_mov_b32_e32 v139, v129
	s_mov_b32 s33, 0
	v_add_u32_e32 v145, 0, v17
	s_barrier
	s_branch .LBB0_320

; #define PG8_STAGE(bufoff, gbase, voff) do { _Pragma("unroll") for (int _i = 0; _i < 2; ++_i) \
;         __builtin_amdgcn_global_load_lds((const unsigned*)((const char*)(gbase) + (voff)[_i]), (PG8_LAS unsigned*)(lds + (bufoff) + ldsw + _i * 8192), 16, 0, 0); } while (0)
; #define PG8_LDA(dst, b, h) do { _Pragma("unroll") for (int m = 0; m < 4; ++m) _Pragma("unroll") for (int k = 0; k < 2; ++k) dst[m][k] = *(const PG8_LAS bf16x8*)(lds + PG8_SA(b, h) + aoff + m * 2048 + k * 1024); } while (0)
; #define PG8_LDB(dst, b, h) do { _Pragma("unroll") for (int n = 0; n < 2; ++n) _Pragma("unroll") for (int k = 0; k < 2; ++k) dst[n][k] = *(const PG8_LAS bf16x8*)(lds + PG8_SB(b, h) + boff + n * 2048 + k * 1024); } while (0)
; #define PG8_MMA(ai, bj, At, Bt) do { __builtin_amdgcn_s_setprio(1); _Pragma("unroll") for (int m = 0; m < 4; ++m) _Pragma("unroll") for (int n = 0; n < 2; ++n) _Pragma("unroll") for (int k = 0; k < 2; ++k) \
;         acc[ai][bj][m][n] = __builtin_amdgcn_mfma_f32_16x16x32_bf16(Bt[n][k], At[m][k], acc[ai][bj][m][n], 0, 0, 0); __builtin_amdgcn_s_setprio(0); } while (0)
; #define PG8_WAIT_V(n) asm volatile("s_waitcnt vmcnt(" #n ")" ::: "memory")
; #define PG8_WAIT_L(n) asm volatile("s_waitcnt lgkmcnt(" #n ")" ::: "memory")
; #define PG8_BAR __builtin_amdgcn_s_barrier()
; #define PG8_SCHED __builtin_amdgcn_sched_barrier(0)
; template <class Epi, class Sched, bool ALIGN_EPI = false, bool SP2 = false>
; __device__ __forceinline__ void gemm_phase(PG8_LAS unsigned char* lds, const Gemm g, const Sched& S, const Epi& E) {
;     ...
;             PG8_LDB(B0, 0, 0); PG8_LDB(B1, 0, 1); PG8_SCHED; PG8_LDA(At, 0, 0); PG8_STAGE(PG8_SA(1, 1), a1 + hstep, voffA);
;             PG8_WAIT_V(8); PG8_WAIT_L(0); PG8_BAR; PG8_MMA(0, 0, At, B0); PG8_MMA(0, 1, At, B1); PG8_BAR; PG8_SCHED;
;             PG8_LDA(At, 0, 1); PG8_STAGE(PG8_SB(0, 0), b2, voffB); PG8_STAGE(PG8_SB(0, 1), b2 + hstep, voffB); PG8_STAGE(PG8_SA(0, 0), a2, voffA);
;             PG8_WAIT_V(8); PG8_WAIT_L(0); PG8_BAR; PG8_MMA(1, 0, At, B0); PG8_MMA(1, 1, At, B1); PG8_BAR; PG8_SCHED;
.LBB0_327:
	s_add_u32 s52, s50, 0xfff80080
	s_addc_u32 s53, s51, -1
	s_add_i32 s56, 0, 0x10000
	s_cmp_eq_u32 s45, 28
	s_cselect_b32 s55, s19, s53
	s_cselect_b32 s54, s34, s52
	v_add_u32_e32 v140, s56, v143
	s_cselect_b32 s53, s31, s43
	s_cselect_b32 s52, s35, s37
	s_add_i32 s58, 0, 0x14000
	ds_read_b128 v[146:149], v140
	ds_read_b128 v[150:153], v140 offset:1024
	ds_read_b128 v[154:157], v140 offset:2048
	ds_read_b128 v[158:161], v140 offset:3072
	v_add_u32_e32 v140, s58, v143
	ds_read_b128 v[162:165], v140
	ds_read_b128 v[166:169], v140 offset:1024
	ds_read_b128 v[170:173], v140 offset:2048
	ds_read_b128 v[174:177], v140 offset:3072
	v_lshl_add_u64 v[140:141], s[50:51], 0, v[136:137]
	s_add_i32 m0, s10, 0xc000
	ds_read_b128 v[178:181], v145
	ds_read_b128 v[182:185], v145 offset:1024
	ds_read_b128 v[186:189], v145 offset:2048
	ds_read_b128 v[190:193], v145 offset:3072
	ds_read_b128 v[220:223], v145 offset:4096
	ds_read_b128 v[224:227], v145 offset:5120
	ds_read_b128 v[228:231], v145 offset:6144
	ds_read_b128 v[232:235], v145 offset:7168
	global_load_lds_dwordx4 v[140:141], off
	v_lshl_add_u64 v[140:141], s[50:51], 0, v[138:139]
	s_add_i32 m0, s10, 0xe000
	s_nop 0
	global_load_lds_dwordx4 v[140:141], off
	s_waitcnt vmcnt(8)
	s_waitcnt lgkmcnt(0)
	s_barrier
	s_setprio 1
	s_waitcnt lgkmcnt(0)
	v_mfma_f32_16x16x32_bf16 v[124:127], v[146:149], v[178:181], v[124:127]
	v_mfma_f32_16x16x32_bf16 v[120:123], v[154:157], v[178:181], v[120:123]
	v_mfma_f32_16x16x32_bf16 v[116:119], v[146:149], v[186:189], v[116:119]
	v_mfma_f32_16x16x32_bf16 v[108:111], v[154:157], v[186:189], v[108:111]
	v_mfma_f32_16x16x32_bf16 v[100:103], v[146:149], v[220:223], v[100:103]
	v_mfma_f32_16x16x32_bf16 v[92:95], v[154:157], v[220:223], v[92:95]
	v_mfma_f32_16x16x32_bf16 v[84:87], v[146:149], v[228:231], v[84:87]
	v_mfma_f32_16x16x32_bf16 v[76:79], v[154:157], v[228:231], v[76:79]
	v_mfma_f32_16x16x32_bf16 v[124:127], v[150:153], v[182:185], v[124:127]
	v_mfma_f32_16x16x32_bf16 v[120:123], v[158:161], v[182:185], v[120:123]
	v_mfma_f32_16x16x32_bf16 v[116:119], v[150:153], v[190:193], v[116:119]
	v_mfma_f32_16x16x32_bf16 v[108:111], v[158:161], v[190:193], v[108:111]
	v_mfma_f32_16x16x32_bf16 v[100:103], v[150:153], v[224:227], v[100:103]
	v_mfma_f32_16x16x32_bf16 v[92:95], v[158:161], v[224:227], v[92:95]
	v_mfma_f32_16x16x32_bf16 v[84:87], v[150:153], v[232:235], v[84:87]
	v_mfma_f32_16x16x32_bf16 v[76:79], v[158:161], v[232:235], v[76:79]
	s_setprio 0
	s_setprio 1
	v_mfma_f32_16x16x32_bf16 v[112:115], v[162:165], v[178:181], v[112:115]
	v_mfma_f32_16x16x32_bf16 v[104:107], v[170:173], v[178:181], v[104:107]
	v_mfma_f32_16x16x32_bf16 v[96:99], v[162:165], v[186:189], v[96:99]
	v_mfma_f32_16x16x32_bf16 v[88:91], v[170:173], v[186:189], v[88:91]
	v_mfma_f32_16x16x32_bf16 v[80:83], v[162:165], v[220:223], v[80:83]
	v_mfma_f32_16x16x32_bf16 v[72:75], v[170:173], v[220:223], v[72:75]
	v_mfma_f32_16x16x32_bf16 v[68:71], v[162:165], v[228:231], v[68:71]
	v_mfma_f32_16x16x32_bf16 v[64:67], v[170:173], v[228:231], v[64:67]
	v_mfma_f32_16x16x32_bf16 v[112:115], v[166:169], v[182:185], v[112:115]
	v_mfma_f32_16x16x32_bf16 v[104:107], v[174:177], v[182:185], v[104:107]
	v_mfma_f32_16x16x32_bf16 v[96:99], v[166:169], v[190:193], v[96:99]
	v_mfma_f32_16x16x32_bf16 v[88:91], v[174:177], v[190:193], v[88:91]
	v_mfma_f32_16x16x32_bf16 v[80:83], v[166:169], v[224:227], v[80:83]
	v_mfma_f32_16x16x32_bf16 v[72:75], v[174:177], v[224:227], v[72:75]
	v_mfma_f32_16x16x32_bf16 v[68:71], v[166:169], v[232:235], v[68:71]
	v_mfma_f32_16x16x32_bf16 v[64:67], v[174:177], v[232:235], v[64:67]
	s_setprio 0
	s_barrier
	s_add_i32 s56, s56, s2
	v_lshl_add_u64 v[140:141], s[52:53], 0, v[128:129]
	s_mov_b32 m0, s56
	ds_read_b128 v[178:181], v145 offset:16384
	ds_read_b128 v[182:185], v145 offset:17408
	ds_read_b128 v[186:189], v145 offset:18432
	ds_read_b128 v[190:193], v145 offset:19456
	ds_read_b128 v[220:223], v145 offset:20480
	ds_read_b128 v[224:227], v145 offset:21504
	ds_read_b128 v[228:231], v145 offset:22528
	ds_read_b128 v[232:235], v145 offset:23552
	global_load_lds_dwordx4 v[140:141], off
	s_add_i32 m0, s56, 0x2000
	s_add_u32 s56, s52, 0x20000
	v_lshl_add_u64 v[206:207], s[52:53], 0, v[130:131]
	s_addc_u32 s57, s53, 0
	s_add_i32 s58, s58, s2
	global_load_lds_dwordx4 v[206:207], off
	v_lshl_add_u64 v[214:215], s[56:57], 0, v[128:129]
	s_mov_b32 m0, s58
	v_lshl_add_u64 v[216:217], s[54:55], 0, v[132:133]
	global_load_lds_dwordx4 v[214:215], off
	v_lshl_add_u64 v[214:215], s[56:57], 0, v[130:131]
	s_add_i32 m0, s58, 0x2000
	s_nop 0
	global_load_lds_dwordx4 v[214:215], off
	v_lshl_add_u64 v[214:215], s[54:55], 0, v[134:135]
	s_mov_b32 m0, s10
	s_nop 0
	global_load_lds_dwordx4 v[214:215], off
	s_mov_b32 m0, s17
	s_nop 0
	global_load_lds_dwordx4 v[216:217], off
	s_waitcnt vmcnt(8)
	s_waitcnt lgkmcnt(0)
	s_barrier
; #define PG8_STAGE(bufoff, gbase, voff) do { _Pragma("unroll") for (int _i = 0; _i < 2; ++_i) \
;         __builtin_amdgcn_global_load_lds((const unsigned*)((const char*)(gbase) + (voff)[_i]), (PG8_LAS unsigned*)(lds + (bufoff) + ldsw + _i * 8192), 16, 0, 0); } while (0)
; #define PG8_LDA(dst, b, h) do { _Pragma("unroll") for (int m = 0; m < 4; ++m) _Pragma("unroll") for (int k = 0; k < 2; ++k) dst[m][k] = *(const PG8_LAS bf16x8*)(lds + PG8_SA(b, h) + aoff + m * 2048 + k * 1024); } while (0)
; #define PG8_LDB(dst, b, h) do { _Pragma("unroll") for (int n = 0; n < 2; ++n) _Pragma("unroll") for (int k = 0; k < 2; ++k) dst[n][k] = *(const PG8_LAS bf16x8*)(lds + PG8_SB(b, h) + boff + n * 2048 + k * 1024); } while (0)
; #define PG8_MMA(ai, bj, At, Bt) do { __builtin_amdgcn_s_setprio(1); _Pragma("unroll") for (int m = 0; m < 4; ++m) _Pragma("unroll") for (int n = 0; n < 2; ++n) _Pragma("unroll") for (int k = 0; k < 2; ++k) \
;         acc[ai][bj][m][n] = __builtin_amdgcn_mfma_f32_16x16x32_bf16(Bt[n][k], At[m][k], acc[ai][bj][m][n], 0, 0, 0); __builtin_amdgcn_s_setprio(0); } while (0)
; #define PG8_WAIT_V(n) asm volatile("s_waitcnt vmcnt(" #n ")" ::: "memory")
; #define PG8_WAIT_L(n) asm volatile("s_waitcnt lgkmcnt(" #n ")" ::: "memory")
; #define PG8_BAR __builtin_amdgcn_s_barrier()
; #define PG8_SCHED __builtin_amdgcn_sched_barrier(0)
; template <class Epi, class Sched, bool ALIGN_EPI = false, bool SP2 = false>
; __device__ __forceinline__ void gemm_phase(PG8_LAS unsigned char* lds, const Gemm g, const Sched& S, const Epi& E) {
;     ...
;             PG8_WAIT_V(8); PG8_WAIT_L(0); PG8_BAR; PG8_MMA(1, 0, At, B0); PG8_MMA(1, 1, At, B1); PG8_BAR; PG8_SCHED;
;             PG8_LDB(B0, 1, 0); PG8_LDB(B1, 1, 1); PG8_SCHED; PG8_LDA(At, 1, 0); PG8_STAGE(PG8_SA(0, 1), a2 + hstep, voffA);
;             PG8_WAIT_V(8); PG8_WAIT_L(0); PG8_BAR; PG8_MMA(0, 0, At, B0); PG8_MMA(0, 1, At, B1); PG8_BAR; PG8_SCHED;
	s_setprio 1
	s_waitcnt lgkmcnt(0)
	v_mfma_f32_16x16x32_bf16 v[60:63], v[146:149], v[178:181], v[60:63]
	v_mfma_f32_16x16x32_bf16 v[56:59], v[154:157], v[178:181], v[56:59]
	v_mfma_f32_16x16x32_bf16 v[52:55], v[146:149], v[186:189], v[52:55]
	v_mfma_f32_16x16x32_bf16 v[44:47], v[154:157], v[186:189], v[44:47]
	v_mfma_f32_16x16x32_bf16 v[36:39], v[146:149], v[220:223], v[36:39]
	v_mfma_f32_16x16x32_bf16 v[28:31], v[154:157], v[220:223], v[28:31]
	v_mfma_f32_16x16x32_bf16 v[20:23], v[146:149], v[228:231], v[20:23]
	v_mfma_f32_16x16x32_bf16 v[12:15], v[154:157], v[228:231], v[12:15]
	v_mfma_f32_16x16x32_bf16 v[60:63], v[150:153], v[182:185], v[60:63]
	v_mfma_f32_16x16x32_bf16 v[56:59], v[158:161], v[182:185], v[56:59]
	v_mfma_f32_16x16x32_bf16 v[52:55], v[150:153], v[190:193], v[52:55]
	v_mfma_f32_16x16x32_bf16 v[44:47], v[158:161], v[190:193], v[44:47]
	v_mfma_f32_16x16x32_bf16 v[36:39], v[150:153], v[224:227], v[36:39]
	v_mfma_f32_16x16x32_bf16 v[28:31], v[158:161], v[224:227], v[28:31]
	v_mfma_f32_16x16x32_bf16 v[20:23], v[150:153], v[232:235], v[20:23]
	v_mfma_f32_16x16x32_bf16 v[12:15], v[158:161], v[232:235], v[12:15]
	s_setprio 0
	s_setprio 1
	v_mfma_f32_16x16x32_bf16 v[48:51], v[162:165], v[178:181], v[48:51]
	v_mfma_f32_16x16x32_bf16 v[40:43], v[170:173], v[178:181], v[40:43]
	v_mfma_f32_16x16x32_bf16 v[32:35], v[162:165], v[186:189], v[32:35]
	v_mfma_f32_16x16x32_bf16 v[24:27], v[170:173], v[186:189], v[24:27]
	v_mfma_f32_16x16x32_bf16 v[16:19], v[162:165], v[220:223], v[16:19]
	v_mfma_f32_16x16x32_bf16 v[8:11], v[170:173], v[220:223], v[8:11]
	v_mfma_f32_16x16x32_bf16 v[4:7], v[162:165], v[228:231], v[4:7]
	v_mfma_f32_16x16x32_bf16 v[0:3], v[170:173], v[228:231], v[0:3]
	v_mfma_f32_16x16x32_bf16 v[48:51], v[166:169], v[182:185], v[48:51]
	v_mfma_f32_16x16x32_bf16 v[40:43], v[174:177], v[182:185], v[40:43]
	v_mfma_f32_16x16x32_bf16 v[32:35], v[166:169], v[190:193], v[32:35]
	v_mfma_f32_16x16x32_bf16 v[24:27], v[174:177], v[190:193], v[24:27]
	v_mfma_f32_16x16x32_bf16 v[16:19], v[166:169], v[224:227], v[16:19]
	v_mfma_f32_16x16x32_bf16 v[8:11], v[174:177], v[224:227], v[8:11]
	v_mfma_f32_16x16x32_bf16 v[4:7], v[166:169], v[232:235], v[4:7]
	v_mfma_f32_16x16x32_bf16 v[0:3], v[174:177], v[232:235], v[0:3]
	s_setprio 0
	s_barrier
	s_add_i32 s56, 0, 0x18000
	s_add_i32 s57, 0, 0x1c000
	v_add_u32_e32 v158, s56, v143
	v_add_u32_e32 v174, s57, v143
	ds_read_b128 v[146:149], v158
	ds_read_b128 v[150:153], v158 offset:1024
	ds_read_b128 v[154:157], v158 offset:2048
	ds_read_b128 v[158:161], v158 offset:3072
	ds_read_b128 v[162:165], v174
	ds_read_b128 v[166:169], v174 offset:1024
	ds_read_b128 v[170:173], v174 offset:2048
	ds_read_b128 v[174:177], v174 offset:3072
	s_add_u32 s54, s54, 0x80000
	s_addc_u32 s55, s55, 0
	s_mov_b32 m0, s26
	v_lshl_add_u64 v[236:237], s[54:55], 0, v[134:135]
	ds_read_b128 v[178:181], v145 offset:32768
	ds_read_b128 v[182:185], v145 offset:33792
	ds_read_b128 v[186:189], v145 offset:34816
	ds_read_b128 v[190:193], v145 offset:35840
	ds_read_b128 v[220:223], v145 offset:36864
	ds_read_b128 v[224:227], v145 offset:37888
	ds_read_b128 v[228:231], v145 offset:38912
	ds_read_b128 v[232:235], v145 offset:39936
	global_load_lds_dwordx4 v[236:237], off
	v_lshl_add_u64 v[236:237], s[54:55], 0, v[132:133]
	s_mov_b32 m0, s27
	s_nop 0
	global_load_lds_dwordx4 v[236:237], off
	s_waitcnt vmcnt(8)
	s_waitcnt lgkmcnt(0)
	s_barrier
	s_setprio 1
	s_waitcnt lgkmcnt(0)
	v_mfma_f32_16x16x32_bf16 v[124:127], v[146:149], v[178:181], v[124:127]
	v_mfma_f32_16x16x32_bf16 v[120:123], v[154:157], v[178:181], v[120:123]
	v_mfma_f32_16x16x32_bf16 v[116:119], v[146:149], v[186:189], v[116:119]
	v_mfma_f32_16x16x32_bf16 v[108:111], v[154:157], v[186:189], v[108:111]
	v_mfma_f32_16x16x32_bf16 v[100:103], v[146:149], v[220:223], v[100:103]
	v_mfma_f32_16x16x32_bf16 v[92:95], v[154:157], v[220:223], v[92:95]
	v_mfma_f32_16x16x32_bf16 v[84:87], v[146:149], v[228:231], v[84:87]
	v_mfma_f32_16x16x32_bf16 v[76:79], v[154:157], v[228:231], v[76:79]
	v_mfma_f32_16x16x32_bf16 v[124:127], v[150:153], v[182:185], v[124:127]
	v_mfma_f32_16x16x32_bf16 v[120:123], v[158:161], v[182:185], v[120:123]
	v_mfma_f32_16x16x32_bf16 v[116:119], v[150:153], v[190:193], v[116:119]
	v_mfma_f32_16x16x32_bf16 v[108:111], v[158:161], v[190:193], v[108:111]
	v_mfma_f32_16x16x32_bf16 v[100:103], v[150:153], v[224:227], v[100:103]
	v_mfma_f32_16x16x32_bf16 v[92:95], v[158:161], v[224:227], v[92:95]
	v_mfma_f32_16x16x32_bf16 v[84:87], v[150:153], v[232:235], v[84:87]
	v_mfma_f32_16x16x32_bf16 v[76:79], v[158:161], v[232:235], v[76:79]
	s_setprio 0
	s_setprio 1
	v_mfma_f32_16x16x32_bf16 v[112:115], v[162:165], v[178:181], v[112:115]
	v_mfma_f32_16x16x32_bf16 v[104:107], v[170:173], v[178:181], v[104:107]
	v_mfma_f32_16x16x32_bf16 v[96:99], v[162:165], v[186:189], v[96:99]
	v_mfma_f32_16x16x32_bf16 v[88:91], v[170:173], v[186:189], v[88:91]
	v_mfma_f32_16x16x32_bf16 v[80:83], v[162:165], v[220:223], v[80:83]
	v_mfma_f32_16x16x32_bf16 v[72:75], v[170:173], v[220:223], v[72:75]
	v_mfma_f32_16x16x32_bf16 v[68:71], v[162:165], v[228:231], v[68:71]
	v_mfma_f32_16x16x32_bf16 v[64:67], v[170:173], v[228:231], v[64:67]
	v_mfma_f32_16x16x32_bf16 v[112:115], v[166:169], v[182:185], v[112:115]
	v_mfma_f32_16x16x32_bf16 v[104:107], v[174:177], v[182:185], v[104:107]
	v_mfma_f32_16x16x32_bf16 v[96:99], v[166:169], v[190:193], v[96:99]
	v_mfma_f32_16x16x32_bf16 v[88:91], v[174:177], v[190:193], v[88:91]
	v_mfma_f32_16x16x32_bf16 v[80:83], v[166:169], v[224:227], v[80:83]
	v_mfma_f32_16x16x32_bf16 v[72:75], v[174:177], v[224:227], v[72:75]
	v_mfma_f32_16x16x32_bf16 v[68:71], v[166:169], v[232:235], v[68:71]
	v_mfma_f32_16x16x32_bf16 v[64:67], v[174:177], v[232:235], v[64:67]
	s_setprio 0
	s_barrier
; __device__ __forceinline__ u32x4 pack8_bf16(f32x4 a, f32x4 b) { u32x4 w; w.x = cvt_pk_bf16(a[0], a[1]); w.y = cvt_pk_bf16(a[2], a[3]); w.z = cvt_pk_bf16(b[0], b[1]); w.w = cvt_pk_bf16(b[2], b[3]); return w; }
; #define PG8_STAGE(bufoff, gbase, voff) do { _Pragma("unroll") for (int _i = 0; _i < 2; ++_i) \
;         __builtin_amdgcn_global_load_lds((const unsigned*)((const char*)(gbase) + (voff)[_i]), (PG8_LAS unsigned*)(lds + (bufoff) + ldsw + _i * 8192), 16, 0, 0); } while (0)
; #define PG8_LDA(dst, b, h) do { _Pragma("unroll") for (int m = 0; m < 4; ++m) _Pragma("unroll") for (int k = 0; k < 2; ++k) dst[m][k] = *(const PG8_LAS bf16x8*)(lds + PG8_SA(b, h) + aoff + m * 2048 + k * 1024); } while (0)
; #define PG8_WAIT_V(n) asm volatile("s_waitcnt vmcnt(" #n ")" ::: "memory")
; #define PG8_WAIT_L(n) asm volatile("s_waitcnt lgkmcnt(" #n ")" ::: "memory")
; #define PG8_BAR __builtin_amdgcn_s_barrier()
; #define PG8_SCHED __builtin_amdgcn_sched_barrier(0)
;     __device__ __forceinline__ void operator()(const f32x4 (&acc)[2][2][4][2], const Unit& u, int wr, int wc, int fr, int fq) const {
;         const int g = u.pn / nNper, pnl = u.pn - g * nNper, pml = u.pm & 63;
;         bf16_t* base = O + (size_t)g * gstride;
;         const int row0 = pml * BM + wr * 64 + fr, col0 = pnl * BM + wc * 32 + 8 * fq;
; #pragma unroll
;         for (int ai = 0; ai < 2; ++ai)
; #pragma unroll
;             for (int m = 0; m < 4; ++m) { bf16_t* rowp = base + (size_t)(row0 + ai * HALF + m * 16) * ldc + col0;
; #pragma unroll
;                 for (int bj = 0; bj < 2; ++bj) { f32x4 v0 = acc[ai][bj][m][0], v1 = acc[ai][bj][m][1];
;                     if (ACT == 1) {
; #pragma unroll
;                         for (int j = 0; j < 4; ++j) { float a = fmaxf(v0[j], 0.f), b = fmaxf(v1[j], 0.f); v0[j] = a * a; v1[j] = b * b; } }
;                     *(u32x4*)(rowp + bj * HALF) = pack8_bf16(v0, v1); } }
; template <class Epi, class Sched, bool ALIGN_EPI = false, bool SP2 = false>
; __device__ __forceinline__ void gemm_phase(PG8_LAS unsigned char* lds, const Gemm g, const Sched& S, const Epi& E) {
;     ...
;             PG8_LDA(At, 1, 1); PG8_STAGE(PG8_SB(1, 0), b3, voffB); PG8_STAGE(PG8_SB(1, 1), b3 + hstep, voffB); PG8_STAGE(PG8_SA(1, 0), a3, voffA);
;             PG8_WAIT_V(8); PG8_WAIT_L(0); PG8_BAR; PG8_MMA(1, 0, At, B0); PG8_MMA(1, 1, At, B1); PG8_BAR; PG8_SCHED;
	s_add_i32 s54, s56, s2
	v_lshl_add_u64 v[140:141], v[140:141], 0, s[20:21]
	s_mov_b32 m0, s54
	ds_read_b128 v[178:181], v145 offset:49152
	ds_read_b128 v[182:185], v145 offset:50176
	ds_read_b128 v[186:189], v145 offset:51200
	ds_read_b128 v[190:193], v145 offset:52224
	ds_read_b128 v[220:223], v145 offset:53248
	ds_read_b128 v[224:227], v145 offset:54272
	ds_read_b128 v[228:231], v145 offset:55296
	ds_read_b128 v[232:235], v145 offset:56320
	global_load_lds_dwordx4 v[140:141], off
	s_add_i32 m0, s54, 0x2000
	s_add_u32 s52, s52, 0x20080
	v_lshl_add_u64 v[140:141], v[206:207], 0, s[20:21]
	s_addc_u32 s53, s53, 0
	s_add_i32 s54, s57, s2
	global_load_lds_dwordx4 v[140:141], off
	v_lshl_add_u64 v[140:141], s[52:53], 0, v[128:129]
	s_mov_b32 m0, s54
	s_nop 0
	global_load_lds_dwordx4 v[140:141], off
	v_lshl_add_u64 v[140:141], s[52:53], 0, v[130:131]
	s_add_i32 m0, s54, 0x2000
	s_nop 0
	global_load_lds_dwordx4 v[140:141], off
	v_lshl_add_u64 v[140:141], v[214:215], 0, s[20:21]
	s_mov_b32 m0, s28
	s_nop 0
	global_load_lds_dwordx4 v[140:141], off
	v_lshl_add_u64 v[140:141], v[216:217], 0, s[20:21]
	s_mov_b32 m0, s29
	s_nop 0
	global_load_lds_dwordx4 v[140:141], off
	s_waitcnt vmcnt(8)
	s_waitcnt lgkmcnt(0)
	s_barrier
	s_setprio 1
	s_waitcnt lgkmcnt(0)
	v_mfma_f32_16x16x32_bf16 v[60:63], v[146:149], v[178:181], v[60:63]
	v_mfma_f32_16x16x32_bf16 v[56:59], v[154:157], v[178:181], v[56:59]
	v_mfma_f32_16x16x32_bf16 v[52:55], v[146:149], v[186:189], v[52:55]
	v_mfma_f32_16x16x32_bf16 v[44:47], v[154:157], v[186:189], v[44:47]
	v_mfma_f32_16x16x32_bf16 v[36:39], v[146:149], v[220:223], v[36:39]
	v_mfma_f32_16x16x32_bf16 v[28:31], v[154:157], v[220:223], v[28:31]
	v_mfma_f32_16x16x32_bf16 v[20:23], v[146:149], v[228:231], v[20:23]
	v_mfma_f32_16x16x32_bf16 v[12:15], v[154:157], v[228:231], v[12:15]
	v_mfma_f32_16x16x32_bf16 v[60:63], v[150:153], v[182:185], v[60:63]
	v_mfma_f32_16x16x32_bf16 v[56:59], v[158:161], v[182:185], v[56:59]
	v_mfma_f32_16x16x32_bf16 v[52:55], v[150:153], v[190:193], v[52:55]
	v_mfma_f32_16x16x32_bf16 v[44:47], v[158:161], v[190:193], v[44:47]
	v_mfma_f32_16x16x32_bf16 v[36:39], v[150:153], v[224:227], v[36:39]
	v_mfma_f32_16x16x32_bf16 v[28:31], v[158:161], v[224:227], v[28:31]
	v_mfma_f32_16x16x32_bf16 v[20:23], v[150:153], v[232:235], v[20:23]
	v_mfma_f32_16x16x32_bf16 v[12:15], v[158:161], v[232:235], v[12:15]
	s_setprio 0
	s_setprio 1
	v_mfma_f32_16x16x32_bf16 v[48:51], v[162:165], v[178:181], v[48:51]
	v_mfma_f32_16x16x32_bf16 v[40:43], v[170:173], v[178:181], v[40:43]
	v_mfma_f32_16x16x32_bf16 v[32:35], v[162:165], v[186:189], v[32:35]
	v_mfma_f32_16x16x32_bf16 v[24:27], v[170:173], v[186:189], v[24:27]
	v_mfma_f32_16x16x32_bf16 v[16:19], v[162:165], v[220:223], v[16:19]
	v_mfma_f32_16x16x32_bf16 v[8:11], v[170:173], v[220:223], v[8:11]
	v_mfma_f32_16x16x32_bf16 v[4:7], v[162:165], v[228:231], v[4:7]
	v_mfma_f32_16x16x32_bf16 v[0:3], v[170:173], v[228:231], v[0:3]
	v_mfma_f32_16x16x32_bf16 v[48:51], v[166:169], v[182:185], v[48:51]
	v_mfma_f32_16x16x32_bf16 v[40:43], v[174:177], v[182:185], v[40:43]
	v_mfma_f32_16x16x32_bf16 v[32:35], v[166:169], v[190:193], v[32:35]
	v_mfma_f32_16x16x32_bf16 v[24:27], v[174:177], v[190:193], v[24:27]
	v_mfma_f32_16x16x32_bf16 v[16:19], v[166:169], v[224:227], v[16:19]
	v_mfma_f32_16x16x32_bf16 v[8:11], v[174:177], v[224:227], v[8:11]
	v_mfma_f32_16x16x32_bf16 v[4:7], v[166:169], v[232:235], v[4:7]
	v_mfma_f32_16x16x32_bf16 v[0:3], v[174:177], v[232:235], v[0:3]
	s_setprio 0
	s_barrier
	s_add_i32 s45, s45, 2
	s_add_u32 s50, s50, 0x100
	s_addc_u32 s51, s51, 0
	s_add_u32 s37, s37, 0x100
	s_addc_u32 s43, s43, 0
	s_cmp_gt_u32 s45, 29
	s_cbranch_scc0 .LBB0_327
	s_and_b64 vcc, exec, s[12:13]
	s_cbranch_vccz .LBB0_330
	s_barrier
.LBB0_330:
	s_ashr_i32 s19, s42, 31
	s_lshr_b32 s19, s19, 29
	s_add_i32 s19, s42, s19
	s_ashr_i32 s34, s19, 3
	s_ashr_i32 s35, s34, 31
	s_lshl_b64 s[50:51], s[34:35], 26
	s_add_u32 s50, s86, s50
	s_addc_u32 s51, s87, s51
	s_lshl_b32 s19, s44, 8
	s_and_b32 s19, s19, 0x3f00
	v_add_u32_e32 v146, s19, v142
	s_lshl_b32 s19, s34, 11
	s_lshl_b32 s31, s42, 8
	s_sub_i32 s19, s31, s19
	v_or_b32_e32 v140, s19, v144
	v_ashrrev_i32_e32 v141, 31, v140
	v_ashrrev_i32_e32 v147, 31, v146
	v_lshl_add_u64 v[148:149], v[140:141], 1, s[50:51]
	v_lshlrev_b64 v[140:141], 12, v[146:147]
	v_lshl_add_u64 v[140:141], v[148:149], 0, v[140:141]
	s_mov_b64 s[34:35], 0x10000
	v_mov_b32_e32 v242, 0x8000
	v_mov_b32_e32 v243, 0
	v_and_b32_e32 v238, 8, v208
	v_cmp_ne_u32_e32 vcc, 0, v238
	v_and_b32_e32 v240, 63, v208
	v_lshrrev_b32_e32 v241, 3, v240
	v_and_b32_e32 v244, 3, v240
	v_lshl_add_u32 v241, v244, 4, v241
	v_and_b32_e32 v244, 4, v240
	v_lshl_add_u32 v241, v244, 1, v241
	v_lshlrev_b32_e32 v240, 2, v241
	v_cvt_pk_bf16_f32 v124, v124, v125
	v_cvt_pk_bf16_f32 v125, v126, v127
	v_cvt_pk_bf16_f32 v126, v120, v121
	v_cvt_pk_bf16_f32 v127, v122, v123
	v_cvt_pk_bf16_f32 v112, v112, v113
	v_cvt_pk_bf16_f32 v113, v114, v115
	v_cvt_pk_bf16_f32 v114, v104, v105
	v_cvt_pk_bf16_f32 v115, v106, v107
	v_mov_b32_dpp v246, v112 row_ror:8 row_mask:0xf bank_mask:0xf
	v_mov_b32_dpp v247, v113 row_ror:8 row_mask:0xf bank_mask:0xf
	v_mov_b32_dpp v248, v114 row_ror:8 row_mask:0xf bank_mask:0xf
	v_mov_b32_dpp v249, v115 row_ror:8 row_mask:0xf bank_mask:0xf
	v_mov_b32_dpp v250, v124 row_ror:8 row_mask:0xf bank_mask:0xf
	v_mov_b32_dpp v251, v125 row_ror:8 row_mask:0xf bank_mask:0xf
	v_mov_b32_dpp v252, v126 row_ror:8 row_mask:0xf bank_mask:0xf
	v_mov_b32_dpp v253, v127 row_ror:8 row_mask:0xf bank_mask:0xf
	v_cndmask_b32_e32 v246, v124, v246, vcc
	v_cndmask_b32_e32 v247, v125, v247, vcc
	v_cndmask_b32_e32 v248, v126, v248, vcc
	v_cndmask_b32_e32 v249, v127, v249, vcc
	v_cndmask_b32_e32 v250, v250, v112, vcc
	v_cndmask_b32_e32 v251, v251, v113, vcc
	v_cndmask_b32_e32 v252, v252, v114, vcc
	v_cndmask_b32_e32 v253, v253, v115, vcc
	ds_bpermute_b32 v246, v240, v246
	ds_bpermute_b32 v247, v240, v247
	ds_bpermute_b32 v248, v240, v248
	ds_bpermute_b32 v249, v240, v249
	ds_bpermute_b32 v250, v240, v250
	ds_bpermute_b32 v251, v240, v251
	ds_bpermute_b32 v252, v240, v252
	ds_bpermute_b32 v253, v240, v253
	v_lshl_add_u64 v[238:239], v[140:141], 0, v[242:243]
	s_waitcnt lgkmcnt(4)
; __device__ __forceinline__ u32x4 pack8_bf16(f32x4 a, f32x4 b) { u32x4 w; w.x = cvt_pk_bf16(a[0], a[1]); w.y = cvt_pk_bf16(a[2], a[3]); w.z = cvt_pk_bf16(b[0], b[1]); w.w = cvt_pk_bf16(b[2], b[3]); return w; }
; #define ACT(t) (KBASE(t) <= qlo + QBLK - 1 && KBASE(t) + KVBLK - 1 >= qlo - W + 1)
;     __device__ __forceinline__ void operator()(const f32x4 (&acc)[2][2][4][2], const Unit& u, int wr, int wc, int fr, int fq) const {
;         const int g = u.pn / nNper, pnl = u.pn - g * nNper, pml = u.pm & 63;
;         bf16_t* base = O + (size_t)g * gstride;
;         const int row0 = pml * BM + wr * 64 + fr, col0 = pnl * BM + wc * 32 + 8 * fq;
; #pragma unroll
;         for (int ai = 0; ai < 2; ++ai)
; #pragma unroll
;             for (int m = 0; m < 4; ++m) { bf16_t* rowp = base + (size_t)(row0 + ai * HALF + m * 16) * ldc + col0;
; #pragma unroll
;                 for (int bj = 0; bj < 2; ++bj) { f32x4 v0 = acc[ai][bj][m][0], v1 = acc[ai][bj][m][1];
;                     if (ACT == 1) {
; #pragma unroll
;                         for (int j = 0; j < 4; ++j) { float a = fmaxf(v0[j], 0.f), b = fmaxf(v1[j], 0.f); v0[j] = a * a; v1[j] = b * b; } }
;                     *(u32x4*)(rowp + bj * HALF) = pack8_bf16(v0, v1); } }
	global_store_dwordx4 v[140:141], v[246:249], off
	s_waitcnt lgkmcnt(0)
	global_store_dwordx4 v[238:239], v[250:253], off
	v_lshl_add_u64 v[140:141], v[140:141], 0, s[34:35]
	v_cvt_pk_bf16_f32 v116, v116, v117
	v_cvt_pk_bf16_f32 v117, v118, v119
	v_cvt_pk_bf16_f32 v118, v108, v109
	v_cvt_pk_bf16_f32 v119, v110, v111
	v_cvt_pk_bf16_f32 v96, v96, v97
	v_cvt_pk_bf16_f32 v97, v98, v99
	v_cvt_pk_bf16_f32 v98, v88, v89
	v_cvt_pk_bf16_f32 v99, v90, v91
	v_mov_b32_dpp v246, v96 row_ror:8 row_mask:0xf bank_mask:0xf
	v_mov_b32_dpp v247, v97 row_ror:8 row_mask:0xf bank_mask:0xf
	v_mov_b32_dpp v248, v98 row_ror:8 row_mask:0xf bank_mask:0xf
	v_mov_b32_dpp v249, v99 row_ror:8 row_mask:0xf bank_mask:0xf
	v_mov_b32_dpp v250, v116 row_ror:8 row_mask:0xf bank_mask:0xf
	v_mov_b32_dpp v251, v117 row_ror:8 row_mask:0xf bank_mask:0xf
	v_mov_b32_dpp v252, v118 row_ror:8 row_mask:0xf bank_mask:0xf
	v_mov_b32_dpp v253, v119 row_ror:8 row_mask:0xf bank_mask:0xf
	v_cndmask_b32_e32 v246, v116, v246, vcc
	v_cndmask_b32_e32 v247, v117, v247, vcc
	v_cndmask_b32_e32 v248, v118, v248, vcc
	v_cndmask_b32_e32 v249, v119, v249, vcc
	v_cndmask_b32_e32 v250, v250, v96, vcc
	v_cndmask_b32_e32 v251, v251, v97, vcc
	v_cndmask_b32_e32 v252, v252, v98, vcc
	v_cndmask_b32_e32 v253, v253, v99, vcc
	ds_bpermute_b32 v246, v240, v246
	ds_bpermute_b32 v247, v240, v247
	ds_bpermute_b32 v248, v240, v248
	ds_bpermute_b32 v249, v240, v249
	ds_bpermute_b32 v250, v240, v250
	ds_bpermute_b32 v251, v240, v251
	ds_bpermute_b32 v252, v240, v252
	ds_bpermute_b32 v253, v240, v253
	v_lshl_add_u64 v[238:239], v[140:141], 0, v[242:243]
	s_waitcnt lgkmcnt(4)
	global_store_dwordx4 v[140:141], v[246:249], off
	s_waitcnt lgkmcnt(0)
	global_store_dwordx4 v[238:239], v[250:253], off
	v_lshl_add_u64 v[140:141], v[140:141], 0, s[34:35]
	v_cvt_pk_bf16_f32 v100, v100, v101
	v_cvt_pk_bf16_f32 v101, v102, v103
	v_cvt_pk_bf16_f32 v102, v92, v93
	v_cvt_pk_bf16_f32 v103, v94, v95
	v_cvt_pk_bf16_f32 v80, v80, v81
	v_cvt_pk_bf16_f32 v81, v82, v83
	v_cvt_pk_bf16_f32 v82, v72, v73
	v_cvt_pk_bf16_f32 v83, v74, v75
	v_mov_b32_dpp v246, v80 row_ror:8 row_mask:0xf bank_mask:0xf
	v_mov_b32_dpp v247, v81 row_ror:8 row_mask:0xf bank_mask:0xf
	v_mov_b32_dpp v248, v82 row_ror:8 row_mask:0xf bank_mask:0xf
	v_mov_b32_dpp v249, v83 row_ror:8 row_mask:0xf bank_mask:0xf
	v_mov_b32_dpp v250, v100 row_ror:8 row_mask:0xf bank_mask:0xf
	v_mov_b32_dpp v251, v101 row_ror:8 row_mask:0xf bank_mask:0xf
	v_mov_b32_dpp v252, v102 row_ror:8 row_mask:0xf bank_mask:0xf
	v_mov_b32_dpp v253, v103 row_ror:8 row_mask:0xf bank_mask:0xf
	v_cndmask_b32_e32 v246, v100, v246, vcc
	v_cndmask_b32_e32 v247, v101, v247, vcc
	v_cndmask_b32_e32 v248, v102, v248, vcc
	v_cndmask_b32_e32 v249, v103, v249, vcc
	v_cndmask_b32_e32 v250, v250, v80, vcc
	v_cndmask_b32_e32 v251, v251, v81, vcc
	v_cndmask_b32_e32 v252, v252, v82, vcc
	v_cndmask_b32_e32 v253, v253, v83, vcc
	ds_bpermute_b32 v246, v240, v246
	ds_bpermute_b32 v247, v240, v247
	ds_bpermute_b32 v248, v240, v248
	ds_bpermute_b32 v249, v240, v249
	ds_bpermute_b32 v250, v240, v250
	ds_bpermute_b32 v251, v240, v251
	ds_bpermute_b32 v252, v240, v252
	ds_bpermute_b32 v253, v240, v253
	v_lshl_add_u64 v[238:239], v[140:141], 0, v[242:243]
	s_waitcnt lgkmcnt(4)
	global_store_dwordx4 v[140:141], v[246:249], off
	s_waitcnt lgkmcnt(0)
	global_store_dwordx4 v[238:239], v[250:253], off
	v_lshl_add_u64 v[140:141], v[140:141], 0, s[34:35]
	v_cvt_pk_bf16_f32 v84, v84, v85
	v_cvt_pk_bf16_f32 v85, v86, v87
	v_cvt_pk_bf16_f32 v86, v76, v77
	v_cvt_pk_bf16_f32 v87, v78, v79
	v_cvt_pk_bf16_f32 v68, v68, v69
	v_cvt_pk_bf16_f32 v69, v70, v71
	v_cvt_pk_bf16_f32 v70, v64, v65
	v_cvt_pk_bf16_f32 v71, v66, v67
	v_mov_b32_dpp v246, v68 row_ror:8 row_mask:0xf bank_mask:0xf
	v_mov_b32_dpp v247, v69 row_ror:8 row_mask:0xf bank_mask:0xf
	v_mov_b32_dpp v248, v70 row_ror:8 row_mask:0xf bank_mask:0xf
	v_mov_b32_dpp v249, v71 row_ror:8 row_mask:0xf bank_mask:0xf
	v_mov_b32_dpp v250, v84 row_ror:8 row_mask:0xf bank_mask:0xf
	v_mov_b32_dpp v251, v85 row_ror:8 row_mask:0xf bank_mask:0xf
	v_mov_b32_dpp v252, v86 row_ror:8 row_mask:0xf bank_mask:0xf
	v_mov_b32_dpp v253, v87 row_ror:8 row_mask:0xf bank_mask:0xf
	v_cndmask_b32_e32 v246, v84, v246, vcc
	v_cndmask_b32_e32 v247, v85, v247, vcc
	v_cndmask_b32_e32 v248, v86, v248, vcc
	v_cndmask_b32_e32 v249, v87, v249, vcc
	v_cndmask_b32_e32 v250, v250, v68, vcc
	v_cndmask_b32_e32 v251, v251, v69, vcc
	v_cndmask_b32_e32 v252, v252, v70, vcc
	v_cndmask_b32_e32 v253, v253, v71, vcc
	ds_bpermute_b32 v246, v240, v246
	ds_bpermute_b32 v247, v240, v247
	ds_bpermute_b32 v248, v240, v248
	ds_bpermute_b32 v249, v240, v249
	ds_bpermute_b32 v250, v240, v250
	ds_bpermute_b32 v251, v240, v251
	ds_bpermute_b32 v252, v240, v252
	ds_bpermute_b32 v253, v240, v253
	v_lshl_add_u64 v[238:239], v[140:141], 0, v[242:243]
	s_waitcnt lgkmcnt(4)
	global_store_dwordx4 v[140:141], v[246:249], off
	s_waitcnt lgkmcnt(0)
; __device__ __forceinline__ u32x4 pack8_bf16(f32x4 a, f32x4 b) { u32x4 w; w.x = cvt_pk_bf16(a[0], a[1]); w.y = cvt_pk_bf16(a[2], a[3]); w.z = cvt_pk_bf16(b[0], b[1]); w.w = cvt_pk_bf16(b[2], b[3]); return w; }
; #define PG8_BAR __builtin_amdgcn_s_barrier()
; #define ACT(t) (KBASE(t) <= qlo + QBLK - 1 && KBASE(t) + KVBLK - 1 >= qlo - W + 1)
;     __device__ __forceinline__ void operator()(const f32x4 (&acc)[2][2][4][2], const Unit& u, int wr, int wc, int fr, int fq) const {
;         const int g = u.pn / nNper, pnl = u.pn - g * nNper, pml = u.pm & 63;
;         bf16_t* base = O + (size_t)g * gstride;
;         const int row0 = pml * BM + wr * 64 + fr, col0 = pnl * BM + wc * 32 + 8 * fq;
; #pragma unroll
;         for (int ai = 0; ai < 2; ++ai)
; #pragma unroll
;             for (int m = 0; m < 4; ++m) { bf16_t* rowp = base + (size_t)(row0 + ai * HALF + m * 16) * ldc + col0;
; #pragma unroll
;                 for (int bj = 0; bj < 2; ++bj) { f32x4 v0 = acc[ai][bj][m][0], v1 = acc[ai][bj][m][1];
;                     if (ACT == 1) {
; #pragma unroll
;                         for (int j = 0; j < 4; ++j) { float a = fmaxf(v0[j], 0.f), b = fmaxf(v1[j], 0.f); v0[j] = a * a; v1[j] = b * b; } }
;                     *(u32x4*)(rowp + bj * HALF) = pack8_bf16(v0, v1); } }
; template <class Epi, class Sched, bool ALIGN_EPI = false, bool SP2 = false>
; __device__ __forceinline__ void gemm_phase(PG8_LAS unsigned char* lds, const Gemm g, const Sched& S, const Epi& E) {
;     ...
;         if (!has_next) break;
; #pragma unroll
;         for (int a = 0; a < 2; ++a)
; #pragma unroll
;             for (int b = 0; b < 2; ++b)
; #pragma unroll
;                 for (int m = 0; m < 4; ++m)
; #pragma unroll
;                     for (int n = 0; n < 2; ++n) acc[a][b][m][n] = (f32x4){0.f, 0.f, 0.f, 0.f};
;         cur = nxt; cA = nA; cB = nB; ++ui;
;         if constexpr (ALIGN_EPI) { if (wr == 1) PG8_BAR; }
	global_store_dwordx4 v[238:239], v[250:253], off
	s_mov_b64 s[34:35], 0x50000
	v_lshl_add_u64 v[140:141], v[140:141], 0, s[34:35]
	s_mov_b64 s[34:35], 0x10000
	v_cvt_pk_bf16_f32 v60, v60, v61
	v_cvt_pk_bf16_f32 v61, v62, v63
	v_cvt_pk_bf16_f32 v62, v56, v57
	v_cvt_pk_bf16_f32 v63, v58, v59
	v_cvt_pk_bf16_f32 v48, v48, v49
	v_cvt_pk_bf16_f32 v49, v50, v51
	v_cvt_pk_bf16_f32 v50, v40, v41
	v_cvt_pk_bf16_f32 v51, v42, v43
	v_mov_b32_dpp v246, v48 row_ror:8 row_mask:0xf bank_mask:0xf
	v_mov_b32_dpp v247, v49 row_ror:8 row_mask:0xf bank_mask:0xf
	v_mov_b32_dpp v248, v50 row_ror:8 row_mask:0xf bank_mask:0xf
	v_mov_b32_dpp v249, v51 row_ror:8 row_mask:0xf bank_mask:0xf
	v_mov_b32_dpp v250, v60 row_ror:8 row_mask:0xf bank_mask:0xf
	v_mov_b32_dpp v251, v61 row_ror:8 row_mask:0xf bank_mask:0xf
	v_mov_b32_dpp v252, v62 row_ror:8 row_mask:0xf bank_mask:0xf
	v_mov_b32_dpp v253, v63 row_ror:8 row_mask:0xf bank_mask:0xf
	v_cndmask_b32_e32 v246, v60, v246, vcc
	v_cndmask_b32_e32 v247, v61, v247, vcc
	v_cndmask_b32_e32 v248, v62, v248, vcc
	v_cndmask_b32_e32 v249, v63, v249, vcc
	v_cndmask_b32_e32 v250, v250, v48, vcc
	v_cndmask_b32_e32 v251, v251, v49, vcc
	v_cndmask_b32_e32 v252, v252, v50, vcc
	v_cndmask_b32_e32 v253, v253, v51, vcc
	ds_bpermute_b32 v246, v240, v246
	ds_bpermute_b32 v247, v240, v247
	ds_bpermute_b32 v248, v240, v248
	ds_bpermute_b32 v249, v240, v249
	ds_bpermute_b32 v250, v240, v250
	ds_bpermute_b32 v251, v240, v251
	ds_bpermute_b32 v252, v240, v252
	ds_bpermute_b32 v253, v240, v253
	v_lshl_add_u64 v[238:239], v[140:141], 0, v[242:243]
	s_waitcnt lgkmcnt(4)
	global_store_dwordx4 v[140:141], v[246:249], off
	s_waitcnt lgkmcnt(0)
	global_store_dwordx4 v[238:239], v[250:253], off
	v_lshl_add_u64 v[140:141], v[140:141], 0, s[34:35]
	v_cvt_pk_bf16_f32 v52, v52, v53
	v_cvt_pk_bf16_f32 v53, v54, v55
	v_cvt_pk_bf16_f32 v54, v44, v45
	v_cvt_pk_bf16_f32 v55, v46, v47
	v_cvt_pk_bf16_f32 v32, v32, v33
	v_cvt_pk_bf16_f32 v33, v34, v35
	v_cvt_pk_bf16_f32 v34, v24, v25
	v_cvt_pk_bf16_f32 v35, v26, v27
	v_mov_b32_dpp v246, v32 row_ror:8 row_mask:0xf bank_mask:0xf
	v_mov_b32_dpp v247, v33 row_ror:8 row_mask:0xf bank_mask:0xf
	v_mov_b32_dpp v248, v34 row_ror:8 row_mask:0xf bank_mask:0xf
	v_mov_b32_dpp v249, v35 row_ror:8 row_mask:0xf bank_mask:0xf
	v_mov_b32_dpp v250, v52 row_ror:8 row_mask:0xf bank_mask:0xf
	v_mov_b32_dpp v251, v53 row_ror:8 row_mask:0xf bank_mask:0xf
	v_mov_b32_dpp v252, v54 row_ror:8 row_mask:0xf bank_mask:0xf
	v_mov_b32_dpp v253, v55 row_ror:8 row_mask:0xf bank_mask:0xf
	v_cndmask_b32_e32 v246, v52, v246, vcc
	v_cndmask_b32_e32 v247, v53, v247, vcc
	v_cndmask_b32_e32 v248, v54, v248, vcc
	v_cndmask_b32_e32 v249, v55, v249, vcc
	v_cndmask_b32_e32 v250, v250, v32, vcc
	v_cndmask_b32_e32 v251, v251, v33, vcc
	v_cndmask_b32_e32 v252, v252, v34, vcc
	v_cndmask_b32_e32 v253, v253, v35, vcc
	ds_bpermute_b32 v246, v240, v246
	ds_bpermute_b32 v247, v240, v247
	ds_bpermute_b32 v248, v240, v248
	ds_bpermute_b32 v249, v240, v249
	ds_bpermute_b32 v250, v240, v250
	ds_bpermute_b32 v251, v240, v251
	ds_bpermute_b32 v252, v240, v252
	ds_bpermute_b32 v253, v240, v253
	v_lshl_add_u64 v[238:239], v[140:141], 0, v[242:243]
	s_waitcnt lgkmcnt(4)
	global_store_dwordx4 v[140:141], v[246:249], off
	s_waitcnt lgkmcnt(0)
	global_store_dwordx4 v[238:239], v[250:253], off
	v_lshl_add_u64 v[140:141], v[140:141], 0, s[34:35]
	v_cvt_pk_bf16_f32 v36, v36, v37
	v_cvt_pk_bf16_f32 v37, v38, v39
	v_cvt_pk_bf16_f32 v38, v28, v29
	v_cvt_pk_bf16_f32 v39, v30, v31
	v_cvt_pk_bf16_f32 v16, v16, v17
	v_cvt_pk_bf16_f32 v17, v18, v19
	v_cvt_pk_bf16_f32 v18, v8, v9
	v_cvt_pk_bf16_f32 v19, v10, v11
	v_mov_b32_dpp v246, v16 row_ror:8 row_mask:0xf bank_mask:0xf
	v_mov_b32_dpp v247, v17 row_ror:8 row_mask:0xf bank_mask:0xf
	v_mov_b32_dpp v248, v18 row_ror:8 row_mask:0xf bank_mask:0xf
	v_mov_b32_dpp v249, v19 row_ror:8 row_mask:0xf bank_mask:0xf
	v_mov_b32_dpp v250, v36 row_ror:8 row_mask:0xf bank_mask:0xf
	v_mov_b32_dpp v251, v37 row_ror:8 row_mask:0xf bank_mask:0xf
	v_mov_b32_dpp v252, v38 row_ror:8 row_mask:0xf bank_mask:0xf
	v_mov_b32_dpp v253, v39 row_ror:8 row_mask:0xf bank_mask:0xf
	v_cndmask_b32_e32 v246, v36, v246, vcc
	v_cndmask_b32_e32 v247, v37, v247, vcc
	v_cndmask_b32_e32 v248, v38, v248, vcc
	v_cndmask_b32_e32 v249, v39, v249, vcc
	v_cndmask_b32_e32 v250, v250, v16, vcc
	v_cndmask_b32_e32 v251, v251, v17, vcc
	v_cndmask_b32_e32 v252, v252, v18, vcc
	v_cndmask_b32_e32 v253, v253, v19, vcc
	ds_bpermute_b32 v246, v240, v246
	ds_bpermute_b32 v247, v240, v247
	ds_bpermute_b32 v248, v240, v248
	ds_bpermute_b32 v249, v240, v249
	ds_bpermute_b32 v250, v240, v250
	ds_bpermute_b32 v251, v240, v251
	ds_bpermute_b32 v252, v240, v252
	ds_bpermute_b32 v253, v240, v253
	v_lshl_add_u64 v[238:239], v[140:141], 0, v[242:243]
	s_waitcnt lgkmcnt(4)
	global_store_dwordx4 v[140:141], v[246:249], off
	s_waitcnt lgkmcnt(0)
	global_store_dwordx4 v[238:239], v[250:253], off
	v_lshl_add_u64 v[140:141], v[140:141], 0, s[34:35]
	v_cvt_pk_bf16_f32 v20, v20, v21
	v_cvt_pk_bf16_f32 v21, v22, v23
	v_cvt_pk_bf16_f32 v22, v12, v13
	v_cvt_pk_bf16_f32 v23, v14, v15
	v_cvt_pk_bf16_f32 v4, v4, v5
	v_cvt_pk_bf16_f32 v5, v6, v7
	v_cvt_pk_bf16_f32 v6, v0, v1
	v_cvt_pk_bf16_f32 v7, v2, v3
	v_mov_b32_dpp v246, v4 row_ror:8 row_mask:0xf bank_mask:0xf
	v_mov_b32_dpp v247, v5 row_ror:8 row_mask:0xf bank_mask:0xf
	v_mov_b32_dpp v248, v6 row_ror:8 row_mask:0xf bank_mask:0xf
	v_mov_b32_dpp v249, v7 row_ror:8 row_mask:0xf bank_mask:0xf
	v_mov_b32_dpp v250, v20 row_ror:8 row_mask:0xf bank_mask:0xf
	v_mov_b32_dpp v251, v21 row_ror:8 row_mask:0xf bank_mask:0xf
	v_mov_b32_dpp v252, v22 row_ror:8 row_mask:0xf bank_mask:0xf
	v_mov_b32_dpp v253, v23 row_ror:8 row_mask:0xf bank_mask:0xf
	v_cndmask_b32_e32 v246, v20, v246, vcc
	v_cndmask_b32_e32 v247, v21, v247, vcc
	v_cndmask_b32_e32 v248, v22, v248, vcc
	v_cndmask_b32_e32 v249, v23, v249, vcc
	v_cndmask_b32_e32 v250, v250, v4, vcc
	v_cndmask_b32_e32 v251, v251, v5, vcc
	v_cndmask_b32_e32 v252, v252, v6, vcc
	v_cndmask_b32_e32 v253, v253, v7, vcc
	ds_bpermute_b32 v246, v240, v246
	ds_bpermute_b32 v247, v240, v247
	ds_bpermute_b32 v248, v240, v248
	ds_bpermute_b32 v249, v240, v249
	ds_bpermute_b32 v250, v240, v250
	ds_bpermute_b32 v251, v240, v251
	ds_bpermute_b32 v252, v240, v252
	ds_bpermute_b32 v253, v240, v253
	v_lshl_add_u64 v[238:239], v[140:141], 0, v[242:243]
	s_waitcnt lgkmcnt(4)
	global_store_dwordx4 v[140:141], v[246:249], off
	s_waitcnt lgkmcnt(0)
	global_store_dwordx4 v[238:239], v[250:253], off
	s_andn2_b64 vcc, exec, s[40:41]
	s_mov_b64 s[34:35], -1
	s_cbranch_vccnz .LBB0_319
	s_andn2_b64 vcc, exec, s[8:9]
	s_cbranch_vccnz .LBB0_318
	s_barrier
	s_branch .LBB0_318

; #define PG8_WAIT_V(n) asm volatile("s_waitcnt vmcnt(" #n ")" ::: "memory")
; #define PG8_BAR __builtin_amdgcn_s_barrier()
; template <class Epi, class Sched, bool ALIGN_EPI = false, bool SP2 = false>
; __device__ __forceinline__ void gemm_phase(PG8_LAS unsigned char* lds, const Gemm g, const Sched& S, const Epi& E) {
;     int tid_l_ = threadIdx.x; asm volatile("" : "+v"(tid_l_)); const int tid = tid_l_, wid = __builtin_amdgcn_readfirstlane(tid >> 6), lane = tid & 63, wr = wid >> 2, wc = wid & 3, fr = lane & 15, fq = lane >> 4;
;     const int K = g.K, nt = K / BK;
;     unsigned voffA[2], voffB[2];
; #pragma unroll
;     for (int i = 0; i < 2; ++i) { int R, C; stage_rc(tid * 16 + i * 8192, R, C); const int Rb = Epi::PERM ? ((R & ~31) + perm32(R & 31)) : R;
;         voffA[i] = (unsigned)(R * K + C) * 2u; voffB[i] = (unsigned)(Rb * K + C) * 2u; }
;     const size_t kstep = (size_t)(BK * 2);
;     const size_t hstep = (size_t)HALF * K * 2;
;     const size_t tstep = 2 * hstep;
;     const unsigned ldsw = (unsigned)wid * 1024u;
;     const int aoff = lds_byte(wr * 64 + fr, fq * 8), boff = lds_byte(wc * 32 + fr, fq * 8);
;     ...
;     Unit cur, nxt; int ui = 0;
;     if (!S.next(0, cur)) return;
;     f32x4 acc[2][2][4][2];
; #pragma unroll
;     for (int a = 0; a < 2; ++a)
; #pragma unroll
;         for (int b = 0; b < 2; ++b)
; #pragma unroll
;             for (int m = 0; m < 4; ++m)
; #pragma unroll
;                 for (int n = 0; n < 2; ++n) acc[a][b][m][n] = (f32x4){0.f, 0.f, 0.f, 0.f};
;     bf16x8 At[4][2], B0[2][2], B1[2][2];
;     const char* cA = (const char*)g.A + (size_t)cur.pm * tstep; const char* cB = (const char*)g.Bt + (size_t)cur.pn * tstep;
;     S.a_ready(cur);
;     if constexpr (SP2) {
;         PG8_STAGE(PG8_SB(0, 0), cB, voffB); PG8_STAGE(PG8_SB(0, 1), cB + hstep, voffB); PG8_STAGE(PG8_SA(0, 0), cA, voffA); PG8_STAGE(PG8_SA(0, 1), cA + hstep, voffA);
;         if (wr == 1) PG8_BAR;
;         PG8_WAIT_V(2); PG8_BAR;
;         PG8_STAGE(PG8_SB(1, 0), cB + kstep, voffB); PG8_STAGE(PG8_SA(1, 0), cA + kstep, voffA); PG8_STAGE(PG8_SB(1, 1), cB + hstep + kstep, voffB);
;         PG8_WAIT_V(6); PG8_BAR;
;     } else {
;         PG8_STAGE(PG8_SB(0, 0), cB, voffB); PG8_STAGE(PG8_SA(0, 0), cA, voffA); PG8_STAGE(PG8_SB(0, 1), cB + hstep, voffB); PG8_STAGE(PG8_SA(0, 1), cA + hstep, voffA);
;         if (wr == 1) PG8_BAR;
;         PG8_WAIT_V(4); PG8_BAR;
.LBB0_440:
	s_andn2_b64 vcc, exec, s[8:9]
	s_cbranch_vccnz .LBB0_468
	s_cmp_gt_i32 s22, 5
	s_mov_b64 s[8:9], -1
	s_cbranch_scc0 .LBB0_463
	s_waitcnt vmcnt(0)
	v_mov_b32_e32 v6, v208
	s_cmpk_gt_i32 s23, 0x7ff
	s_nop 0
	v_readfirstlane_b32 s12, v6
	s_cbranch_scc1 .LBB0_462
	v_lshlrev_b32_e32 v3, 4, v6
	v_add_u32_e32 v1, 0x2000, v3
	v_ashrrev_i32_e32 v0, 31, v1
	v_lshrrev_b32_e32 v0, 22, v0
	v_add_u32_e32 v0, v1, v0
	v_ashrrev_i32_e32 v0, 10, v0
	v_mul_i32_i24_e32 v2, 0x400, v0
	v_sub_u32_e32 v1, v1, v2
	v_lshrrev_b32_e32 v2, 4, v1
	v_bitop3_b32 v2, v2, v1, 32 bitop3:0x6c
	v_ashrrev_i32_e32 v1, 31, v2
	v_lshrrev_b32_e32 v1, 26, v1
	v_add_u32_e32 v4, v2, v1
	v_lshlrev_b32_e32 v5, 3, v0
	v_ashrrev_i32_e32 v1, 6, v4
	v_and_b32_e32 v5, -16, v5
	v_add_u32_e32 v5, v1, v5
	v_and_b32_e32 v7, 3, v1
	s_mov_b32 s7, 0xfffe0
	v_lshrrev_b32_e32 v8, 2, v5
	v_lshlrev_b32_e32 v9, 1, v5
	v_and_b32_e32 v4, 0xc0, v4
	v_and_b32_e32 v252, s7, v5
	v_lshl_or_b32 v7, v252, 1, v7
	v_and_b32_e32 v8, 4, v8
	v_and_b32_e32 v9, 24, v9
	v_sub_u32_e32 v2, v2, v4
	v_mov_b32_e32 v12, 1
	v_or3_b32 v7, v7, v8, v9
	v_lshlrev_b32_e32 v8, 5, v0
	v_ashrrev_i16_sdwa v2, v12, sext(v2) dst_sel:DWORD dst_unused:UNUSED_PAD src0_sel:DWORD src1_sel:BYTE_0
	v_and_b32_e32 v8, 32, v8
	v_bfe_i32 v2, v2, 0, 16
	v_add_lshl_u32 v4, v8, v2, 1
	v_lshl_add_u32 v130, v7, 12, v4
	v_lshl_add_u32 v132, v5, 12, v4
	v_bfe_i32 v4, v6, 27, 1
	v_lshrrev_b32_e32 v4, 22, v4
	v_add_u32_e32 v4, v3, v4
	v_and_b32_e32 v4, 0xfffffc00, v4
	v_sub_u32_e32 v3, v3, v4
	v_lshrrev_b32_e32 v4, 4, v3
	v_bitop3_b32 v5, v4, v3, 32 bitop3:0x6c
	v_ashrrev_i32_e32 v4, 31, v6
	v_lshrrev_b32_e32 v4, 26, v4
	v_ashrrev_i32_e32 v3, 31, v5
	v_add_u32_e32 v4, v6, v4
	v_lshrrev_b32_e32 v3, 26, v3
	v_ashrrev_i32_e32 v4, 6, v4
	v_add_u32_e32 v7, v5, v3
	v_lshlrev_b32_e32 v8, 3, v4
	v_ashrrev_i32_e32 v3, 6, v7
	v_and_b32_e32 v8, -16, v8
	v_add_u32_e32 v8, v3, v8
	v_and_b32_e32 v9, 3, v3
	s_ashr_i32 s13, s12, 6
	v_and_b32_e32 v252, s7, v8
	v_lshl_or_b32 v9, v252, 1, v9
	v_readlane_b32 s6, v255, 5
	s_ashr_i32 s18, s12, 8
	s_lshl_b32 s2, s13, 10
	v_readlane_b32 s7, v255, 6
	s_and_b64 s[8:9], s[6:7], exec
	s_cselect_b32 s8, s67, s66
	v_readlane_b32 s6, v255, 4
	s_add_i32 s8, s8, s6
	s_ashr_i32 s9, s8, 31
	s_lshr_b32 s9, s9, 25
	s_add_i32 s9, s8, s9
	s_ashr_i32 s10, s9, 7
	s_lshl_b32 s10, s10, 2
	s_mov_b32 s83, s17
	s_sub_i32 s17, 64, s10
	s_min_i32 s17, s17, 4
	v_and_b32_e32 v7, 0xc0, v7
	s_abs_i32 s19, s17
	v_sub_u32_e32 v5, v5, v7
	v_cvt_f32_u32_e32 v7, s19
	s_sub_i32 s27, 0, s19
	s_and_b32 s9, s9, 0xffffff80
	s_sub_i32 s8, s8, s9
	v_rcp_iflag_f32_e32 v7, v7
	s_abs_i32 s26, s8
	s_xor_b32 s9, s8, s17
	s_ashr_i32 s9, s9, 31
	v_mul_f32_e32 v7, 0x4f7ffffe, v7
	v_cvt_u32_f32_e32 v7, v7
	v_readlane_b32 s6, v255, 7
	v_lshrrev_b32_e32 v10, 2, v8
	v_lshlrev_b32_e32 v11, 1, v8
	v_readfirstlane_b32 s28, v7
	s_mul_i32 s27, s27, s28
	s_mul_hi_u32 s27, s28, s27
	s_add_i32 s28, s28, s27
	s_mul_hi_u32 s27, s26, s28
	s_mul_i32 s28, s27, s19
	s_sub_i32 s26, s26, s28
	s_add_i32 s28, s27, 1
	s_sub_i32 s29, s26, s19
	s_cmp_ge_u32 s26, s19
	s_cselect_b32 s27, s28, s27
	s_cselect_b32 s26, s29, s26
	s_add_i32 s28, s27, 1
	s_cmp_ge_u32 s26, s19
	s_cselect_b32 s19, s28, s27
	s_xor_b32 s19, s19, s9
	s_sub_i32 s9, s19, s9
	s_mul_i32 s17, s9, s17
	s_sub_i32 s8, s8, s17
	s_add_i32 s8, s8, s6
	v_readlane_b32 s6, v255, 8
	s_add_i32 s46, s8, s10
	s_add_i32 s62, s9, s6
	v_and_b32_e32 v10, 4, v10
	v_and_b32_e32 v11, 24, v11
	s_ashr_i32 s47, s46, 31
	s_ashr_i32 s63, s62, 31
	v_or3_b32 v9, v9, v10, v11
	v_lshlrev_b32_e32 v10, 5, v4
	v_ashrrev_i16_sdwa v5, v12, sext(v5) dst_sel:DWORD dst_unused:UNUSED_PAD src0_sel:DWORD src1_sel:BYTE_0
	s_lshl_b64 s[8:9], s[46:47], 20
	s_lshl_b64 s[26:27], s[62:63], 20
	v_and_b32_e32 v10, 32, v10
	v_bfe_i32 v5, v5, 0, 16
	s_add_u32 s68, s38, s26
	v_add_lshl_u32 v10, v10, v5, 1
	s_addc_u32 s69, s39, s27
	s_add_i32 s7, s2, 0
	v_lshl_add_u32 v128, v9, 12, v10
	s_add_i32 m0, s7, 0x10000
	v_lshl_add_u32 v134, v8, 12, v10
	global_load_lds_dwordx4 v128, s[68:69]
	s_add_i32 m0, s7, 0x12000
	s_add_u32 s26, s68, 0x20000
	global_load_lds_dwordx4 v130, s[68:69]
	s_addc_u32 s27, s69, 0
	s_add_i32 m0, s7, 0x14000
	s_nop 0
	global_load_lds_dwordx4 v128, s[26:27]
	s_add_i32 m0, s7, 0x16000
	s_add_u32 s66, s58, s8
	s_addc_u32 s67, s59, s9
	s_add_i32 s10, s7, 0x2000
	global_load_lds_dwordx4 v130, s[26:27]
	s_mov_b32 m0, s7
	s_add_u32 s8, s66, 0x80000
	global_load_lds_dwordx4 v134, s[66:67]
	s_mov_b32 m0, s10
	s_addc_u32 s9, s67, 0
	s_add_i32 s17, s7, 0x4000
	global_load_lds_dwordx4 v132, s[66:67]
	s_mov_b32 m0, s17
	s_add_i32 s26, s7, 0x6000
	global_load_lds_dwordx4 v134, s[8:9]
	s_mov_b32 m0, s26
	s_cmp_eq_u32 s18, 1
	global_load_lds_dwordx4 v132, s[8:9]
	s_cselect_b64 s[8:9], -1, 0
	s_cmp_lg_u32 s18, 1
	s_cbranch_scc1 .LBB0_445
	s_barrier
.LBB0_445:
	v_lshrrev_b32_e32 v16, 1, v6
	v_and_b32_e32 v16, 24, v16
	s_lshl_b32 s13, s13, 5
	v_and_b32_e32 v7, 15, v6
	v_lshlrev_b32_e32 v17, 1, v16
	v_lshlrev_b32_e32 v6, 2, v6
	s_and_b32 s29, s13, 0x60
	v_lshl_add_u64 v[8:9], s[68:69], 0, v[128:129]
	v_mov_b32_e32 v131, v129
	v_bfe_u32 v252, v208, 3, 3
	v_lshl_or_b32 v142, s18, 6, v252
	v_lshl_or_b32 v7, v7, 6, v17
	s_lshl_b32 s18, s18, 13
	v_and_b32_e32 v6, 32, v6
	s_lshl_b32 s13, s29, 7
	v_lshl_add_u64 v[10:11], s[68:69], 0, v[130:131]
	v_mov_b32_e32 v135, v129
	v_bitop3_b32 v17, v7, s18, v6 bitop3:0xde
	v_bitop3_b32 v143, v7, s13, v6 bitop3:0xde
	s_add_i32 m0, s7, 0x18000
	v_lshl_add_u64 v[6:7], v[8:9], 0, s[20:21]
	v_lshl_add_u64 v[12:13], s[66:67], 0, v[134:135]
	v_mov_b32_e32 v133, v129
	s_waitcnt vmcnt(2)
	s_barrier
	global_load_lds_dwordx4 v[6:7], off
	v_lshl_add_u64 v[6:7], v[10:11], 0, s[20:21]
	s_add_i32 m0, s7, 0x1a000
	s_add_i32 s27, s7, 0x8000
	s_add_i32 s28, s7, 0xa000
	v_lshl_add_u64 v[14:15], s[66:67], 0, v[132:133]
	global_load_lds_dwordx4 v[6:7], off
	v_lshl_add_u64 v[6:7], v[12:13], 0, s[20:21]
	s_mov_b32 m0, s27
	s_add_u32 s18, s68, 0x20080
	global_load_lds_dwordx4 v[6:7], off
	v_lshl_add_u64 v[6:7], v[14:15], 0, s[20:21]
	s_mov_b32 m0, s28
	s_addc_u32 s19, s69, 0
	global_load_lds_dwordx4 v[6:7], off
	s_add_i32 m0, s7, 0x1c000
	v_lshl_add_u64 v[6:7], s[18:19], 0, v[128:129]
	global_load_lds_dwordx4 v[6:7], off
	v_lshl_add_u64 v[6:7], s[18:19], 0, v[130:131]
	s_add_i32 m0, s7, 0x1e000
	s_cmpk_lt_u32 s12, 0x100
	global_load_lds_dwordx4 v[6:7], off
	v_lshlrev_b32_e32 v6, 15, v4
	v_and_b32_e32 v6, 0xffff0000, v6
	v_lshl_add_u32 v3, v3, 12, v6
	v_and_b32_e32 v4, 1, v4
	v_lshl_or_b32 v3, v4, 6, v3
	v_lshl_add_u32 v136, v5, 1, v3
	v_lshlrev_b32_e32 v3, 15, v0
	v_and_b32_e32 v3, 0xffff0000, v3
	s_waitcnt vmcnt(6)
	v_lshl_add_u32 v1, v1, 12, v3
	v_and_b32_e32 v0, 1, v0
	v_lshl_or_b32 v0, v0, 6, v1
	s_cselect_b64 s[12:13], -1, 0
	v_and_b32_e32 v252, 7, v208
	v_lshlrev_b32_e32 v252, 3, v252
	v_lshl_or_b32 v144, s29, 1, v252
	v_mov_b32_e32 v137, v129
	v_lshl_add_u32 v138, v2, 1, v0
	v_mov_b32_e32 v139, v129
	s_mov_b32 s29, 0
	v_add_u32_e32 v145, 0, v17
	s_barrier
	s_branch .LBB0_448

; #define PG8_STAGE(bufoff, gbase, voff) do { _Pragma("unroll") for (int _i = 0; _i < 2; ++_i) \
;         __builtin_amdgcn_global_load_lds((const unsigned*)((const char*)(gbase) + (voff)[_i]), (PG8_LAS unsigned*)(lds + (bufoff) + ldsw + _i * 8192), 16, 0, 0); } while (0)
; #define PG8_LDA(dst, b, h) do { _Pragma("unroll") for (int m = 0; m < 4; ++m) _Pragma("unroll") for (int k = 0; k < 2; ++k) dst[m][k] = *(const PG8_LAS bf16x8*)(lds + PG8_SA(b, h) + aoff + m * 2048 + k * 1024); } while (0)
; #define PG8_LDB(dst, b, h) do { _Pragma("unroll") for (int n = 0; n < 2; ++n) _Pragma("unroll") for (int k = 0; k < 2; ++k) dst[n][k] = *(const PG8_LAS bf16x8*)(lds + PG8_SB(b, h) + boff + n * 2048 + k * 1024); } while (0)
; #define PG8_MMA(ai, bj, At, Bt) do { __builtin_amdgcn_s_setprio(1); _Pragma("unroll") for (int m = 0; m < 4; ++m) _Pragma("unroll") for (int n = 0; n < 2; ++n) _Pragma("unroll") for (int k = 0; k < 2; ++k) \
;         acc[ai][bj][m][n] = __builtin_amdgcn_mfma_f32_16x16x32_bf16(Bt[n][k], At[m][k], acc[ai][bj][m][n], 0, 0, 0); __builtin_amdgcn_s_setprio(0); } while (0)
; #define PG8_WAIT_V(n) asm volatile("s_waitcnt vmcnt(" #n ")" ::: "memory")
; #define PG8_WAIT_L(n) asm volatile("s_waitcnt lgkmcnt(" #n ")" ::: "memory")
; #define PG8_BAR __builtin_amdgcn_s_barrier()
; #define PG8_SCHED __builtin_amdgcn_sched_barrier(0)
; template <class Epi, class Sched, bool ALIGN_EPI = false, bool SP2 = false>
; __device__ __forceinline__ void gemm_phase(PG8_LAS unsigned char* lds, const Gemm g, const Sched& S, const Epi& E) {
;     ...
;             PG8_LDB(B0, 0, 0); PG8_LDB(B1, 0, 1); PG8_SCHED; PG8_LDA(At, 0, 0); PG8_STAGE(PG8_SA(1, 1), a1 + hstep, voffA);
;             PG8_WAIT_V(8); PG8_WAIT_L(0); PG8_BAR; PG8_MMA(0, 0, At, B0); PG8_MMA(0, 1, At, B1); PG8_BAR; PG8_SCHED;
;             PG8_LDA(At, 0, 1); PG8_STAGE(PG8_SB(0, 0), b2, voffB); PG8_STAGE(PG8_SB(0, 1), b2 + hstep, voffB); PG8_STAGE(PG8_SA(0, 0), a2, voffA);
;             PG8_WAIT_V(8); PG8_WAIT_L(0); PG8_BAR; PG8_MMA(1, 0, At, B0); PG8_MMA(1, 1, At, B1); PG8_BAR; PG8_SCHED;
.LBB0_455:
	s_add_u32 s49, s66, 0xfff80080
	s_addc_u32 s52, s67, -1
	s_add_i32 s53, 0, 0x10000
	s_cmp_eq_u32 s47, 28
	s_cselect_b32 s71, s19, s52
	s_cselect_b32 s70, s33, s49
	v_add_u32_e32 v140, s53, v143
	s_cselect_b32 s69, s31, s37
	s_cselect_b32 s68, s34, s35
	s_add_i32 s49, 0, 0x14000
	ds_read_b128 v[146:149], v140
	ds_read_b128 v[150:153], v140 offset:1024
	ds_read_b128 v[154:157], v140 offset:2048
	ds_read_b128 v[158:161], v140 offset:3072
	v_add_u32_e32 v140, s49, v143
	ds_read_b128 v[162:165], v140
	ds_read_b128 v[166:169], v140 offset:1024
	ds_read_b128 v[170:173], v140 offset:2048
	ds_read_b128 v[174:177], v140 offset:3072
	v_lshl_add_u64 v[140:141], s[66:67], 0, v[136:137]
	s_add_i32 m0, s7, 0xc000
	ds_read_b128 v[178:181], v145
	ds_read_b128 v[182:185], v145 offset:1024
	ds_read_b128 v[186:189], v145 offset:2048
	ds_read_b128 v[190:193], v145 offset:3072
	ds_read_b128 v[220:223], v145 offset:4096
	ds_read_b128 v[224:227], v145 offset:5120
	ds_read_b128 v[228:231], v145 offset:6144
	ds_read_b128 v[232:235], v145 offset:7168
	global_load_lds_dwordx4 v[140:141], off
	v_lshl_add_u64 v[140:141], s[66:67], 0, v[138:139]
	s_add_i32 m0, s7, 0xe000
	s_nop 0
	global_load_lds_dwordx4 v[140:141], off
	s_waitcnt vmcnt(8)
	s_waitcnt lgkmcnt(0)
	s_barrier
	s_setprio 1
	s_waitcnt lgkmcnt(0)
	v_mfma_f32_16x16x32_bf16 v[124:127], v[146:149], v[178:181], v[124:127]
	v_mfma_f32_16x16x32_bf16 v[120:123], v[154:157], v[178:181], v[120:123]
	v_mfma_f32_16x16x32_bf16 v[108:111], v[146:149], v[186:189], v[108:111]
	v_mfma_f32_16x16x32_bf16 v[104:107], v[154:157], v[186:189], v[104:107]
	v_mfma_f32_16x16x32_bf16 v[92:95], v[146:149], v[220:223], v[92:95]
	v_mfma_f32_16x16x32_bf16 v[88:91], v[154:157], v[220:223], v[88:91]
	v_mfma_f32_16x16x32_bf16 v[76:79], v[146:149], v[228:231], v[76:79]
	v_mfma_f32_16x16x32_bf16 v[72:75], v[154:157], v[228:231], v[72:75]
	v_mfma_f32_16x16x32_bf16 v[124:127], v[150:153], v[182:185], v[124:127]
	v_mfma_f32_16x16x32_bf16 v[120:123], v[158:161], v[182:185], v[120:123]
	v_mfma_f32_16x16x32_bf16 v[108:111], v[150:153], v[190:193], v[108:111]
	v_mfma_f32_16x16x32_bf16 v[104:107], v[158:161], v[190:193], v[104:107]
	v_mfma_f32_16x16x32_bf16 v[92:95], v[150:153], v[224:227], v[92:95]
	v_mfma_f32_16x16x32_bf16 v[88:91], v[158:161], v[224:227], v[88:91]
	v_mfma_f32_16x16x32_bf16 v[76:79], v[150:153], v[232:235], v[76:79]
	v_mfma_f32_16x16x32_bf16 v[72:75], v[158:161], v[232:235], v[72:75]
	s_setprio 0
	s_setprio 1
	v_mfma_f32_16x16x32_bf16 v[116:119], v[162:165], v[178:181], v[116:119]
	v_mfma_f32_16x16x32_bf16 v[112:115], v[170:173], v[178:181], v[112:115]
	v_mfma_f32_16x16x32_bf16 v[100:103], v[162:165], v[186:189], v[100:103]
	v_mfma_f32_16x16x32_bf16 v[96:99], v[170:173], v[186:189], v[96:99]
	v_mfma_f32_16x16x32_bf16 v[84:87], v[162:165], v[220:223], v[84:87]
	v_mfma_f32_16x16x32_bf16 v[80:83], v[170:173], v[220:223], v[80:83]
	v_mfma_f32_16x16x32_bf16 v[68:71], v[162:165], v[228:231], v[68:71]
	v_mfma_f32_16x16x32_bf16 v[64:67], v[170:173], v[228:231], v[64:67]
	v_mfma_f32_16x16x32_bf16 v[116:119], v[166:169], v[182:185], v[116:119]
	v_mfma_f32_16x16x32_bf16 v[112:115], v[174:177], v[182:185], v[112:115]
	v_mfma_f32_16x16x32_bf16 v[100:103], v[166:169], v[190:193], v[100:103]
	v_mfma_f32_16x16x32_bf16 v[96:99], v[174:177], v[190:193], v[96:99]
	v_mfma_f32_16x16x32_bf16 v[84:87], v[166:169], v[224:227], v[84:87]
	v_mfma_f32_16x16x32_bf16 v[80:83], v[174:177], v[224:227], v[80:83]
	v_mfma_f32_16x16x32_bf16 v[68:71], v[166:169], v[232:235], v[68:71]
	v_mfma_f32_16x16x32_bf16 v[64:67], v[174:177], v[232:235], v[64:67]
	s_setprio 0
	s_barrier
	s_add_i32 s52, s53, s2
	v_lshl_add_u64 v[140:141], s[68:69], 0, v[128:129]
	s_mov_b32 m0, s52
	ds_read_b128 v[178:181], v145 offset:16384
	ds_read_b128 v[182:185], v145 offset:17408
	ds_read_b128 v[186:189], v145 offset:18432
	ds_read_b128 v[190:193], v145 offset:19456
	ds_read_b128 v[220:223], v145 offset:20480
	ds_read_b128 v[224:227], v145 offset:21504
	ds_read_b128 v[228:231], v145 offset:22528
	ds_read_b128 v[232:235], v145 offset:23552
	global_load_lds_dwordx4 v[140:141], off
	s_add_i32 m0, s52, 0x2000
	s_add_u32 s52, s68, 0x20000
	v_lshl_add_u64 v[206:207], s[68:69], 0, v[130:131]
	s_addc_u32 s53, s69, 0
	s_add_i32 s49, s49, s2
	global_load_lds_dwordx4 v[206:207], off
	v_lshl_add_u64 v[214:215], s[52:53], 0, v[128:129]
	s_mov_b32 m0, s49
	v_lshl_add_u64 v[216:217], s[70:71], 0, v[132:133]
	global_load_lds_dwordx4 v[214:215], off
	v_lshl_add_u64 v[214:215], s[52:53], 0, v[130:131]
	s_add_i32 m0, s49, 0x2000
	s_nop 0
	global_load_lds_dwordx4 v[214:215], off
	v_lshl_add_u64 v[214:215], s[70:71], 0, v[134:135]
	s_mov_b32 m0, s7
	s_nop 0
	global_load_lds_dwordx4 v[214:215], off
	s_mov_b32 m0, s10
	s_nop 0
	global_load_lds_dwordx4 v[216:217], off
	s_waitcnt vmcnt(8)
	s_waitcnt lgkmcnt(0)
	s_barrier
; #define PG8_STAGE(bufoff, gbase, voff) do { _Pragma("unroll") for (int _i = 0; _i < 2; ++_i) \
;         __builtin_amdgcn_global_load_lds((const unsigned*)((const char*)(gbase) + (voff)[_i]), (PG8_LAS unsigned*)(lds + (bufoff) + ldsw + _i * 8192), 16, 0, 0); } while (0)
; #define PG8_LDA(dst, b, h) do { _Pragma("unroll") for (int m = 0; m < 4; ++m) _Pragma("unroll") for (int k = 0; k < 2; ++k) dst[m][k] = *(const PG8_LAS bf16x8*)(lds + PG8_SA(b, h) + aoff + m * 2048 + k * 1024); } while (0)
; #define PG8_LDB(dst, b, h) do { _Pragma("unroll") for (int n = 0; n < 2; ++n) _Pragma("unroll") for (int k = 0; k < 2; ++k) dst[n][k] = *(const PG8_LAS bf16x8*)(lds + PG8_SB(b, h) + boff + n * 2048 + k * 1024); } while (0)
; #define PG8_MMA(ai, bj, At, Bt) do { __builtin_amdgcn_s_setprio(1); _Pragma("unroll") for (int m = 0; m < 4; ++m) _Pragma("unroll") for (int n = 0; n < 2; ++n) _Pragma("unroll") for (int k = 0; k < 2; ++k) \
;         acc[ai][bj][m][n] = __builtin_amdgcn_mfma_f32_16x16x32_bf16(Bt[n][k], At[m][k], acc[ai][bj][m][n], 0, 0, 0); __builtin_amdgcn_s_setprio(0); } while (0)
; #define PG8_WAIT_V(n) asm volatile("s_waitcnt vmcnt(" #n ")" ::: "memory")
; #define PG8_WAIT_L(n) asm volatile("s_waitcnt lgkmcnt(" #n ")" ::: "memory")
; #define PG8_BAR __builtin_amdgcn_s_barrier()
; #define PG8_SCHED __builtin_amdgcn_sched_barrier(0)
; template <class Epi, class Sched, bool ALIGN_EPI = false, bool SP2 = false>
; __device__ __forceinline__ void gemm_phase(PG8_LAS unsigned char* lds, const Gemm g, const Sched& S, const Epi& E) {
;     ...
;             PG8_WAIT_V(8); PG8_WAIT_L(0); PG8_BAR; PG8_MMA(1, 0, At, B0); PG8_MMA(1, 1, At, B1); PG8_BAR; PG8_SCHED;
;             PG8_LDB(B0, 1, 0); PG8_LDB(B1, 1, 1); PG8_SCHED; PG8_LDA(At, 1, 0); PG8_STAGE(PG8_SA(0, 1), a2 + hstep, voffA);
;             PG8_WAIT_V(8); PG8_WAIT_L(0); PG8_BAR; PG8_MMA(0, 0, At, B0); PG8_MMA(0, 1, At, B1); PG8_BAR; PG8_SCHED;
	s_setprio 1
	s_waitcnt lgkmcnt(0)
	v_mfma_f32_16x16x32_bf16 v[60:63], v[146:149], v[178:181], v[60:63]
	v_mfma_f32_16x16x32_bf16 v[56:59], v[154:157], v[178:181], v[56:59]
	v_mfma_f32_16x16x32_bf16 v[44:47], v[146:149], v[186:189], v[44:47]
	v_mfma_f32_16x16x32_bf16 v[40:43], v[154:157], v[186:189], v[40:43]
	v_mfma_f32_16x16x32_bf16 v[28:31], v[146:149], v[220:223], v[28:31]
	v_mfma_f32_16x16x32_bf16 v[24:27], v[154:157], v[220:223], v[24:27]
	v_mfma_f32_16x16x32_bf16 v[12:15], v[146:149], v[228:231], v[12:15]
	v_mfma_f32_16x16x32_bf16 v[8:11], v[154:157], v[228:231], v[8:11]
	v_mfma_f32_16x16x32_bf16 v[60:63], v[150:153], v[182:185], v[60:63]
	v_mfma_f32_16x16x32_bf16 v[56:59], v[158:161], v[182:185], v[56:59]
	v_mfma_f32_16x16x32_bf16 v[44:47], v[150:153], v[190:193], v[44:47]
	v_mfma_f32_16x16x32_bf16 v[40:43], v[158:161], v[190:193], v[40:43]
	v_mfma_f32_16x16x32_bf16 v[28:31], v[150:153], v[224:227], v[28:31]
	v_mfma_f32_16x16x32_bf16 v[24:27], v[158:161], v[224:227], v[24:27]
	v_mfma_f32_16x16x32_bf16 v[12:15], v[150:153], v[232:235], v[12:15]
	v_mfma_f32_16x16x32_bf16 v[8:11], v[158:161], v[232:235], v[8:11]
	s_setprio 0
	s_setprio 1
	v_mfma_f32_16x16x32_bf16 v[52:55], v[162:165], v[178:181], v[52:55]
	v_mfma_f32_16x16x32_bf16 v[48:51], v[170:173], v[178:181], v[48:51]
	v_mfma_f32_16x16x32_bf16 v[36:39], v[162:165], v[186:189], v[36:39]
	v_mfma_f32_16x16x32_bf16 v[32:35], v[170:173], v[186:189], v[32:35]
	v_mfma_f32_16x16x32_bf16 v[20:23], v[162:165], v[220:223], v[20:23]
	v_mfma_f32_16x16x32_bf16 v[16:19], v[170:173], v[220:223], v[16:19]
	v_mfma_f32_16x16x32_bf16 v[4:7], v[162:165], v[228:231], v[4:7]
	v_mfma_f32_16x16x32_bf16 v[0:3], v[170:173], v[228:231], v[0:3]
	v_mfma_f32_16x16x32_bf16 v[52:55], v[166:169], v[182:185], v[52:55]
	v_mfma_f32_16x16x32_bf16 v[48:51], v[174:177], v[182:185], v[48:51]
	v_mfma_f32_16x16x32_bf16 v[36:39], v[166:169], v[190:193], v[36:39]
	v_mfma_f32_16x16x32_bf16 v[32:35], v[174:177], v[190:193], v[32:35]
	v_mfma_f32_16x16x32_bf16 v[20:23], v[166:169], v[224:227], v[20:23]
	v_mfma_f32_16x16x32_bf16 v[16:19], v[174:177], v[224:227], v[16:19]
	v_mfma_f32_16x16x32_bf16 v[4:7], v[166:169], v[232:235], v[4:7]
	v_mfma_f32_16x16x32_bf16 v[0:3], v[174:177], v[232:235], v[0:3]
	s_setprio 0
	s_barrier
	s_add_i32 s49, 0, 0x18000
	s_add_i32 s63, 0, 0x1c000
	v_add_u32_e32 v158, s49, v143
	v_add_u32_e32 v174, s63, v143
	ds_read_b128 v[146:149], v158
	ds_read_b128 v[150:153], v158 offset:1024
	ds_read_b128 v[154:157], v158 offset:2048
	ds_read_b128 v[158:161], v158 offset:3072
	ds_read_b128 v[162:165], v174
	ds_read_b128 v[166:169], v174 offset:1024
	ds_read_b128 v[170:173], v174 offset:2048
	ds_read_b128 v[174:177], v174 offset:3072
	s_add_u32 s52, s70, 0x80000
	s_addc_u32 s53, s71, 0
	s_mov_b32 m0, s17
	v_lshl_add_u64 v[236:237], s[52:53], 0, v[134:135]
	ds_read_b128 v[178:181], v145 offset:32768
	ds_read_b128 v[182:185], v145 offset:33792
	ds_read_b128 v[186:189], v145 offset:34816
	ds_read_b128 v[190:193], v145 offset:35840
	ds_read_b128 v[220:223], v145 offset:36864
	ds_read_b128 v[224:227], v145 offset:37888
	ds_read_b128 v[228:231], v145 offset:38912
	ds_read_b128 v[232:235], v145 offset:39936
	global_load_lds_dwordx4 v[236:237], off
	v_lshl_add_u64 v[236:237], s[52:53], 0, v[132:133]
	s_mov_b32 m0, s26
	s_nop 0
	global_load_lds_dwordx4 v[236:237], off
	s_waitcnt vmcnt(8)
	s_waitcnt lgkmcnt(0)
	s_barrier
	s_setprio 1
	s_waitcnt lgkmcnt(0)
	v_mfma_f32_16x16x32_bf16 v[124:127], v[146:149], v[178:181], v[124:127]
	v_mfma_f32_16x16x32_bf16 v[120:123], v[154:157], v[178:181], v[120:123]
	v_mfma_f32_16x16x32_bf16 v[108:111], v[146:149], v[186:189], v[108:111]
	v_mfma_f32_16x16x32_bf16 v[104:107], v[154:157], v[186:189], v[104:107]
	v_mfma_f32_16x16x32_bf16 v[92:95], v[146:149], v[220:223], v[92:95]
	v_mfma_f32_16x16x32_bf16 v[88:91], v[154:157], v[220:223], v[88:91]
	v_mfma_f32_16x16x32_bf16 v[76:79], v[146:149], v[228:231], v[76:79]
	v_mfma_f32_16x16x32_bf16 v[72:75], v[154:157], v[228:231], v[72:75]
	v_mfma_f32_16x16x32_bf16 v[124:127], v[150:153], v[182:185], v[124:127]
	v_mfma_f32_16x16x32_bf16 v[120:123], v[158:161], v[182:185], v[120:123]
	v_mfma_f32_16x16x32_bf16 v[108:111], v[150:153], v[190:193], v[108:111]
	v_mfma_f32_16x16x32_bf16 v[104:107], v[158:161], v[190:193], v[104:107]
	v_mfma_f32_16x16x32_bf16 v[92:95], v[150:153], v[224:227], v[92:95]
	v_mfma_f32_16x16x32_bf16 v[88:91], v[158:161], v[224:227], v[88:91]
	v_mfma_f32_16x16x32_bf16 v[76:79], v[150:153], v[232:235], v[76:79]
	v_mfma_f32_16x16x32_bf16 v[72:75], v[158:161], v[232:235], v[72:75]
	s_setprio 0
	s_setprio 1
	v_mfma_f32_16x16x32_bf16 v[116:119], v[162:165], v[178:181], v[116:119]
	v_mfma_f32_16x16x32_bf16 v[112:115], v[170:173], v[178:181], v[112:115]
	v_mfma_f32_16x16x32_bf16 v[100:103], v[162:165], v[186:189], v[100:103]
	v_mfma_f32_16x16x32_bf16 v[96:99], v[170:173], v[186:189], v[96:99]
	v_mfma_f32_16x16x32_bf16 v[84:87], v[162:165], v[220:223], v[84:87]
	v_mfma_f32_16x16x32_bf16 v[80:83], v[170:173], v[220:223], v[80:83]
	v_mfma_f32_16x16x32_bf16 v[68:71], v[162:165], v[228:231], v[68:71]
	v_mfma_f32_16x16x32_bf16 v[64:67], v[170:173], v[228:231], v[64:67]
	v_mfma_f32_16x16x32_bf16 v[116:119], v[166:169], v[182:185], v[116:119]
	v_mfma_f32_16x16x32_bf16 v[112:115], v[174:177], v[182:185], v[112:115]
	v_mfma_f32_16x16x32_bf16 v[100:103], v[166:169], v[190:193], v[100:103]
	v_mfma_f32_16x16x32_bf16 v[96:99], v[174:177], v[190:193], v[96:99]
	v_mfma_f32_16x16x32_bf16 v[84:87], v[166:169], v[224:227], v[84:87]
	v_mfma_f32_16x16x32_bf16 v[80:83], v[174:177], v[224:227], v[80:83]
	v_mfma_f32_16x16x32_bf16 v[68:71], v[166:169], v[232:235], v[68:71]
	v_mfma_f32_16x16x32_bf16 v[64:67], v[174:177], v[232:235], v[64:67]
	s_setprio 0
	s_barrier
; __device__ __forceinline__ u32x4 pack8_bf16(f32x4 a, f32x4 b) { u32x4 w; w.x = cvt_pk_bf16(a[0], a[1]); w.y = cvt_pk_bf16(a[2], a[3]); w.z = cvt_pk_bf16(b[0], b[1]); w.w = cvt_pk_bf16(b[2], b[3]); return w; }
; #define PG8_STAGE(bufoff, gbase, voff) do { _Pragma("unroll") for (int _i = 0; _i < 2; ++_i) \
;         __builtin_amdgcn_global_load_lds((const unsigned*)((const char*)(gbase) + (voff)[_i]), (PG8_LAS unsigned*)(lds + (bufoff) + ldsw + _i * 8192), 16, 0, 0); } while (0)
; #define PG8_LDA(dst, b, h) do { _Pragma("unroll") for (int m = 0; m < 4; ++m) _Pragma("unroll") for (int k = 0; k < 2; ++k) dst[m][k] = *(const PG8_LAS bf16x8*)(lds + PG8_SA(b, h) + aoff + m * 2048 + k * 1024); } while (0)
; #define PG8_WAIT_V(n) asm volatile("s_waitcnt vmcnt(" #n ")" ::: "memory")
; #define PG8_WAIT_L(n) asm volatile("s_waitcnt lgkmcnt(" #n ")" ::: "memory")
; #define PG8_BAR __builtin_amdgcn_s_barrier()
;     __device__ __forceinline__ void operator()(const f32x4 (&acc)[2][2][4][2], const Unit& u, int wr, int wc, int fr, int fq) const {
;         const int g = u.pn / nNper, pnl = u.pn - g * nNper, pml = u.pm & 63;
;         bf16_t* base = O + (size_t)g * gstride;
;         const int row0 = pml * BM + wr * 64 + fr, col0 = pnl * BM + wc * 32 + 8 * fq;
; #pragma unroll
;         for (int ai = 0; ai < 2; ++ai)
; #pragma unroll
;             for (int m = 0; m < 4; ++m) { bf16_t* rowp = base + (size_t)(row0 + ai * HALF + m * 16) * ldc + col0;
; #pragma unroll
;                 for (int bj = 0; bj < 2; ++bj) { f32x4 v0 = acc[ai][bj][m][0], v1 = acc[ai][bj][m][1];
;                     if (ACT == 1) {
; #pragma unroll
;                         for (int j = 0; j < 4; ++j) { float a = fmaxf(v0[j], 0.f), b = fmaxf(v1[j], 0.f); v0[j] = a * a; v1[j] = b * b; } }
;                     *(u32x4*)(rowp + bj * HALF) = pack8_bf16(v0, v1); } }
; template <class Epi, class Sched, bool ALIGN_EPI = false, bool SP2 = false>
; __device__ __forceinline__ void gemm_phase(PG8_LAS unsigned char* lds, const Gemm g, const Sched& S, const Epi& E) {
;     ...
;             PG8_LDA(At, 1, 1); PG8_STAGE(PG8_SB(1, 0), b3, voffB); PG8_STAGE(PG8_SB(1, 1), b3 + hstep, voffB); PG8_STAGE(PG8_SA(1, 0), a3, voffA);
;             PG8_WAIT_V(8); PG8_WAIT_L(0); PG8_BAR; PG8_MMA(1, 0, At, B0); PG8_MMA(1, 1, At, B1); PG8_BAR; PG8_SCHED;
;     ...
;         if constexpr (ALIGN_EPI) { if (wr == 0) PG8_BAR; }
	s_add_i32 s49, s49, s2
	v_lshl_add_u64 v[140:141], v[140:141], 0, s[20:21]
	s_mov_b32 m0, s49
	ds_read_b128 v[178:181], v145 offset:49152
	ds_read_b128 v[182:185], v145 offset:50176
	ds_read_b128 v[186:189], v145 offset:51200
	ds_read_b128 v[190:193], v145 offset:52224
	ds_read_b128 v[220:223], v145 offset:53248
	ds_read_b128 v[224:227], v145 offset:54272
	ds_read_b128 v[228:231], v145 offset:55296
	ds_read_b128 v[232:235], v145 offset:56320
	global_load_lds_dwordx4 v[140:141], off
	s_add_i32 m0, s49, 0x2000
	s_add_u32 s52, s68, 0x20080
	v_lshl_add_u64 v[140:141], v[206:207], 0, s[20:21]
	s_addc_u32 s53, s69, 0
	s_add_i32 s49, s63, s2
	global_load_lds_dwordx4 v[140:141], off
	v_lshl_add_u64 v[140:141], s[52:53], 0, v[128:129]
	s_mov_b32 m0, s49
	s_nop 0
	global_load_lds_dwordx4 v[140:141], off
	v_lshl_add_u64 v[140:141], s[52:53], 0, v[130:131]
	s_add_i32 m0, s49, 0x2000
	s_nop 0
	global_load_lds_dwordx4 v[140:141], off
	v_lshl_add_u64 v[140:141], v[214:215], 0, s[20:21]
	s_mov_b32 m0, s27
	s_nop 0
	global_load_lds_dwordx4 v[140:141], off
	v_lshl_add_u64 v[140:141], v[216:217], 0, s[20:21]
	s_mov_b32 m0, s28
	s_nop 0
	global_load_lds_dwordx4 v[140:141], off
	s_waitcnt vmcnt(8)
	s_waitcnt lgkmcnt(0)
	s_barrier
	s_setprio 1
	s_waitcnt lgkmcnt(0)
	v_mfma_f32_16x16x32_bf16 v[60:63], v[146:149], v[178:181], v[60:63]
	v_mfma_f32_16x16x32_bf16 v[56:59], v[154:157], v[178:181], v[56:59]
	v_mfma_f32_16x16x32_bf16 v[44:47], v[146:149], v[186:189], v[44:47]
	v_mfma_f32_16x16x32_bf16 v[40:43], v[154:157], v[186:189], v[40:43]
	v_mfma_f32_16x16x32_bf16 v[28:31], v[146:149], v[220:223], v[28:31]
	v_mfma_f32_16x16x32_bf16 v[24:27], v[154:157], v[220:223], v[24:27]
	v_mfma_f32_16x16x32_bf16 v[12:15], v[146:149], v[228:231], v[12:15]
	v_mfma_f32_16x16x32_bf16 v[8:11], v[154:157], v[228:231], v[8:11]
	v_mfma_f32_16x16x32_bf16 v[60:63], v[150:153], v[182:185], v[60:63]
	v_mfma_f32_16x16x32_bf16 v[56:59], v[158:161], v[182:185], v[56:59]
	v_mfma_f32_16x16x32_bf16 v[44:47], v[150:153], v[190:193], v[44:47]
	v_mfma_f32_16x16x32_bf16 v[40:43], v[158:161], v[190:193], v[40:43]
	v_mfma_f32_16x16x32_bf16 v[28:31], v[150:153], v[224:227], v[28:31]
	v_mfma_f32_16x16x32_bf16 v[24:27], v[158:161], v[224:227], v[24:27]
	v_mfma_f32_16x16x32_bf16 v[12:15], v[150:153], v[232:235], v[12:15]
	v_mfma_f32_16x16x32_bf16 v[8:11], v[158:161], v[232:235], v[8:11]
	s_setprio 0
	s_setprio 1
	v_mfma_f32_16x16x32_bf16 v[52:55], v[162:165], v[178:181], v[52:55]
	v_mfma_f32_16x16x32_bf16 v[48:51], v[170:173], v[178:181], v[48:51]
	v_mfma_f32_16x16x32_bf16 v[36:39], v[162:165], v[186:189], v[36:39]
	v_mfma_f32_16x16x32_bf16 v[32:35], v[170:173], v[186:189], v[32:35]
	v_mfma_f32_16x16x32_bf16 v[20:23], v[162:165], v[220:223], v[20:23]
	v_mfma_f32_16x16x32_bf16 v[16:19], v[170:173], v[220:223], v[16:19]
	v_mfma_f32_16x16x32_bf16 v[4:7], v[162:165], v[228:231], v[4:7]
	v_mfma_f32_16x16x32_bf16 v[0:3], v[170:173], v[228:231], v[0:3]
	v_mfma_f32_16x16x32_bf16 v[52:55], v[166:169], v[182:185], v[52:55]
	v_mfma_f32_16x16x32_bf16 v[48:51], v[174:177], v[182:185], v[48:51]
	v_mfma_f32_16x16x32_bf16 v[36:39], v[166:169], v[190:193], v[36:39]
	v_mfma_f32_16x16x32_bf16 v[32:35], v[174:177], v[190:193], v[32:35]
	v_mfma_f32_16x16x32_bf16 v[20:23], v[166:169], v[224:227], v[20:23]
	v_mfma_f32_16x16x32_bf16 v[16:19], v[174:177], v[224:227], v[16:19]
	v_mfma_f32_16x16x32_bf16 v[4:7], v[166:169], v[232:235], v[4:7]
	v_mfma_f32_16x16x32_bf16 v[0:3], v[174:177], v[232:235], v[0:3]
	s_setprio 0
	s_barrier
	s_add_i32 s47, s47, 2
	s_add_u32 s66, s66, 0x100
	s_addc_u32 s67, s67, 0
	s_add_u32 s35, s35, 0x100
	s_addc_u32 s37, s37, 0
	s_cmp_gt_u32 s47, 29
	s_cbranch_scc0 .LBB0_455
	s_and_b64 vcc, exec, s[12:13]
	s_cbranch_vccz .LBB0_458
	s_barrier
.LBB0_458:
	s_ashr_i32 s19, s62, 31
	s_lshr_b32 s19, s19, 27
	s_add_i32 s19, s62, s19
	s_and_b32 s19, s19, 0xffffe0
	s_lshl_b32 s31, s46, 8
	s_sub_i32 s19, s62, s19
	s_and_b32 s31, s31, 0x3f00
	v_add_u32_e32 v146, s31, v142
	v_lshl_or_b32 v140, s19, 8, v144
	v_ashrrev_i32_e32 v141, 31, v140
	v_ashrrev_i32_e32 v147, 31, v146
	v_lshl_add_u64 v[148:149], v[140:141], 1, s[60:61]
	v_lshlrev_b64 v[140:141], 14, v[146:147]
	v_lshl_add_u64 v[140:141], v[148:149], 0, v[140:141]
	s_mov_b64 s[34:35], 0x40000
	v_mov_b32_e32 v242, 0x20000
	v_mov_b32_e32 v243, 0
	v_and_b32_e32 v238, 8, v208
	v_cmp_ne_u32_e32 vcc, 0, v238
	v_and_b32_e32 v240, 63, v208
	v_lshrrev_b32_e32 v241, 3, v240
	v_and_b32_e32 v244, 3, v240
	v_lshl_add_u32 v241, v244, 4, v241
	v_and_b32_e32 v244, 4, v240
	v_lshl_add_u32 v241, v244, 1, v241
	v_lshlrev_b32_e32 v240, 2, v241
	v_max_f32_e32 v124, 0, v124
	v_max_f32_e32 v125, 0, v125
	v_max_f32_e32 v126, 0, v126
	v_max_f32_e32 v127, 0, v127
	v_max_f32_e32 v120, 0, v120
	v_max_f32_e32 v121, 0, v121
	v_max_f32_e32 v122, 0, v122
	v_max_f32_e32 v123, 0, v123
	v_max_f32_e32 v116, 0, v116
	v_max_f32_e32 v117, 0, v117
	v_max_f32_e32 v118, 0, v118
	v_max_f32_e32 v119, 0, v119
	v_max_f32_e32 v112, 0, v112
	v_max_f32_e32 v113, 0, v113
	v_max_f32_e32 v114, 0, v114
	v_max_f32_e32 v115, 0, v115
	v_mul_f32_e32 v124, v124, v124
	v_mul_f32_e32 v125, v125, v125
	v_mul_f32_e32 v126, v126, v126
	v_mul_f32_e32 v127, v127, v127
	v_mul_f32_e32 v120, v120, v120
	v_mul_f32_e32 v121, v121, v121
	v_mul_f32_e32 v122, v122, v122
	v_mul_f32_e32 v123, v123, v123
	v_mul_f32_e32 v116, v116, v116
	v_mul_f32_e32 v117, v117, v117
	v_mul_f32_e32 v118, v118, v118
	v_mul_f32_e32 v119, v119, v119
	v_mul_f32_e32 v112, v112, v112
	v_mul_f32_e32 v113, v113, v113
	v_mul_f32_e32 v114, v114, v114
	v_mul_f32_e32 v115, v115, v115
	v_cvt_pk_bf16_f32 v124, v124, v125
	v_cvt_pk_bf16_f32 v125, v126, v127
	v_cvt_pk_bf16_f32 v126, v120, v121
	v_cvt_pk_bf16_f32 v127, v122, v123
	v_cvt_pk_bf16_f32 v116, v116, v117
	v_cvt_pk_bf16_f32 v117, v118, v119
	v_cvt_pk_bf16_f32 v118, v112, v113
	v_cvt_pk_bf16_f32 v119, v114, v115
	v_mov_b32_dpp v246, v116 row_ror:8 row_mask:0xf bank_mask:0xf
	v_mov_b32_dpp v247, v117 row_ror:8 row_mask:0xf bank_mask:0xf
	v_mov_b32_dpp v248, v118 row_ror:8 row_mask:0xf bank_mask:0xf
	v_mov_b32_dpp v249, v119 row_ror:8 row_mask:0xf bank_mask:0xf
	v_mov_b32_dpp v250, v124 row_ror:8 row_mask:0xf bank_mask:0xf
	v_mov_b32_dpp v251, v125 row_ror:8 row_mask:0xf bank_mask:0xf
	v_mov_b32_dpp v252, v126 row_ror:8 row_mask:0xf bank_mask:0xf
	v_mov_b32_dpp v253, v127 row_ror:8 row_mask:0xf bank_mask:0xf
	v_cndmask_b32_e32 v246, v124, v246, vcc
	v_cndmask_b32_e32 v247, v125, v247, vcc
	v_cndmask_b32_e32 v248, v126, v248, vcc
	v_cndmask_b32_e32 v249, v127, v249, vcc
	v_cndmask_b32_e32 v250, v250, v116, vcc
	v_cndmask_b32_e32 v251, v251, v117, vcc
	v_cndmask_b32_e32 v252, v252, v118, vcc
	v_cndmask_b32_e32 v253, v253, v119, vcc
	ds_bpermute_b32 v246, v240, v246
	ds_bpermute_b32 v247, v240, v247
	ds_bpermute_b32 v248, v240, v248
	ds_bpermute_b32 v249, v240, v249
	ds_bpermute_b32 v250, v240, v250
	ds_bpermute_b32 v251, v240, v251
	ds_bpermute_b32 v252, v240, v252
	ds_bpermute_b32 v253, v240, v253
	v_lshl_add_u64 v[238:239], v[140:141], 0, v[242:243]
	s_waitcnt lgkmcnt(4)
; __device__ __forceinline__ u32x4 pack8_bf16(f32x4 a, f32x4 b) { u32x4 w; w.x = cvt_pk_bf16(a[0], a[1]); w.y = cvt_pk_bf16(a[2], a[3]); w.z = cvt_pk_bf16(b[0], b[1]); w.w = cvt_pk_bf16(b[2], b[3]); return w; }
; #define ACT(t) (KBASE(t) <= qlo + QBLK - 1 && KBASE(t) + KVBLK - 1 >= qlo - W + 1)
;     __device__ __forceinline__ void operator()(const f32x4 (&acc)[2][2][4][2], const Unit& u, int wr, int wc, int fr, int fq) const {
;     ...
;             for (int m = 0; m < 4; ++m) { bf16_t* rowp = base + (size_t)(row0 + ai * HALF + m * 16) * ldc + col0;
; #pragma unroll
;                 for (int bj = 0; bj < 2; ++bj) { f32x4 v0 = acc[ai][bj][m][0], v1 = acc[ai][bj][m][1];
;                     if (ACT == 1) {
; #pragma unroll
;                         for (int j = 0; j < 4; ++j) { float a = fmaxf(v0[j], 0.f), b = fmaxf(v1[j], 0.f); v0[j] = a * a; v1[j] = b * b; } }
;                     *(u32x4*)(rowp + bj * HALF) = pack8_bf16(v0, v1); } }
	global_store_dwordx4 v[140:141], v[246:249], off
	s_waitcnt lgkmcnt(0)
	global_store_dwordx4 v[238:239], v[250:253], off
	v_lshl_add_u64 v[140:141], v[140:141], 0, s[34:35]
	v_max_f32_e32 v108, 0, v108
	v_max_f32_e32 v109, 0, v109
	v_max_f32_e32 v110, 0, v110
	v_max_f32_e32 v111, 0, v111
	v_max_f32_e32 v104, 0, v104
	v_max_f32_e32 v105, 0, v105
	v_max_f32_e32 v106, 0, v106
	v_max_f32_e32 v107, 0, v107
	v_max_f32_e32 v100, 0, v100
	v_max_f32_e32 v101, 0, v101
	v_max_f32_e32 v102, 0, v102
	v_max_f32_e32 v103, 0, v103
	v_max_f32_e32 v96, 0, v96
	v_max_f32_e32 v97, 0, v97
	v_max_f32_e32 v98, 0, v98
	v_max_f32_e32 v99, 0, v99
	v_mul_f32_e32 v108, v108, v108
	v_mul_f32_e32 v109, v109, v109
	v_mul_f32_e32 v110, v110, v110
	v_mul_f32_e32 v111, v111, v111
	v_mul_f32_e32 v104, v104, v104
	v_mul_f32_e32 v105, v105, v105
	v_mul_f32_e32 v106, v106, v106
	v_mul_f32_e32 v107, v107, v107
	v_mul_f32_e32 v100, v100, v100
	v_mul_f32_e32 v101, v101, v101
	v_mul_f32_e32 v102, v102, v102
	v_mul_f32_e32 v103, v103, v103
	v_mul_f32_e32 v96, v96, v96
	v_mul_f32_e32 v97, v97, v97
	v_mul_f32_e32 v98, v98, v98
	v_mul_f32_e32 v99, v99, v99
	v_cvt_pk_bf16_f32 v108, v108, v109
	v_cvt_pk_bf16_f32 v109, v110, v111
	v_cvt_pk_bf16_f32 v110, v104, v105
	v_cvt_pk_bf16_f32 v111, v106, v107
	v_cvt_pk_bf16_f32 v100, v100, v101
	v_cvt_pk_bf16_f32 v101, v102, v103
	v_cvt_pk_bf16_f32 v102, v96, v97
	v_cvt_pk_bf16_f32 v103, v98, v99
	v_mov_b32_dpp v246, v100 row_ror:8 row_mask:0xf bank_mask:0xf
	v_mov_b32_dpp v247, v101 row_ror:8 row_mask:0xf bank_mask:0xf
	v_mov_b32_dpp v248, v102 row_ror:8 row_mask:0xf bank_mask:0xf
	v_mov_b32_dpp v249, v103 row_ror:8 row_mask:0xf bank_mask:0xf
	v_mov_b32_dpp v250, v108 row_ror:8 row_mask:0xf bank_mask:0xf
	v_mov_b32_dpp v251, v109 row_ror:8 row_mask:0xf bank_mask:0xf
	v_mov_b32_dpp v252, v110 row_ror:8 row_mask:0xf bank_mask:0xf
	v_mov_b32_dpp v253, v111 row_ror:8 row_mask:0xf bank_mask:0xf
	v_cndmask_b32_e32 v246, v108, v246, vcc
	v_cndmask_b32_e32 v247, v109, v247, vcc
	v_cndmask_b32_e32 v248, v110, v248, vcc
	v_cndmask_b32_e32 v249, v111, v249, vcc
	v_cndmask_b32_e32 v250, v250, v100, vcc
	v_cndmask_b32_e32 v251, v251, v101, vcc
	v_cndmask_b32_e32 v252, v252, v102, vcc
	v_cndmask_b32_e32 v253, v253, v103, vcc
	ds_bpermute_b32 v246, v240, v246
	ds_bpermute_b32 v247, v240, v247
	ds_bpermute_b32 v248, v240, v248
	ds_bpermute_b32 v249, v240, v249
	ds_bpermute_b32 v250, v240, v250
	ds_bpermute_b32 v251, v240, v251
	ds_bpermute_b32 v252, v240, v252
	ds_bpermute_b32 v253, v240, v253
	v_lshl_add_u64 v[238:239], v[140:141], 0, v[242:243]
	s_waitcnt lgkmcnt(4)
	global_store_dwordx4 v[140:141], v[246:249], off
	s_waitcnt lgkmcnt(0)
	global_store_dwordx4 v[238:239], v[250:253], off
	v_lshl_add_u64 v[140:141], v[140:141], 0, s[34:35]
	v_max_f32_e32 v92, 0, v92
	v_max_f32_e32 v93, 0, v93
	v_max_f32_e32 v94, 0, v94
	v_max_f32_e32 v95, 0, v95
	v_max_f32_e32 v88, 0, v88
	v_max_f32_e32 v89, 0, v89
	v_max_f32_e32 v90, 0, v90
	v_max_f32_e32 v91, 0, v91
	v_max_f32_e32 v84, 0, v84
	v_max_f32_e32 v85, 0, v85
	v_max_f32_e32 v86, 0, v86
	v_max_f32_e32 v87, 0, v87
	v_max_f32_e32 v80, 0, v80
	v_max_f32_e32 v81, 0, v81
	v_max_f32_e32 v82, 0, v82
	v_max_f32_e32 v83, 0, v83
	v_mul_f32_e32 v92, v92, v92
	v_mul_f32_e32 v93, v93, v93
	v_mul_f32_e32 v94, v94, v94
	v_mul_f32_e32 v95, v95, v95
	v_mul_f32_e32 v88, v88, v88
	v_mul_f32_e32 v89, v89, v89
	v_mul_f32_e32 v90, v90, v90
	v_mul_f32_e32 v91, v91, v91
	v_mul_f32_e32 v84, v84, v84
	v_mul_f32_e32 v85, v85, v85
	v_mul_f32_e32 v86, v86, v86
	v_mul_f32_e32 v87, v87, v87
	v_mul_f32_e32 v80, v80, v80
	v_mul_f32_e32 v81, v81, v81
	v_mul_f32_e32 v82, v82, v82
	v_mul_f32_e32 v83, v83, v83
	v_cvt_pk_bf16_f32 v92, v92, v93
	v_cvt_pk_bf16_f32 v93, v94, v95
	v_cvt_pk_bf16_f32 v94, v88, v89
	v_cvt_pk_bf16_f32 v95, v90, v91
	v_cvt_pk_bf16_f32 v84, v84, v85
	v_cvt_pk_bf16_f32 v85, v86, v87
	v_cvt_pk_bf16_f32 v86, v80, v81
	v_cvt_pk_bf16_f32 v87, v82, v83
	v_mov_b32_dpp v246, v84 row_ror:8 row_mask:0xf bank_mask:0xf
	v_mov_b32_dpp v247, v85 row_ror:8 row_mask:0xf bank_mask:0xf
	v_mov_b32_dpp v248, v86 row_ror:8 row_mask:0xf bank_mask:0xf
	v_mov_b32_dpp v249, v87 row_ror:8 row_mask:0xf bank_mask:0xf
	v_mov_b32_dpp v250, v92 row_ror:8 row_mask:0xf bank_mask:0xf
	v_mov_b32_dpp v251, v93 row_ror:8 row_mask:0xf bank_mask:0xf
	v_mov_b32_dpp v252, v94 row_ror:8 row_mask:0xf bank_mask:0xf
	v_mov_b32_dpp v253, v95 row_ror:8 row_mask:0xf bank_mask:0xf
	v_cndmask_b32_e32 v246, v92, v246, vcc
	v_cndmask_b32_e32 v247, v93, v247, vcc
	v_cndmask_b32_e32 v248, v94, v248, vcc
	v_cndmask_b32_e32 v249, v95, v249, vcc
	v_cndmask_b32_e32 v250, v250, v84, vcc
	v_cndmask_b32_e32 v251, v251, v85, vcc
	v_cndmask_b32_e32 v252, v252, v86, vcc
	v_cndmask_b32_e32 v253, v253, v87, vcc
	ds_bpermute_b32 v246, v240, v246
	ds_bpermute_b32 v247, v240, v247
	ds_bpermute_b32 v248, v240, v248
	ds_bpermute_b32 v249, v240, v249
	ds_bpermute_b32 v250, v240, v250
	ds_bpermute_b32 v251, v240, v251
	ds_bpermute_b32 v252, v240, v252
	ds_bpermute_b32 v253, v240, v253
	v_lshl_add_u64 v[238:239], v[140:141], 0, v[242:243]
	s_waitcnt lgkmcnt(4)
	global_store_dwordx4 v[140:141], v[246:249], off
	s_waitcnt lgkmcnt(0)
; __device__ __forceinline__ u32x4 pack8_bf16(f32x4 a, f32x4 b) { u32x4 w; w.x = cvt_pk_bf16(a[0], a[1]); w.y = cvt_pk_bf16(a[2], a[3]); w.z = cvt_pk_bf16(b[0], b[1]); w.w = cvt_pk_bf16(b[2], b[3]); return w; }
; #define ACT(t) (KBASE(t) <= qlo + QBLK - 1 && KBASE(t) + KVBLK - 1 >= qlo - W + 1)
;     __device__ __forceinline__ void operator()(const f32x4 (&acc)[2][2][4][2], const Unit& u, int wr, int wc, int fr, int fq) const {
;     ...
;             for (int m = 0; m < 4; ++m) { bf16_t* rowp = base + (size_t)(row0 + ai * HALF + m * 16) * ldc + col0;
; #pragma unroll
;                 for (int bj = 0; bj < 2; ++bj) { f32x4 v0 = acc[ai][bj][m][0], v1 = acc[ai][bj][m][1];
;                     if (ACT == 1) {
; #pragma unroll
;                         for (int j = 0; j < 4; ++j) { float a = fmaxf(v0[j], 0.f), b = fmaxf(v1[j], 0.f); v0[j] = a * a; v1[j] = b * b; } }
;                     *(u32x4*)(rowp + bj * HALF) = pack8_bf16(v0, v1); } }
	global_store_dwordx4 v[238:239], v[250:253], off
	v_lshl_add_u64 v[140:141], v[140:141], 0, s[34:35]
	v_max_f32_e32 v76, 0, v76
	v_max_f32_e32 v77, 0, v77
	v_max_f32_e32 v78, 0, v78
	v_max_f32_e32 v79, 0, v79
	v_max_f32_e32 v72, 0, v72
	v_max_f32_e32 v73, 0, v73
	v_max_f32_e32 v74, 0, v74
	v_max_f32_e32 v75, 0, v75
	v_max_f32_e32 v68, 0, v68
	v_max_f32_e32 v69, 0, v69
	v_max_f32_e32 v70, 0, v70
	v_max_f32_e32 v71, 0, v71
	v_max_f32_e32 v64, 0, v64
	v_max_f32_e32 v65, 0, v65
	v_max_f32_e32 v66, 0, v66
	v_max_f32_e32 v67, 0, v67
	v_mul_f32_e32 v76, v76, v76
	v_mul_f32_e32 v77, v77, v77
	v_mul_f32_e32 v78, v78, v78
	v_mul_f32_e32 v79, v79, v79
	v_mul_f32_e32 v72, v72, v72
	v_mul_f32_e32 v73, v73, v73
	v_mul_f32_e32 v74, v74, v74
	v_mul_f32_e32 v75, v75, v75
	v_mul_f32_e32 v68, v68, v68
	v_mul_f32_e32 v69, v69, v69
	v_mul_f32_e32 v70, v70, v70
	v_mul_f32_e32 v71, v71, v71
	v_mul_f32_e32 v64, v64, v64
	v_mul_f32_e32 v65, v65, v65
	v_mul_f32_e32 v66, v66, v66
	v_mul_f32_e32 v67, v67, v67
	v_cvt_pk_bf16_f32 v76, v76, v77
	v_cvt_pk_bf16_f32 v77, v78, v79
	v_cvt_pk_bf16_f32 v78, v72, v73
	v_cvt_pk_bf16_f32 v79, v74, v75
	v_cvt_pk_bf16_f32 v68, v68, v69
	v_cvt_pk_bf16_f32 v69, v70, v71
	v_cvt_pk_bf16_f32 v70, v64, v65
	v_cvt_pk_bf16_f32 v71, v66, v67
	v_mov_b32_dpp v246, v68 row_ror:8 row_mask:0xf bank_mask:0xf
	v_mov_b32_dpp v247, v69 row_ror:8 row_mask:0xf bank_mask:0xf
	v_mov_b32_dpp v248, v70 row_ror:8 row_mask:0xf bank_mask:0xf
	v_mov_b32_dpp v249, v71 row_ror:8 row_mask:0xf bank_mask:0xf
	v_mov_b32_dpp v250, v76 row_ror:8 row_mask:0xf bank_mask:0xf
	v_mov_b32_dpp v251, v77 row_ror:8 row_mask:0xf bank_mask:0xf
	v_mov_b32_dpp v252, v78 row_ror:8 row_mask:0xf bank_mask:0xf
	v_mov_b32_dpp v253, v79 row_ror:8 row_mask:0xf bank_mask:0xf
	v_cndmask_b32_e32 v246, v76, v246, vcc
	v_cndmask_b32_e32 v247, v77, v247, vcc
	v_cndmask_b32_e32 v248, v78, v248, vcc
	v_cndmask_b32_e32 v249, v79, v249, vcc
	v_cndmask_b32_e32 v250, v250, v68, vcc
	v_cndmask_b32_e32 v251, v251, v69, vcc
	v_cndmask_b32_e32 v252, v252, v70, vcc
	v_cndmask_b32_e32 v253, v253, v71, vcc
	ds_bpermute_b32 v246, v240, v246
	ds_bpermute_b32 v247, v240, v247
	ds_bpermute_b32 v248, v240, v248
	ds_bpermute_b32 v249, v240, v249
	ds_bpermute_b32 v250, v240, v250
	ds_bpermute_b32 v251, v240, v251
	ds_bpermute_b32 v252, v240, v252
	ds_bpermute_b32 v253, v240, v253
	v_lshl_add_u64 v[238:239], v[140:141], 0, v[242:243]
	s_waitcnt lgkmcnt(4)
	global_store_dwordx4 v[140:141], v[246:249], off
	s_waitcnt lgkmcnt(0)
	global_store_dwordx4 v[238:239], v[250:253], off
	s_mov_b64 s[34:35], 0x140000
	v_lshl_add_u64 v[140:141], v[140:141], 0, s[34:35]
	s_mov_b64 s[34:35], 0x40000
	v_max_f32_e32 v60, 0, v60
	v_max_f32_e32 v61, 0, v61
	v_max_f32_e32 v62, 0, v62
	v_max_f32_e32 v63, 0, v63
	v_max_f32_e32 v56, 0, v56
	v_max_f32_e32 v57, 0, v57
	v_max_f32_e32 v58, 0, v58
	v_max_f32_e32 v59, 0, v59
	v_max_f32_e32 v52, 0, v52
	v_max_f32_e32 v53, 0, v53
	v_max_f32_e32 v54, 0, v54
	v_max_f32_e32 v55, 0, v55
	v_max_f32_e32 v48, 0, v48
	v_max_f32_e32 v49, 0, v49
	v_max_f32_e32 v50, 0, v50
	v_max_f32_e32 v51, 0, v51
	v_mul_f32_e32 v60, v60, v60
	v_mul_f32_e32 v61, v61, v61
	v_mul_f32_e32 v62, v62, v62
	v_mul_f32_e32 v63, v63, v63
	v_mul_f32_e32 v56, v56, v56
	v_mul_f32_e32 v57, v57, v57
	v_mul_f32_e32 v58, v58, v58
	v_mul_f32_e32 v59, v59, v59
	v_mul_f32_e32 v52, v52, v52
	v_mul_f32_e32 v53, v53, v53
	v_mul_f32_e32 v54, v54, v54
	v_mul_f32_e32 v55, v55, v55
	v_mul_f32_e32 v48, v48, v48
	v_mul_f32_e32 v49, v49, v49
	v_mul_f32_e32 v50, v50, v50
	v_mul_f32_e32 v51, v51, v51
	v_cvt_pk_bf16_f32 v60, v60, v61
	v_cvt_pk_bf16_f32 v61, v62, v63
	v_cvt_pk_bf16_f32 v62, v56, v57
	v_cvt_pk_bf16_f32 v63, v58, v59
	v_cvt_pk_bf16_f32 v52, v52, v53
	v_cvt_pk_bf16_f32 v53, v54, v55
	v_cvt_pk_bf16_f32 v54, v48, v49
	v_cvt_pk_bf16_f32 v55, v50, v51
	v_mov_b32_dpp v246, v52 row_ror:8 row_mask:0xf bank_mask:0xf
	v_mov_b32_dpp v247, v53 row_ror:8 row_mask:0xf bank_mask:0xf
	v_mov_b32_dpp v248, v54 row_ror:8 row_mask:0xf bank_mask:0xf
	v_mov_b32_dpp v249, v55 row_ror:8 row_mask:0xf bank_mask:0xf
	v_mov_b32_dpp v250, v60 row_ror:8 row_mask:0xf bank_mask:0xf
	v_mov_b32_dpp v251, v61 row_ror:8 row_mask:0xf bank_mask:0xf
	v_mov_b32_dpp v252, v62 row_ror:8 row_mask:0xf bank_mask:0xf
	v_mov_b32_dpp v253, v63 row_ror:8 row_mask:0xf bank_mask:0xf
	v_cndmask_b32_e32 v246, v60, v246, vcc
	v_cndmask_b32_e32 v247, v61, v247, vcc
	v_cndmask_b32_e32 v248, v62, v248, vcc
	v_cndmask_b32_e32 v249, v63, v249, vcc
	v_cndmask_b32_e32 v250, v250, v52, vcc
	v_cndmask_b32_e32 v251, v251, v53, vcc
	v_cndmask_b32_e32 v252, v252, v54, vcc
	v_cndmask_b32_e32 v253, v253, v55, vcc
	ds_bpermute_b32 v246, v240, v246
	ds_bpermute_b32 v247, v240, v247
	ds_bpermute_b32 v248, v240, v248
	ds_bpermute_b32 v249, v240, v249
	ds_bpermute_b32 v250, v240, v250
	ds_bpermute_b32 v251, v240, v251
	ds_bpermute_b32 v252, v240, v252
	ds_bpermute_b32 v253, v240, v253
	v_lshl_add_u64 v[238:239], v[140:141], 0, v[242:243]
	s_waitcnt lgkmcnt(4)
	global_store_dwordx4 v[140:141], v[246:249], off
	s_waitcnt lgkmcnt(0)
; __device__ __forceinline__ u32x4 pack8_bf16(f32x4 a, f32x4 b) { u32x4 w; w.x = cvt_pk_bf16(a[0], a[1]); w.y = cvt_pk_bf16(a[2], a[3]); w.z = cvt_pk_bf16(b[0], b[1]); w.w = cvt_pk_bf16(b[2], b[3]); return w; }
; #define ACT(t) (KBASE(t) <= qlo + QBLK - 1 && KBASE(t) + KVBLK - 1 >= qlo - W + 1)
;     __device__ __forceinline__ void operator()(const f32x4 (&acc)[2][2][4][2], const Unit& u, int wr, int wc, int fr, int fq) const {
;     ...
;             for (int m = 0; m < 4; ++m) { bf16_t* rowp = base + (size_t)(row0 + ai * HALF + m * 16) * ldc + col0;
; #pragma unroll
;                 for (int bj = 0; bj < 2; ++bj) { f32x4 v0 = acc[ai][bj][m][0], v1 = acc[ai][bj][m][1];
;                     if (ACT == 1) {
; #pragma unroll
;                         for (int j = 0; j < 4; ++j) { float a = fmaxf(v0[j], 0.f), b = fmaxf(v1[j], 0.f); v0[j] = a * a; v1[j] = b * b; } }
;                     *(u32x4*)(rowp + bj * HALF) = pack8_bf16(v0, v1); } }
	global_store_dwordx4 v[238:239], v[250:253], off
	v_lshl_add_u64 v[140:141], v[140:141], 0, s[34:35]
	v_max_f32_e32 v44, 0, v44
	v_max_f32_e32 v45, 0, v45
	v_max_f32_e32 v46, 0, v46
	v_max_f32_e32 v47, 0, v47
	v_max_f32_e32 v40, 0, v40
	v_max_f32_e32 v41, 0, v41
	v_max_f32_e32 v42, 0, v42
	v_max_f32_e32 v43, 0, v43
	v_max_f32_e32 v36, 0, v36
	v_max_f32_e32 v37, 0, v37
	v_max_f32_e32 v38, 0, v38
	v_max_f32_e32 v39, 0, v39
	v_max_f32_e32 v32, 0, v32
	v_max_f32_e32 v33, 0, v33
	v_max_f32_e32 v34, 0, v34
	v_max_f32_e32 v35, 0, v35
	v_mul_f32_e32 v44, v44, v44
	v_mul_f32_e32 v45, v45, v45
	v_mul_f32_e32 v46, v46, v46
	v_mul_f32_e32 v47, v47, v47
	v_mul_f32_e32 v40, v40, v40
	v_mul_f32_e32 v41, v41, v41
	v_mul_f32_e32 v42, v42, v42
	v_mul_f32_e32 v43, v43, v43
	v_mul_f32_e32 v36, v36, v36
	v_mul_f32_e32 v37, v37, v37
	v_mul_f32_e32 v38, v38, v38
	v_mul_f32_e32 v39, v39, v39
	v_mul_f32_e32 v32, v32, v32
	v_mul_f32_e32 v33, v33, v33
	v_mul_f32_e32 v34, v34, v34
	v_mul_f32_e32 v35, v35, v35
	v_cvt_pk_bf16_f32 v44, v44, v45
	v_cvt_pk_bf16_f32 v45, v46, v47
	v_cvt_pk_bf16_f32 v46, v40, v41
	v_cvt_pk_bf16_f32 v47, v42, v43
	v_cvt_pk_bf16_f32 v36, v36, v37
	v_cvt_pk_bf16_f32 v37, v38, v39
	v_cvt_pk_bf16_f32 v38, v32, v33
	v_cvt_pk_bf16_f32 v39, v34, v35
	v_mov_b32_dpp v246, v36 row_ror:8 row_mask:0xf bank_mask:0xf
	v_mov_b32_dpp v247, v37 row_ror:8 row_mask:0xf bank_mask:0xf
	v_mov_b32_dpp v248, v38 row_ror:8 row_mask:0xf bank_mask:0xf
	v_mov_b32_dpp v249, v39 row_ror:8 row_mask:0xf bank_mask:0xf
	v_mov_b32_dpp v250, v44 row_ror:8 row_mask:0xf bank_mask:0xf
	v_mov_b32_dpp v251, v45 row_ror:8 row_mask:0xf bank_mask:0xf
	v_mov_b32_dpp v252, v46 row_ror:8 row_mask:0xf bank_mask:0xf
	v_mov_b32_dpp v253, v47 row_ror:8 row_mask:0xf bank_mask:0xf
	v_cndmask_b32_e32 v246, v44, v246, vcc
	v_cndmask_b32_e32 v247, v45, v247, vcc
	v_cndmask_b32_e32 v248, v46, v248, vcc
	v_cndmask_b32_e32 v249, v47, v249, vcc
	v_cndmask_b32_e32 v250, v250, v36, vcc
	v_cndmask_b32_e32 v251, v251, v37, vcc
	v_cndmask_b32_e32 v252, v252, v38, vcc
	v_cndmask_b32_e32 v253, v253, v39, vcc
	ds_bpermute_b32 v246, v240, v246
	ds_bpermute_b32 v247, v240, v247
	ds_bpermute_b32 v248, v240, v248
	ds_bpermute_b32 v249, v240, v249
	ds_bpermute_b32 v250, v240, v250
	ds_bpermute_b32 v251, v240, v251
	ds_bpermute_b32 v252, v240, v252
	ds_bpermute_b32 v253, v240, v253
	v_lshl_add_u64 v[238:239], v[140:141], 0, v[242:243]
	s_waitcnt lgkmcnt(4)
	global_store_dwordx4 v[140:141], v[246:249], off
	s_waitcnt lgkmcnt(0)
	global_store_dwordx4 v[238:239], v[250:253], off
	v_lshl_add_u64 v[140:141], v[140:141], 0, s[34:35]
	v_max_f32_e32 v28, 0, v28
	v_max_f32_e32 v29, 0, v29
	v_max_f32_e32 v30, 0, v30
	v_max_f32_e32 v31, 0, v31
	v_max_f32_e32 v24, 0, v24
	v_max_f32_e32 v25, 0, v25
	v_max_f32_e32 v26, 0, v26
	v_max_f32_e32 v27, 0, v27
	v_max_f32_e32 v20, 0, v20
	v_max_f32_e32 v21, 0, v21
	v_max_f32_e32 v22, 0, v22
	v_max_f32_e32 v23, 0, v23
	v_max_f32_e32 v16, 0, v16
	v_max_f32_e32 v17, 0, v17
	v_max_f32_e32 v18, 0, v18
	v_max_f32_e32 v19, 0, v19
	v_mul_f32_e32 v28, v28, v28
	v_mul_f32_e32 v29, v29, v29
	v_mul_f32_e32 v30, v30, v30
	v_mul_f32_e32 v31, v31, v31
	v_mul_f32_e32 v24, v24, v24
	v_mul_f32_e32 v25, v25, v25
	v_mul_f32_e32 v26, v26, v26
	v_mul_f32_e32 v27, v27, v27
	v_mul_f32_e32 v20, v20, v20
	v_mul_f32_e32 v21, v21, v21
	v_mul_f32_e32 v22, v22, v22
	v_mul_f32_e32 v23, v23, v23
	v_mul_f32_e32 v16, v16, v16
	v_mul_f32_e32 v17, v17, v17
	v_mul_f32_e32 v18, v18, v18
	v_mul_f32_e32 v19, v19, v19
	v_cvt_pk_bf16_f32 v28, v28, v29
	v_cvt_pk_bf16_f32 v29, v30, v31
	v_cvt_pk_bf16_f32 v30, v24, v25
	v_cvt_pk_bf16_f32 v31, v26, v27
	v_cvt_pk_bf16_f32 v20, v20, v21
	v_cvt_pk_bf16_f32 v21, v22, v23
	v_cvt_pk_bf16_f32 v22, v16, v17
	v_cvt_pk_bf16_f32 v23, v18, v19
	v_mov_b32_dpp v246, v20 row_ror:8 row_mask:0xf bank_mask:0xf
	v_mov_b32_dpp v247, v21 row_ror:8 row_mask:0xf bank_mask:0xf
	v_mov_b32_dpp v248, v22 row_ror:8 row_mask:0xf bank_mask:0xf
	v_mov_b32_dpp v249, v23 row_ror:8 row_mask:0xf bank_mask:0xf
	v_mov_b32_dpp v250, v28 row_ror:8 row_mask:0xf bank_mask:0xf
	v_mov_b32_dpp v251, v29 row_ror:8 row_mask:0xf bank_mask:0xf
	v_mov_b32_dpp v252, v30 row_ror:8 row_mask:0xf bank_mask:0xf
	v_mov_b32_dpp v253, v31 row_ror:8 row_mask:0xf bank_mask:0xf
	v_cndmask_b32_e32 v246, v28, v246, vcc
	v_cndmask_b32_e32 v247, v29, v247, vcc
	v_cndmask_b32_e32 v248, v30, v248, vcc
	v_cndmask_b32_e32 v249, v31, v249, vcc
	v_cndmask_b32_e32 v250, v250, v20, vcc
	v_cndmask_b32_e32 v251, v251, v21, vcc
	v_cndmask_b32_e32 v252, v252, v22, vcc
	v_cndmask_b32_e32 v253, v253, v23, vcc
	ds_bpermute_b32 v246, v240, v246
	ds_bpermute_b32 v247, v240, v247
	ds_bpermute_b32 v248, v240, v248
	ds_bpermute_b32 v249, v240, v249
	ds_bpermute_b32 v250, v240, v250
	ds_bpermute_b32 v251, v240, v251
	ds_bpermute_b32 v252, v240, v252
	ds_bpermute_b32 v253, v240, v253
	v_lshl_add_u64 v[238:239], v[140:141], 0, v[242:243]
	s_waitcnt lgkmcnt(4)
; __device__ __forceinline__ u32x4 pack8_bf16(f32x4 a, f32x4 b) { u32x4 w; w.x = cvt_pk_bf16(a[0], a[1]); w.y = cvt_pk_bf16(a[2], a[3]); w.z = cvt_pk_bf16(b[0], b[1]); w.w = cvt_pk_bf16(b[2], b[3]); return w; }
; #define PG8_BAR __builtin_amdgcn_s_barrier()
; #define ACT(t) (KBASE(t) <= qlo + QBLK - 1 && KBASE(t) + KVBLK - 1 >= qlo - W + 1)
;     __device__ __forceinline__ void operator()(const f32x4 (&acc)[2][2][4][2], const Unit& u, int wr, int wc, int fr, int fq) const {
;     ...
;             for (int m = 0; m < 4; ++m) { bf16_t* rowp = base + (size_t)(row0 + ai * HALF + m * 16) * ldc + col0;
; #pragma unroll
;                 for (int bj = 0; bj < 2; ++bj) { f32x4 v0 = acc[ai][bj][m][0], v1 = acc[ai][bj][m][1];
;                     if (ACT == 1) {
; #pragma unroll
;                         for (int j = 0; j < 4; ++j) { float a = fmaxf(v0[j], 0.f), b = fmaxf(v1[j], 0.f); v0[j] = a * a; v1[j] = b * b; } }
;                     *(u32x4*)(rowp + bj * HALF) = pack8_bf16(v0, v1); } }
; template <class Epi, class Sched, bool ALIGN_EPI = false, bool SP2 = false>
; __device__ __forceinline__ void gemm_phase(PG8_LAS unsigned char* lds, const Gemm g, const Sched& S, const Epi& E) {
;     ...
;         if (!has_next) break;
; #pragma unroll
;         for (int a = 0; a < 2; ++a)
; #pragma unroll
;             for (int b = 0; b < 2; ++b)
; #pragma unroll
;                 for (int m = 0; m < 4; ++m)
; #pragma unroll
;                     for (int n = 0; n < 2; ++n) acc[a][b][m][n] = (f32x4){0.f, 0.f, 0.f, 0.f};
;         cur = nxt; cA = nA; cB = nB; ++ui;
;         if constexpr (ALIGN_EPI) { if (wr == 1) PG8_BAR; }
	global_store_dwordx4 v[140:141], v[246:249], off
	s_waitcnt lgkmcnt(0)
	global_store_dwordx4 v[238:239], v[250:253], off
	v_lshl_add_u64 v[140:141], v[140:141], 0, s[34:35]
	v_max_f32_e32 v12, 0, v12
	v_max_f32_e32 v13, 0, v13
	v_max_f32_e32 v14, 0, v14
	v_max_f32_e32 v15, 0, v15
	v_max_f32_e32 v8, 0, v8
	v_max_f32_e32 v9, 0, v9
	v_max_f32_e32 v10, 0, v10
	v_max_f32_e32 v11, 0, v11
	v_max_f32_e32 v4, 0, v4
	v_max_f32_e32 v5, 0, v5
	v_max_f32_e32 v6, 0, v6
	v_max_f32_e32 v7, 0, v7
	v_max_f32_e32 v0, 0, v0
	v_max_f32_e32 v1, 0, v1
	v_max_f32_e32 v2, 0, v2
	v_max_f32_e32 v3, 0, v3
	v_mul_f32_e32 v12, v12, v12
	v_mul_f32_e32 v13, v13, v13
	v_mul_f32_e32 v14, v14, v14
	v_mul_f32_e32 v15, v15, v15
	v_mul_f32_e32 v8, v8, v8
	v_mul_f32_e32 v9, v9, v9
	v_mul_f32_e32 v10, v10, v10
	v_mul_f32_e32 v11, v11, v11
	v_mul_f32_e32 v4, v4, v4
	v_mul_f32_e32 v5, v5, v5
	v_mul_f32_e32 v6, v6, v6
	v_mul_f32_e32 v7, v7, v7
	v_mul_f32_e32 v0, v0, v0
	v_mul_f32_e32 v1, v1, v1
	v_mul_f32_e32 v2, v2, v2
	v_mul_f32_e32 v3, v3, v3
	v_cvt_pk_bf16_f32 v12, v12, v13
	v_cvt_pk_bf16_f32 v13, v14, v15
	v_cvt_pk_bf16_f32 v14, v8, v9
	v_cvt_pk_bf16_f32 v15, v10, v11
	v_cvt_pk_bf16_f32 v4, v4, v5
	v_cvt_pk_bf16_f32 v5, v6, v7
	v_cvt_pk_bf16_f32 v6, v0, v1
	v_cvt_pk_bf16_f32 v7, v2, v3
	v_mov_b32_dpp v246, v4 row_ror:8 row_mask:0xf bank_mask:0xf
	v_mov_b32_dpp v247, v5 row_ror:8 row_mask:0xf bank_mask:0xf
	v_mov_b32_dpp v248, v6 row_ror:8 row_mask:0xf bank_mask:0xf
	v_mov_b32_dpp v249, v7 row_ror:8 row_mask:0xf bank_mask:0xf
	v_mov_b32_dpp v250, v12 row_ror:8 row_mask:0xf bank_mask:0xf
	v_mov_b32_dpp v251, v13 row_ror:8 row_mask:0xf bank_mask:0xf
	v_mov_b32_dpp v252, v14 row_ror:8 row_mask:0xf bank_mask:0xf
	v_mov_b32_dpp v253, v15 row_ror:8 row_mask:0xf bank_mask:0xf
	v_cndmask_b32_e32 v246, v12, v246, vcc
	v_cndmask_b32_e32 v247, v13, v247, vcc
	v_cndmask_b32_e32 v248, v14, v248, vcc
	v_cndmask_b32_e32 v249, v15, v249, vcc
	v_cndmask_b32_e32 v250, v250, v4, vcc
	v_cndmask_b32_e32 v251, v251, v5, vcc
	v_cndmask_b32_e32 v252, v252, v6, vcc
	v_cndmask_b32_e32 v253, v253, v7, vcc
	ds_bpermute_b32 v246, v240, v246
	ds_bpermute_b32 v247, v240, v247
	ds_bpermute_b32 v248, v240, v248
	ds_bpermute_b32 v249, v240, v249
	ds_bpermute_b32 v250, v240, v250
	ds_bpermute_b32 v251, v240, v251
	ds_bpermute_b32 v252, v240, v252
	ds_bpermute_b32 v253, v240, v253
	v_lshl_add_u64 v[238:239], v[140:141], 0, v[242:243]
	s_waitcnt lgkmcnt(4)
	global_store_dwordx4 v[140:141], v[246:249], off
	s_waitcnt lgkmcnt(0)
	global_store_dwordx4 v[238:239], v[250:253], off
	s_andn2_b64 vcc, exec, s[40:41]
	s_mov_b64 s[34:35], -1
	s_cbranch_vccnz .LBB0_447
	s_andn2_b64 vcc, exec, s[8:9]
	s_cbranch_vccnz .LBB0_446
	s_barrier
	s_branch .LBB0_446
